# v26 + K-loop load segments: vmcnt/lgkmcnt wait pair before each barrier merged into one s_waitcnt; m0 write hoisted above the address VALU so hipcc's s_nop 0 before the LDS-DMA load goes
# speedup vs baseline: 1.0010x; 1.0010x over previous
.LBB0_123:
	s_ashr_i32 s19, s18, 31
	s_lshl_b64 s[20:21], s[18:19], 19
	v_readlane_b32 s70, v246, 34
	v_readlane_b32 s71, v246, 35
	s_add_u32 s20, s70, s20
	s_addc_u32 s21, s71, s21
	s_and_b64 s[22:23], s[0:1], exec
	s_cselect_b32 s5, s21, s3
	s_cselect_b32 s19, s20, s2
	s_ashr_i32 s17, s16, 31
	s_lshl_b64 s[22:23], s[16:17], 19
	s_add_u32 s22, s15, s22
	s_addc_u32 s23, s30, s23
	s_and_b64 s[28:29], s[0:1], exec
	s_cselect_b32 s17, s23, s27
	s_cselect_b32 s25, s22, s26
	s_add_u32 s2, s2, 0x40080
	s_addc_u32 s3, s3, 0
	s_add_u32 s33, s26, 0x100
	s_addc_u32 s46, s27, 0
	s_mov_b32 s47, -2
	v_readlane_b32 s68, v246, 32
	v_readlane_b32 s69, v246, 33
	ds_read_b128 v[128:131], v161
	ds_read_b128 v[132:135], v161 offset:1024
	ds_read_b128 v[152:155], v161 offset:2048
	ds_read_b128 v[164:167], v161 offset:3072
	ds_read_b128 v[172:175], v162
	ds_read_b128 v[176:179], v162 offset:1024
	ds_read_b128 v[180:183], v162 offset:2048
	ds_read_b128 v[184:187], v162 offset:3072
	s_add_u32 s26, s2, 0xfffc0080
	s_addc_u32 s27, s3, -1
	s_cmp_eq_u32 s47, 12
	s_cselect_b32 s29, s5, s27
	s_cselect_b32 s28, s19, s26
	s_cselect_b32 s27, s17, s46
	s_cselect_b32 s26, s25, s33
	v_lshl_add_u64 v[156:157], s[2:3], 0, v[144:145]
	s_add_i32 m0, s34, 0xc000
	ds_read_b128 v[188:191], v163
	ds_read_b128 v[192:195], v163 offset:1024
	ds_read_b128 v[196:199], v163 offset:2048
	ds_read_b128 v[200:203], v163 offset:3072
	ds_read_b128 v[204:207], v163 offset:4096
	ds_read_b128 v[208:211], v163 offset:5120
	ds_read_b128 v[212:215], v163 offset:6144
	ds_read_b128 v[216:219], v163 offset:7168
	global_load_lds_dwordx4 v[156:157], off
	s_add_i32 m0, s34, 0xe000
	v_lshl_add_u64 v[156:157], s[2:3], 0, v[146:147]
	global_load_lds_dwordx4 v[156:157], off
	s_waitcnt vmcnt(8) lgkmcnt(0)
	s_barrier
	v_mfma_f32_16x16x32_bf16 v[124:127], v[128:131], v[188:191], 0
	v_mfma_f32_16x16x32_bf16 v[120:123], v[152:155], v[188:191], 0
	v_mfma_f32_16x16x32_bf16 v[108:111], v[128:131], v[196:199], 0
	v_mfma_f32_16x16x32_bf16 v[104:107], v[152:155], v[196:199], 0
	v_mfma_f32_16x16x32_bf16 v[92:95], v[128:131], v[204:207], 0
	v_mfma_f32_16x16x32_bf16 v[88:91], v[152:155], v[204:207], 0
	v_mfma_f32_16x16x32_bf16 v[76:79], v[128:131], v[212:215], 0
	v_mfma_f32_16x16x32_bf16 v[72:75], v[152:155], v[212:215], 0
	v_mfma_f32_16x16x32_bf16 v[124:127], v[132:135], v[192:195], v[124:127]
	v_mfma_f32_16x16x32_bf16 v[120:123], v[164:167], v[192:195], v[120:123]
	v_mfma_f32_16x16x32_bf16 v[108:111], v[132:135], v[200:203], v[108:111]
	v_mfma_f32_16x16x32_bf16 v[104:107], v[164:167], v[200:203], v[104:107]
	v_mfma_f32_16x16x32_bf16 v[92:95], v[132:135], v[208:211], v[92:95]
	v_mfma_f32_16x16x32_bf16 v[88:91], v[164:167], v[208:211], v[88:91]
	v_mfma_f32_16x16x32_bf16 v[76:79], v[132:135], v[216:219], v[76:79]
	v_mfma_f32_16x16x32_bf16 v[72:75], v[164:167], v[216:219], v[72:75]
	v_mfma_f32_16x16x32_bf16 v[116:119], v[172:175], v[188:191], 0
	v_mfma_f32_16x16x32_bf16 v[112:115], v[180:183], v[188:191], 0
	v_mfma_f32_16x16x32_bf16 v[100:103], v[172:175], v[196:199], 0
	v_mfma_f32_16x16x32_bf16 v[96:99], v[180:183], v[196:199], 0
	v_mfma_f32_16x16x32_bf16 v[84:87], v[172:175], v[204:207], 0
	v_mfma_f32_16x16x32_bf16 v[80:83], v[180:183], v[204:207], 0
	v_mfma_f32_16x16x32_bf16 v[68:71], v[172:175], v[212:215], 0
	v_mfma_f32_16x16x32_bf16 v[64:67], v[180:183], v[212:215], 0
	v_mfma_f32_16x16x32_bf16 v[116:119], v[176:179], v[192:195], v[116:119]
	v_mfma_f32_16x16x32_bf16 v[112:115], v[184:187], v[192:195], v[112:115]
	v_mfma_f32_16x16x32_bf16 v[100:103], v[176:179], v[200:203], v[100:103]
	v_mfma_f32_16x16x32_bf16 v[96:99], v[184:187], v[200:203], v[96:99]
	v_mfma_f32_16x16x32_bf16 v[84:87], v[176:179], v[208:211], v[84:87]
	v_mfma_f32_16x16x32_bf16 v[80:83], v[184:187], v[208:211], v[80:83]
	v_mfma_f32_16x16x32_bf16 v[68:71], v[176:179], v[216:219], v[68:71]
	v_mfma_f32_16x16x32_bf16 v[64:67], v[184:187], v[216:219], v[64:67]
	s_barrier
	s_add_i32 s49, s44, s31
	v_lshl_add_u64 v[156:157], s[26:27], 0, v[138:139]
	s_mov_b32 m0, s49
	ds_read_b128 v[188:191], v163 offset:16384
	ds_read_b128 v[192:195], v163 offset:17408
	ds_read_b128 v[196:199], v163 offset:18432
	ds_read_b128 v[200:203], v163 offset:19456
	ds_read_b128 v[204:207], v163 offset:20480
	ds_read_b128 v[208:211], v163 offset:21504
	ds_read_b128 v[212:215], v163 offset:22528
	ds_read_b128 v[216:219], v163 offset:23552
	global_load_lds_dwordx4 v[156:157], off
	s_add_i32 m0, s49, 0x2000
	s_add_u32 s50, s26, 0x40000
	v_lshl_add_u64 v[168:169], s[26:27], 0, v[142:143]
	s_addc_u32 s51, s27, 0
	s_add_i32 s49, s45, s31
	global_load_lds_dwordx4 v[168:169], off
	v_lshl_add_u64 v[220:221], s[50:51], 0, v[138:139]
	s_mov_b32 m0, s49
	v_lshl_add_u64 v[222:223], s[28:29], 0, v[140:141]
	global_load_lds_dwordx4 v[220:221], off
	s_add_i32 m0, s49, 0x2000
	v_lshl_add_u64 v[220:221], s[50:51], 0, v[142:143]
	global_load_lds_dwordx4 v[220:221], off
	s_mov_b32 m0, s34
	v_lshl_add_u64 v[220:221], s[28:29], 0, v[136:137]
	global_load_lds_dwordx4 v[220:221], off
	s_mov_b32 m0, s35
	s_nop 0
	global_load_lds_dwordx4 v[222:223], off
	s_waitcnt vmcnt(8) lgkmcnt(0)
	s_barrier
	v_mfma_f32_16x16x32_bf16 v[60:63], v[128:131], v[188:191], 0
	v_mfma_f32_16x16x32_bf16 v[56:59], v[152:155], v[188:191], 0
	v_mfma_f32_16x16x32_bf16 v[44:47], v[128:131], v[196:199], 0
	v_mfma_f32_16x16x32_bf16 v[40:43], v[152:155], v[196:199], 0
	v_mfma_f32_16x16x32_bf16 v[28:31], v[128:131], v[204:207], 0
	v_mfma_f32_16x16x32_bf16 v[24:27], v[152:155], v[204:207], 0
	v_mfma_f32_16x16x32_bf16 v[12:15], v[128:131], v[212:215], 0
	v_mfma_f32_16x16x32_bf16 v[8:11], v[152:155], v[212:215], 0
	v_mfma_f32_16x16x32_bf16 v[60:63], v[132:135], v[192:195], v[60:63]
	v_mfma_f32_16x16x32_bf16 v[56:59], v[164:167], v[192:195], v[56:59]
	v_mfma_f32_16x16x32_bf16 v[44:47], v[132:135], v[200:203], v[44:47]
	v_mfma_f32_16x16x32_bf16 v[40:43], v[164:167], v[200:203], v[40:43]
	v_mfma_f32_16x16x32_bf16 v[28:31], v[132:135], v[208:211], v[28:31]
	v_mfma_f32_16x16x32_bf16 v[24:27], v[164:167], v[208:211], v[24:27]
	v_mfma_f32_16x16x32_bf16 v[12:15], v[132:135], v[216:219], v[12:15]
	v_mfma_f32_16x16x32_bf16 v[8:11], v[164:167], v[216:219], v[8:11]
	v_mfma_f32_16x16x32_bf16 v[52:55], v[172:175], v[188:191], 0
	v_mfma_f32_16x16x32_bf16 v[48:51], v[180:183], v[188:191], 0
	v_mfma_f32_16x16x32_bf16 v[36:39], v[172:175], v[196:199], 0
	v_mfma_f32_16x16x32_bf16 v[32:35], v[180:183], v[196:199], 0
	v_mfma_f32_16x16x32_bf16 v[20:23], v[172:175], v[204:207], 0
	v_mfma_f32_16x16x32_bf16 v[16:19], v[180:183], v[204:207], 0
	v_mfma_f32_16x16x32_bf16 v[4:7], v[172:175], v[212:215], 0
	v_mfma_f32_16x16x32_bf16 v[0:3], v[180:183], v[212:215], 0
	v_mfma_f32_16x16x32_bf16 v[52:55], v[176:179], v[192:195], v[52:55]
	v_mfma_f32_16x16x32_bf16 v[48:51], v[184:187], v[192:195], v[48:51]
	v_mfma_f32_16x16x32_bf16 v[36:39], v[176:179], v[200:203], v[36:39]
	v_mfma_f32_16x16x32_bf16 v[32:35], v[184:187], v[200:203], v[32:35]
	v_mfma_f32_16x16x32_bf16 v[20:23], v[176:179], v[208:211], v[20:23]
	v_mfma_f32_16x16x32_bf16 v[16:19], v[184:187], v[208:211], v[16:19]
	v_mfma_f32_16x16x32_bf16 v[4:7], v[176:179], v[216:219], v[4:7]
	v_mfma_f32_16x16x32_bf16 v[0:3], v[184:187], v[216:219], v[0:3]
	s_barrier
	s_branch .Lpeel124_mid
.LBB0_124:
	ds_read_b128 v[128:131], v161
	ds_read_b128 v[132:135], v161 offset:1024
	ds_read_b128 v[152:155], v161 offset:2048
	ds_read_b128 v[164:167], v161 offset:3072
	ds_read_b128 v[172:175], v162
	ds_read_b128 v[176:179], v162 offset:1024
	ds_read_b128 v[180:183], v162 offset:2048
	ds_read_b128 v[184:187], v162 offset:3072
	s_add_u32 s26, s2, 0xfffc0080
	s_addc_u32 s27, s3, -1
	s_cmp_eq_u32 s47, 12
	s_cselect_b32 s29, s5, s27
	s_cselect_b32 s28, s19, s26
	s_cselect_b32 s27, s17, s46
	s_cselect_b32 s26, s25, s33
	v_lshl_add_u64 v[156:157], s[2:3], 0, v[144:145]
	s_add_i32 m0, s34, 0xc000
	ds_read_b128 v[188:191], v163
	ds_read_b128 v[192:195], v163 offset:1024
	ds_read_b128 v[196:199], v163 offset:2048
	ds_read_b128 v[200:203], v163 offset:3072
	ds_read_b128 v[204:207], v163 offset:4096
	ds_read_b128 v[208:211], v163 offset:5120
	ds_read_b128 v[212:215], v163 offset:6144
	ds_read_b128 v[216:219], v163 offset:7168
	global_load_lds_dwordx4 v[156:157], off
	s_add_i32 m0, s34, 0xe000
	v_lshl_add_u64 v[156:157], s[2:3], 0, v[146:147]
	global_load_lds_dwordx4 v[156:157], off
	s_waitcnt vmcnt(8) lgkmcnt(0)
	s_barrier
	v_mfma_f32_16x16x32_bf16 v[124:127], v[128:131], v[188:191], v[124:127]
	v_mfma_f32_16x16x32_bf16 v[120:123], v[152:155], v[188:191], v[120:123]
	v_mfma_f32_16x16x32_bf16 v[108:111], v[128:131], v[196:199], v[108:111]
	v_mfma_f32_16x16x32_bf16 v[104:107], v[152:155], v[196:199], v[104:107]
	v_mfma_f32_16x16x32_bf16 v[92:95], v[128:131], v[204:207], v[92:95]
	v_mfma_f32_16x16x32_bf16 v[88:91], v[152:155], v[204:207], v[88:91]
	v_mfma_f32_16x16x32_bf16 v[76:79], v[128:131], v[212:215], v[76:79]
	v_mfma_f32_16x16x32_bf16 v[72:75], v[152:155], v[212:215], v[72:75]
	v_mfma_f32_16x16x32_bf16 v[124:127], v[132:135], v[192:195], v[124:127]
	v_mfma_f32_16x16x32_bf16 v[120:123], v[164:167], v[192:195], v[120:123]
	v_mfma_f32_16x16x32_bf16 v[108:111], v[132:135], v[200:203], v[108:111]
	v_mfma_f32_16x16x32_bf16 v[104:107], v[164:167], v[200:203], v[104:107]
	v_mfma_f32_16x16x32_bf16 v[92:95], v[132:135], v[208:211], v[92:95]
	v_mfma_f32_16x16x32_bf16 v[88:91], v[164:167], v[208:211], v[88:91]
	v_mfma_f32_16x16x32_bf16 v[76:79], v[132:135], v[216:219], v[76:79]
	v_mfma_f32_16x16x32_bf16 v[72:75], v[164:167], v[216:219], v[72:75]
	v_mfma_f32_16x16x32_bf16 v[116:119], v[172:175], v[188:191], v[116:119]
	v_mfma_f32_16x16x32_bf16 v[112:115], v[180:183], v[188:191], v[112:115]
	v_mfma_f32_16x16x32_bf16 v[100:103], v[172:175], v[196:199], v[100:103]
	v_mfma_f32_16x16x32_bf16 v[96:99], v[180:183], v[196:199], v[96:99]
	v_mfma_f32_16x16x32_bf16 v[84:87], v[172:175], v[204:207], v[84:87]
	v_mfma_f32_16x16x32_bf16 v[80:83], v[180:183], v[204:207], v[80:83]
	v_mfma_f32_16x16x32_bf16 v[68:71], v[172:175], v[212:215], v[68:71]
	v_mfma_f32_16x16x32_bf16 v[64:67], v[180:183], v[212:215], v[64:67]
	v_mfma_f32_16x16x32_bf16 v[116:119], v[176:179], v[192:195], v[116:119]
	v_mfma_f32_16x16x32_bf16 v[112:115], v[184:187], v[192:195], v[112:115]
	v_mfma_f32_16x16x32_bf16 v[100:103], v[176:179], v[200:203], v[100:103]
	v_mfma_f32_16x16x32_bf16 v[96:99], v[184:187], v[200:203], v[96:99]
	v_mfma_f32_16x16x32_bf16 v[84:87], v[176:179], v[208:211], v[84:87]
	v_mfma_f32_16x16x32_bf16 v[80:83], v[184:187], v[208:211], v[80:83]
	v_mfma_f32_16x16x32_bf16 v[68:71], v[176:179], v[216:219], v[68:71]
	v_mfma_f32_16x16x32_bf16 v[64:67], v[184:187], v[216:219], v[64:67]
	s_barrier
	s_add_i32 s49, s44, s31
	v_lshl_add_u64 v[156:157], s[26:27], 0, v[138:139]
	s_mov_b32 m0, s49
	ds_read_b128 v[188:191], v163 offset:16384
	ds_read_b128 v[192:195], v163 offset:17408
	ds_read_b128 v[196:199], v163 offset:18432
	ds_read_b128 v[200:203], v163 offset:19456
	ds_read_b128 v[204:207], v163 offset:20480
	ds_read_b128 v[208:211], v163 offset:21504
	ds_read_b128 v[212:215], v163 offset:22528
	ds_read_b128 v[216:219], v163 offset:23552
	global_load_lds_dwordx4 v[156:157], off
	s_add_i32 m0, s49, 0x2000
	s_add_u32 s50, s26, 0x40000
	v_lshl_add_u64 v[168:169], s[26:27], 0, v[142:143]
	s_addc_u32 s51, s27, 0
	s_add_i32 s49, s45, s31
	global_load_lds_dwordx4 v[168:169], off
	v_lshl_add_u64 v[220:221], s[50:51], 0, v[138:139]
	s_mov_b32 m0, s49
	v_lshl_add_u64 v[222:223], s[28:29], 0, v[140:141]
	global_load_lds_dwordx4 v[220:221], off
	s_add_i32 m0, s49, 0x2000
	v_lshl_add_u64 v[220:221], s[50:51], 0, v[142:143]
	global_load_lds_dwordx4 v[220:221], off
	s_mov_b32 m0, s34
	v_lshl_add_u64 v[220:221], s[28:29], 0, v[136:137]
	global_load_lds_dwordx4 v[220:221], off
	s_mov_b32 m0, s35
	s_nop 0
	global_load_lds_dwordx4 v[222:223], off
	s_waitcnt vmcnt(8) lgkmcnt(0)
	s_barrier
	v_mfma_f32_16x16x32_bf16 v[60:63], v[128:131], v[188:191], v[60:63]
	v_mfma_f32_16x16x32_bf16 v[56:59], v[152:155], v[188:191], v[56:59]
	v_mfma_f32_16x16x32_bf16 v[44:47], v[128:131], v[196:199], v[44:47]
	v_mfma_f32_16x16x32_bf16 v[40:43], v[152:155], v[196:199], v[40:43]
	v_mfma_f32_16x16x32_bf16 v[28:31], v[128:131], v[204:207], v[28:31]
	v_mfma_f32_16x16x32_bf16 v[24:27], v[152:155], v[204:207], v[24:27]
	v_mfma_f32_16x16x32_bf16 v[12:15], v[128:131], v[212:215], v[12:15]
	v_mfma_f32_16x16x32_bf16 v[8:11], v[152:155], v[212:215], v[8:11]
	v_mfma_f32_16x16x32_bf16 v[60:63], v[132:135], v[192:195], v[60:63]
	v_mfma_f32_16x16x32_bf16 v[56:59], v[164:167], v[192:195], v[56:59]
	v_mfma_f32_16x16x32_bf16 v[44:47], v[132:135], v[200:203], v[44:47]
	v_mfma_f32_16x16x32_bf16 v[40:43], v[164:167], v[200:203], v[40:43]
	v_mfma_f32_16x16x32_bf16 v[28:31], v[132:135], v[208:211], v[28:31]
	v_mfma_f32_16x16x32_bf16 v[24:27], v[164:167], v[208:211], v[24:27]
	v_mfma_f32_16x16x32_bf16 v[12:15], v[132:135], v[216:219], v[12:15]
	v_mfma_f32_16x16x32_bf16 v[8:11], v[164:167], v[216:219], v[8:11]
	v_mfma_f32_16x16x32_bf16 v[52:55], v[172:175], v[188:191], v[52:55]
	v_mfma_f32_16x16x32_bf16 v[48:51], v[180:183], v[188:191], v[48:51]
	v_mfma_f32_16x16x32_bf16 v[36:39], v[172:175], v[196:199], v[36:39]
	v_mfma_f32_16x16x32_bf16 v[32:35], v[180:183], v[196:199], v[32:35]
	v_mfma_f32_16x16x32_bf16 v[20:23], v[172:175], v[204:207], v[20:23]
	v_mfma_f32_16x16x32_bf16 v[16:19], v[180:183], v[204:207], v[16:19]
	v_mfma_f32_16x16x32_bf16 v[4:7], v[172:175], v[212:215], v[4:7]
	v_mfma_f32_16x16x32_bf16 v[0:3], v[180:183], v[212:215], v[0:3]
	v_mfma_f32_16x16x32_bf16 v[52:55], v[176:179], v[192:195], v[52:55]
	v_mfma_f32_16x16x32_bf16 v[48:51], v[184:187], v[192:195], v[48:51]
	v_mfma_f32_16x16x32_bf16 v[36:39], v[176:179], v[200:203], v[36:39]
	v_mfma_f32_16x16x32_bf16 v[32:35], v[184:187], v[200:203], v[32:35]
	v_mfma_f32_16x16x32_bf16 v[20:23], v[176:179], v[208:211], v[20:23]
	v_mfma_f32_16x16x32_bf16 v[16:19], v[184:187], v[208:211], v[16:19]
	v_mfma_f32_16x16x32_bf16 v[4:7], v[176:179], v[216:219], v[4:7]
	v_mfma_f32_16x16x32_bf16 v[0:3], v[184:187], v[216:219], v[0:3]
	s_barrier
.Lpeel124_mid:
	s_add_i32 s49, 0, 0x18000
	s_add_i32 s50, 0, 0x1c000
	v_add_u32_e32 v164, s49, v159
	v_add_u32_e32 v184, s50, v159
	ds_read_b128 v[128:131], v164
	ds_read_b128 v[132:135], v164 offset:1024
	ds_read_b128 v[152:155], v164 offset:2048
	ds_read_b128 v[164:167], v164 offset:3072
	ds_read_b128 v[172:175], v184
	ds_read_b128 v[176:179], v184 offset:1024
	ds_read_b128 v[180:183], v184 offset:2048
	ds_read_b128 v[184:187], v184 offset:3072
	s_add_u32 s28, s28, 0x40000
	s_addc_u32 s29, s29, 0
	s_mov_b32 m0, s36
	v_lshl_add_u64 v[224:225], s[28:29], 0, v[136:137]
	ds_read_b128 v[188:191], v163 offset:32768
	ds_read_b128 v[192:195], v163 offset:33792
	ds_read_b128 v[196:199], v163 offset:34816
	ds_read_b128 v[200:203], v163 offset:35840
	ds_read_b128 v[204:207], v163 offset:36864
	ds_read_b128 v[208:211], v163 offset:37888
	ds_read_b128 v[212:215], v163 offset:38912
	ds_read_b128 v[216:219], v163 offset:39936
	global_load_lds_dwordx4 v[224:225], off
	s_mov_b32 m0, s37
	v_lshl_add_u64 v[224:225], s[28:29], 0, v[140:141]
	global_load_lds_dwordx4 v[224:225], off
	s_waitcnt vmcnt(8) lgkmcnt(0)
	s_barrier
	v_mfma_f32_16x16x32_bf16 v[124:127], v[128:131], v[188:191], v[124:127]
	v_mfma_f32_16x16x32_bf16 v[120:123], v[152:155], v[188:191], v[120:123]
	v_mfma_f32_16x16x32_bf16 v[108:111], v[128:131], v[196:199], v[108:111]
	v_mfma_f32_16x16x32_bf16 v[104:107], v[152:155], v[196:199], v[104:107]
	v_mfma_f32_16x16x32_bf16 v[92:95], v[128:131], v[204:207], v[92:95]
	v_mfma_f32_16x16x32_bf16 v[88:91], v[152:155], v[204:207], v[88:91]
	v_mfma_f32_16x16x32_bf16 v[76:79], v[128:131], v[212:215], v[76:79]
	v_mfma_f32_16x16x32_bf16 v[72:75], v[152:155], v[212:215], v[72:75]
	v_mfma_f32_16x16x32_bf16 v[124:127], v[132:135], v[192:195], v[124:127]
	v_mfma_f32_16x16x32_bf16 v[120:123], v[164:167], v[192:195], v[120:123]
	v_mfma_f32_16x16x32_bf16 v[108:111], v[132:135], v[200:203], v[108:111]
	v_mfma_f32_16x16x32_bf16 v[104:107], v[164:167], v[200:203], v[104:107]
	v_mfma_f32_16x16x32_bf16 v[92:95], v[132:135], v[208:211], v[92:95]
	v_mfma_f32_16x16x32_bf16 v[88:91], v[164:167], v[208:211], v[88:91]
	v_mfma_f32_16x16x32_bf16 v[76:79], v[132:135], v[216:219], v[76:79]
	v_mfma_f32_16x16x32_bf16 v[72:75], v[164:167], v[216:219], v[72:75]
	v_mfma_f32_16x16x32_bf16 v[116:119], v[172:175], v[188:191], v[116:119]
	v_mfma_f32_16x16x32_bf16 v[112:115], v[180:183], v[188:191], v[112:115]
	v_mfma_f32_16x16x32_bf16 v[100:103], v[172:175], v[196:199], v[100:103]
	v_mfma_f32_16x16x32_bf16 v[96:99], v[180:183], v[196:199], v[96:99]
	v_mfma_f32_16x16x32_bf16 v[84:87], v[172:175], v[204:207], v[84:87]
	v_mfma_f32_16x16x32_bf16 v[80:83], v[180:183], v[204:207], v[80:83]
	v_mfma_f32_16x16x32_bf16 v[68:71], v[172:175], v[212:215], v[68:71]
	v_mfma_f32_16x16x32_bf16 v[64:67], v[180:183], v[212:215], v[64:67]
	v_mfma_f32_16x16x32_bf16 v[116:119], v[176:179], v[192:195], v[116:119]
	v_mfma_f32_16x16x32_bf16 v[112:115], v[184:187], v[192:195], v[112:115]
	v_mfma_f32_16x16x32_bf16 v[100:103], v[176:179], v[200:203], v[100:103]
	v_mfma_f32_16x16x32_bf16 v[96:99], v[184:187], v[200:203], v[96:99]
	v_mfma_f32_16x16x32_bf16 v[84:87], v[176:179], v[208:211], v[84:87]
	v_mfma_f32_16x16x32_bf16 v[80:83], v[184:187], v[208:211], v[80:83]
	v_mfma_f32_16x16x32_bf16 v[68:71], v[176:179], v[216:219], v[68:71]
	v_mfma_f32_16x16x32_bf16 v[64:67], v[184:187], v[216:219], v[64:67]
	s_barrier
	s_add_i32 s28, s49, s31
	v_lshl_add_u64 v[156:157], v[156:157], 0, s[10:11]
	s_mov_b32 m0, s28
	ds_read_b128 v[188:191], v163 offset:49152
	ds_read_b128 v[192:195], v163 offset:50176
	ds_read_b128 v[196:199], v163 offset:51200
	ds_read_b128 v[200:203], v163 offset:52224
	ds_read_b128 v[204:207], v163 offset:53248
	ds_read_b128 v[208:211], v163 offset:54272
	ds_read_b128 v[212:215], v163 offset:55296
	ds_read_b128 v[216:219], v163 offset:56320
	global_load_lds_dwordx4 v[156:157], off
	s_add_i32 m0, s28, 0x2000
	s_add_u32 s26, s26, 0x40080
	v_lshl_add_u64 v[156:157], v[168:169], 0, s[10:11]
	s_addc_u32 s27, s27, 0
	s_add_i32 s28, s50, s31
	global_load_lds_dwordx4 v[156:157], off
	s_mov_b32 m0, s28
	v_lshl_add_u64 v[156:157], s[26:27], 0, v[138:139]
	global_load_lds_dwordx4 v[156:157], off
	s_add_i32 m0, s28, 0x2000
	v_lshl_add_u64 v[156:157], s[26:27], 0, v[142:143]
	global_load_lds_dwordx4 v[156:157], off
	v_lshl_add_u64 v[156:157], v[220:221], 0, s[10:11]
	s_mov_b32 m0, s41
	s_nop 0
	global_load_lds_dwordx4 v[156:157], off
	v_lshl_add_u64 v[156:157], v[222:223], 0, s[10:11]
	s_mov_b32 m0, s42
	s_nop 0
	global_load_lds_dwordx4 v[156:157], off
	s_waitcnt vmcnt(8) lgkmcnt(0)
	s_barrier
	v_mfma_f32_16x16x32_bf16 v[60:63], v[128:131], v[188:191], v[60:63]
	v_mfma_f32_16x16x32_bf16 v[56:59], v[152:155], v[188:191], v[56:59]
	v_mfma_f32_16x16x32_bf16 v[44:47], v[128:131], v[196:199], v[44:47]
	v_mfma_f32_16x16x32_bf16 v[40:43], v[152:155], v[196:199], v[40:43]
	v_mfma_f32_16x16x32_bf16 v[28:31], v[128:131], v[204:207], v[28:31]
	v_mfma_f32_16x16x32_bf16 v[24:27], v[152:155], v[204:207], v[24:27]
	v_mfma_f32_16x16x32_bf16 v[12:15], v[128:131], v[212:215], v[12:15]
	v_mfma_f32_16x16x32_bf16 v[8:11], v[152:155], v[212:215], v[8:11]
	v_mfma_f32_16x16x32_bf16 v[60:63], v[132:135], v[192:195], v[60:63]
	v_mfma_f32_16x16x32_bf16 v[56:59], v[164:167], v[192:195], v[56:59]
	v_mfma_f32_16x16x32_bf16 v[44:47], v[132:135], v[200:203], v[44:47]
	v_mfma_f32_16x16x32_bf16 v[40:43], v[164:167], v[200:203], v[40:43]
	v_mfma_f32_16x16x32_bf16 v[28:31], v[132:135], v[208:211], v[28:31]
	v_mfma_f32_16x16x32_bf16 v[24:27], v[164:167], v[208:211], v[24:27]
	v_mfma_f32_16x16x32_bf16 v[12:15], v[132:135], v[216:219], v[12:15]
	v_mfma_f32_16x16x32_bf16 v[8:11], v[164:167], v[216:219], v[8:11]
	v_mfma_f32_16x16x32_bf16 v[52:55], v[172:175], v[188:191], v[52:55]
	v_mfma_f32_16x16x32_bf16 v[48:51], v[180:183], v[188:191], v[48:51]
	v_mfma_f32_16x16x32_bf16 v[36:39], v[172:175], v[196:199], v[36:39]
	v_mfma_f32_16x16x32_bf16 v[32:35], v[180:183], v[196:199], v[32:35]
	v_mfma_f32_16x16x32_bf16 v[20:23], v[172:175], v[204:207], v[20:23]
	v_mfma_f32_16x16x32_bf16 v[16:19], v[180:183], v[204:207], v[16:19]
	v_mfma_f32_16x16x32_bf16 v[4:7], v[172:175], v[212:215], v[4:7]
	v_mfma_f32_16x16x32_bf16 v[0:3], v[180:183], v[212:215], v[0:3]
	v_mfma_f32_16x16x32_bf16 v[52:55], v[176:179], v[192:195], v[52:55]
	v_mfma_f32_16x16x32_bf16 v[48:51], v[184:187], v[192:195], v[48:51]
	v_mfma_f32_16x16x32_bf16 v[36:39], v[176:179], v[200:203], v[36:39]
	v_mfma_f32_16x16x32_bf16 v[32:35], v[184:187], v[200:203], v[32:35]
	v_mfma_f32_16x16x32_bf16 v[20:23], v[176:179], v[208:211], v[20:23]
	v_mfma_f32_16x16x32_bf16 v[16:19], v[184:187], v[208:211], v[16:19]
	v_mfma_f32_16x16x32_bf16 v[4:7], v[176:179], v[216:219], v[4:7]
	v_mfma_f32_16x16x32_bf16 v[0:3], v[184:187], v[216:219], v[0:3]
	s_barrier
	s_add_i32 s47, s47, 2
	s_add_u32 s2, s2, 0x100
	s_addc_u32 s3, s3, 0
	s_add_u32 s33, s33, 0x100
	s_addc_u32 s46, s46, 0
	s_cmp_gt_u32 s47, 13
	s_cbranch_scc0 .LBB0_124
	s_and_b64 vcc, exec, s[12:13]
	s_cbranch_vccz .LBB0_127
	s_barrier

.LBB0_456:
	v_readlane_b32 s68, v246, 32
	v_readlane_b32 s69, v246, 33
	s_ashr_i32 s13, s12, 31
	v_readlane_b32 s70, v246, 34
	v_readlane_b32 s71, v246, 35
	s_mov_b64 s[60:61], s[68:69]
	s_lshl_b64 s[14:15], s[12:13], 19
	s_mov_b64 s[62:63], s[70:71]
	s_add_u32 s14, s62, s14
	s_addc_u32 s15, s63, s15
	s_and_b64 s[16:17], s[0:1], exec
	s_cselect_b32 s13, s15, s21
	s_cselect_b32 s42, s14, s20
	s_ashr_i32 s11, s10, 31
	s_lshl_b64 s[16:17], s[10:11], 19
	v_readlane_b32 s24, v246, 36
	v_readlane_b32 s25, v246, 37
	s_add_u32 s16, s24, s16
	s_addc_u32 s17, s25, s17
	s_and_b64 s[24:25], s[0:1], exec
	s_cselect_b32 s11, s17, s23
	s_cselect_b32 s43, s16, s22
	s_add_u32 s20, s20, 0x40080
	s_addc_u32 s21, s21, 0
	s_add_u32 s44, s22, 0x100
	s_addc_u32 s45, s23, 0
	s_mov_b32 s46, -2
	ds_read_b128 v[152:155], v148
	ds_read_b128 v[156:159], v148 offset:1024
	ds_read_b128 v[160:163], v148 offset:2048
	ds_read_b128 v[164:167], v148 offset:3072
	ds_read_b128 v[172:175], v149
	ds_read_b128 v[176:179], v149 offset:1024
	ds_read_b128 v[180:183], v149 offset:2048
	ds_read_b128 v[184:187], v149 offset:3072
	s_add_u32 s22, s20, 0xfffc0080
	s_addc_u32 s23, s21, -1
	s_cmp_eq_u32 s46, 12
	s_cselect_b32 s25, s13, s23
	s_cselect_b32 s24, s42, s22
	s_cselect_b32 s23, s11, s45
	s_cselect_b32 s22, s43, s44
	v_lshl_add_u64 v[168:169], s[20:21], 0, v[136:137]
	s_add_i32 m0, s19, 0xc000
	ds_read_b128 v[188:191], v150
	ds_read_b128 v[192:195], v150 offset:1024
	ds_read_b128 v[196:199], v150 offset:2048
	ds_read_b128 v[200:203], v150 offset:3072
	ds_read_b128 v[204:207], v150 offset:4096
	ds_read_b128 v[208:211], v150 offset:5120
	ds_read_b128 v[212:215], v150 offset:6144
	ds_read_b128 v[216:219], v150 offset:7168
	global_load_lds_dwordx4 v[168:169], off
	s_add_i32 m0, s19, 0xe000
	v_lshl_add_u64 v[168:169], s[20:21], 0, v[138:139]
	global_load_lds_dwordx4 v[168:169], off
	s_waitcnt vmcnt(8) lgkmcnt(0)
	s_barrier
	v_mfma_f32_16x16x32_bf16 v[124:127], v[152:155], v[188:191], 0
	v_mfma_f32_16x16x32_bf16 v[120:123], v[160:163], v[188:191], 0
	v_mfma_f32_16x16x32_bf16 v[116:119], v[152:155], v[196:199], 0
	v_mfma_f32_16x16x32_bf16 v[108:111], v[160:163], v[196:199], 0
	v_mfma_f32_16x16x32_bf16 v[100:103], v[152:155], v[204:207], 0
	v_mfma_f32_16x16x32_bf16 v[92:95], v[160:163], v[204:207], 0
	v_mfma_f32_16x16x32_bf16 v[84:87], v[152:155], v[212:215], 0
	v_mfma_f32_16x16x32_bf16 v[76:79], v[160:163], v[212:215], 0
	v_mfma_f32_16x16x32_bf16 v[124:127], v[156:159], v[192:195], v[124:127]
	v_mfma_f32_16x16x32_bf16 v[120:123], v[164:167], v[192:195], v[120:123]
	v_mfma_f32_16x16x32_bf16 v[116:119], v[156:159], v[200:203], v[116:119]
	v_mfma_f32_16x16x32_bf16 v[108:111], v[164:167], v[200:203], v[108:111]
	v_mfma_f32_16x16x32_bf16 v[100:103], v[156:159], v[208:211], v[100:103]
	v_mfma_f32_16x16x32_bf16 v[92:95], v[164:167], v[208:211], v[92:95]
	v_mfma_f32_16x16x32_bf16 v[84:87], v[156:159], v[216:219], v[84:87]
	v_mfma_f32_16x16x32_bf16 v[76:79], v[164:167], v[216:219], v[76:79]
	v_mfma_f32_16x16x32_bf16 v[112:115], v[172:175], v[188:191], 0
	v_mfma_f32_16x16x32_bf16 v[104:107], v[180:183], v[188:191], 0
	v_mfma_f32_16x16x32_bf16 v[96:99], v[172:175], v[196:199], 0
	v_mfma_f32_16x16x32_bf16 v[88:91], v[180:183], v[196:199], 0
	v_mfma_f32_16x16x32_bf16 v[80:83], v[172:175], v[204:207], 0
	v_mfma_f32_16x16x32_bf16 v[72:75], v[180:183], v[204:207], 0
	v_mfma_f32_16x16x32_bf16 v[68:71], v[172:175], v[212:215], 0
	v_mfma_f32_16x16x32_bf16 v[64:67], v[180:183], v[212:215], 0
	v_mfma_f32_16x16x32_bf16 v[112:115], v[176:179], v[192:195], v[112:115]
	v_mfma_f32_16x16x32_bf16 v[104:107], v[184:187], v[192:195], v[104:107]
	v_mfma_f32_16x16x32_bf16 v[96:99], v[176:179], v[200:203], v[96:99]
	v_mfma_f32_16x16x32_bf16 v[88:91], v[184:187], v[200:203], v[88:91]
	v_mfma_f32_16x16x32_bf16 v[80:83], v[176:179], v[208:211], v[80:83]
	v_mfma_f32_16x16x32_bf16 v[72:75], v[184:187], v[208:211], v[72:75]
	v_mfma_f32_16x16x32_bf16 v[68:71], v[176:179], v[216:219], v[68:71]
	v_mfma_f32_16x16x32_bf16 v[64:67], v[184:187], v[216:219], v[64:67]
	s_barrier
	s_add_i32 s47, s38, s26
	v_lshl_add_u64 v[168:169], s[22:23], 0, v[130:131]
	s_mov_b32 m0, s47
	ds_read_b128 v[188:191], v150 offset:16384
	ds_read_b128 v[192:195], v150 offset:17408
	ds_read_b128 v[196:199], v150 offset:18432
	ds_read_b128 v[200:203], v150 offset:19456
	ds_read_b128 v[204:207], v150 offset:20480
	ds_read_b128 v[208:211], v150 offset:21504
	ds_read_b128 v[212:215], v150 offset:22528
	ds_read_b128 v[216:219], v150 offset:23552
	global_load_lds_dwordx4 v[168:169], off
	s_add_i32 m0, s47, 0x2000
	s_add_u32 s48, s22, 0x40000
	v_lshl_add_u64 v[220:221], s[22:23], 0, v[134:135]
	s_addc_u32 s49, s23, 0
	s_add_i32 s47, s39, s26
	global_load_lds_dwordx4 v[220:221], off
	v_lshl_add_u64 v[222:223], s[48:49], 0, v[130:131]
	s_mov_b32 m0, s47
	v_lshl_add_u64 v[224:225], s[24:25], 0, v[132:133]
	global_load_lds_dwordx4 v[222:223], off
	s_add_i32 m0, s47, 0x2000
	v_lshl_add_u64 v[222:223], s[48:49], 0, v[134:135]
	global_load_lds_dwordx4 v[222:223], off
	s_mov_b32 m0, s19
	v_lshl_add_u64 v[222:223], s[24:25], 0, v[128:129]
	global_load_lds_dwordx4 v[222:223], off
	s_mov_b32 m0, s29
	s_nop 0
	global_load_lds_dwordx4 v[224:225], off
	s_waitcnt vmcnt(8) lgkmcnt(0)
	s_barrier
	v_mfma_f32_16x16x32_bf16 v[60:63], v[152:155], v[188:191], 0
	v_mfma_f32_16x16x32_bf16 v[56:59], v[160:163], v[188:191], 0
	v_mfma_f32_16x16x32_bf16 v[52:55], v[152:155], v[196:199], 0
	v_mfma_f32_16x16x32_bf16 v[44:47], v[160:163], v[196:199], 0
	v_mfma_f32_16x16x32_bf16 v[36:39], v[152:155], v[204:207], 0
	v_mfma_f32_16x16x32_bf16 v[28:31], v[160:163], v[204:207], 0
	v_mfma_f32_16x16x32_bf16 v[20:23], v[152:155], v[212:215], 0
	v_mfma_f32_16x16x32_bf16 v[12:15], v[160:163], v[212:215], 0
	v_mfma_f32_16x16x32_bf16 v[60:63], v[156:159], v[192:195], v[60:63]
	v_mfma_f32_16x16x32_bf16 v[56:59], v[164:167], v[192:195], v[56:59]
	v_mfma_f32_16x16x32_bf16 v[52:55], v[156:159], v[200:203], v[52:55]
	v_mfma_f32_16x16x32_bf16 v[44:47], v[164:167], v[200:203], v[44:47]
	v_mfma_f32_16x16x32_bf16 v[36:39], v[156:159], v[208:211], v[36:39]
	v_mfma_f32_16x16x32_bf16 v[28:31], v[164:167], v[208:211], v[28:31]
	v_mfma_f32_16x16x32_bf16 v[20:23], v[156:159], v[216:219], v[20:23]
	v_mfma_f32_16x16x32_bf16 v[12:15], v[164:167], v[216:219], v[12:15]
	v_mfma_f32_16x16x32_bf16 v[48:51], v[172:175], v[188:191], 0
	v_mfma_f32_16x16x32_bf16 v[40:43], v[180:183], v[188:191], 0
	v_mfma_f32_16x16x32_bf16 v[32:35], v[172:175], v[196:199], 0
	v_mfma_f32_16x16x32_bf16 v[24:27], v[180:183], v[196:199], 0
	v_mfma_f32_16x16x32_bf16 v[16:19], v[172:175], v[204:207], 0
	v_mfma_f32_16x16x32_bf16 v[8:11], v[180:183], v[204:207], 0
	v_mfma_f32_16x16x32_bf16 v[4:7], v[172:175], v[212:215], 0
	v_mfma_f32_16x16x32_bf16 v[0:3], v[180:183], v[212:215], 0
	v_mfma_f32_16x16x32_bf16 v[48:51], v[176:179], v[192:195], v[48:51]
	v_mfma_f32_16x16x32_bf16 v[40:43], v[184:187], v[192:195], v[40:43]
	v_mfma_f32_16x16x32_bf16 v[32:35], v[176:179], v[200:203], v[32:35]
	v_mfma_f32_16x16x32_bf16 v[24:27], v[184:187], v[200:203], v[24:27]
	v_mfma_f32_16x16x32_bf16 v[16:19], v[176:179], v[208:211], v[16:19]
	v_mfma_f32_16x16x32_bf16 v[8:11], v[184:187], v[208:211], v[8:11]
	v_mfma_f32_16x16x32_bf16 v[4:7], v[176:179], v[216:219], v[4:7]
	v_mfma_f32_16x16x32_bf16 v[0:3], v[184:187], v[216:219], v[0:3]
	s_barrier
	s_branch .Lpeel457_mid
.LBB0_457:
	ds_read_b128 v[152:155], v148
	ds_read_b128 v[156:159], v148 offset:1024
	ds_read_b128 v[160:163], v148 offset:2048
	ds_read_b128 v[164:167], v148 offset:3072
	ds_read_b128 v[172:175], v149
	ds_read_b128 v[176:179], v149 offset:1024
	ds_read_b128 v[180:183], v149 offset:2048
	ds_read_b128 v[184:187], v149 offset:3072
	s_add_u32 s22, s20, 0xfffc0080
	s_addc_u32 s23, s21, -1
	s_cmp_eq_u32 s46, 12
	s_cselect_b32 s25, s13, s23
	s_cselect_b32 s24, s42, s22
	s_cselect_b32 s23, s11, s45
	s_cselect_b32 s22, s43, s44
	v_lshl_add_u64 v[168:169], s[20:21], 0, v[136:137]
	s_add_i32 m0, s19, 0xc000
	ds_read_b128 v[188:191], v150
	ds_read_b128 v[192:195], v150 offset:1024
	ds_read_b128 v[196:199], v150 offset:2048
	ds_read_b128 v[200:203], v150 offset:3072
	ds_read_b128 v[204:207], v150 offset:4096
	ds_read_b128 v[208:211], v150 offset:5120
	ds_read_b128 v[212:215], v150 offset:6144
	ds_read_b128 v[216:219], v150 offset:7168
	global_load_lds_dwordx4 v[168:169], off
	s_add_i32 m0, s19, 0xe000
	v_lshl_add_u64 v[168:169], s[20:21], 0, v[138:139]
	global_load_lds_dwordx4 v[168:169], off
	s_waitcnt vmcnt(8) lgkmcnt(0)
	s_barrier
	v_mfma_f32_16x16x32_bf16 v[124:127], v[152:155], v[188:191], v[124:127]
	v_mfma_f32_16x16x32_bf16 v[120:123], v[160:163], v[188:191], v[120:123]
	v_mfma_f32_16x16x32_bf16 v[116:119], v[152:155], v[196:199], v[116:119]
	v_mfma_f32_16x16x32_bf16 v[108:111], v[160:163], v[196:199], v[108:111]
	v_mfma_f32_16x16x32_bf16 v[100:103], v[152:155], v[204:207], v[100:103]
	v_mfma_f32_16x16x32_bf16 v[92:95], v[160:163], v[204:207], v[92:95]
	v_mfma_f32_16x16x32_bf16 v[84:87], v[152:155], v[212:215], v[84:87]
	v_mfma_f32_16x16x32_bf16 v[76:79], v[160:163], v[212:215], v[76:79]
	v_mfma_f32_16x16x32_bf16 v[124:127], v[156:159], v[192:195], v[124:127]
	v_mfma_f32_16x16x32_bf16 v[120:123], v[164:167], v[192:195], v[120:123]
	v_mfma_f32_16x16x32_bf16 v[116:119], v[156:159], v[200:203], v[116:119]
	v_mfma_f32_16x16x32_bf16 v[108:111], v[164:167], v[200:203], v[108:111]
	v_mfma_f32_16x16x32_bf16 v[100:103], v[156:159], v[208:211], v[100:103]
	v_mfma_f32_16x16x32_bf16 v[92:95], v[164:167], v[208:211], v[92:95]
	v_mfma_f32_16x16x32_bf16 v[84:87], v[156:159], v[216:219], v[84:87]
	v_mfma_f32_16x16x32_bf16 v[76:79], v[164:167], v[216:219], v[76:79]
	v_mfma_f32_16x16x32_bf16 v[112:115], v[172:175], v[188:191], v[112:115]
	v_mfma_f32_16x16x32_bf16 v[104:107], v[180:183], v[188:191], v[104:107]
	v_mfma_f32_16x16x32_bf16 v[96:99], v[172:175], v[196:199], v[96:99]
	v_mfma_f32_16x16x32_bf16 v[88:91], v[180:183], v[196:199], v[88:91]
	v_mfma_f32_16x16x32_bf16 v[80:83], v[172:175], v[204:207], v[80:83]
	v_mfma_f32_16x16x32_bf16 v[72:75], v[180:183], v[204:207], v[72:75]
	v_mfma_f32_16x16x32_bf16 v[68:71], v[172:175], v[212:215], v[68:71]
	v_mfma_f32_16x16x32_bf16 v[64:67], v[180:183], v[212:215], v[64:67]
	v_mfma_f32_16x16x32_bf16 v[112:115], v[176:179], v[192:195], v[112:115]
	v_mfma_f32_16x16x32_bf16 v[104:107], v[184:187], v[192:195], v[104:107]
	v_mfma_f32_16x16x32_bf16 v[96:99], v[176:179], v[200:203], v[96:99]
	v_mfma_f32_16x16x32_bf16 v[88:91], v[184:187], v[200:203], v[88:91]
	v_mfma_f32_16x16x32_bf16 v[80:83], v[176:179], v[208:211], v[80:83]
	v_mfma_f32_16x16x32_bf16 v[72:75], v[184:187], v[208:211], v[72:75]
	v_mfma_f32_16x16x32_bf16 v[68:71], v[176:179], v[216:219], v[68:71]
	v_mfma_f32_16x16x32_bf16 v[64:67], v[184:187], v[216:219], v[64:67]
	s_barrier
	s_add_i32 s47, s38, s26
	v_lshl_add_u64 v[168:169], s[22:23], 0, v[130:131]
	s_mov_b32 m0, s47
	ds_read_b128 v[188:191], v150 offset:16384
	ds_read_b128 v[192:195], v150 offset:17408
	ds_read_b128 v[196:199], v150 offset:18432
	ds_read_b128 v[200:203], v150 offset:19456
	ds_read_b128 v[204:207], v150 offset:20480
	ds_read_b128 v[208:211], v150 offset:21504
	ds_read_b128 v[212:215], v150 offset:22528
	ds_read_b128 v[216:219], v150 offset:23552
	global_load_lds_dwordx4 v[168:169], off
	s_add_i32 m0, s47, 0x2000
	s_add_u32 s48, s22, 0x40000
	v_lshl_add_u64 v[220:221], s[22:23], 0, v[134:135]
	s_addc_u32 s49, s23, 0
	s_add_i32 s47, s39, s26
	global_load_lds_dwordx4 v[220:221], off
	v_lshl_add_u64 v[222:223], s[48:49], 0, v[130:131]
	s_mov_b32 m0, s47
	v_lshl_add_u64 v[224:225], s[24:25], 0, v[132:133]
	global_load_lds_dwordx4 v[222:223], off
	s_add_i32 m0, s47, 0x2000
	v_lshl_add_u64 v[222:223], s[48:49], 0, v[134:135]
	global_load_lds_dwordx4 v[222:223], off
	s_mov_b32 m0, s19
	v_lshl_add_u64 v[222:223], s[24:25], 0, v[128:129]
	global_load_lds_dwordx4 v[222:223], off
	s_mov_b32 m0, s29
	s_nop 0
	global_load_lds_dwordx4 v[224:225], off
	s_waitcnt vmcnt(8) lgkmcnt(0)
	s_barrier
	v_mfma_f32_16x16x32_bf16 v[60:63], v[152:155], v[188:191], v[60:63]
	v_mfma_f32_16x16x32_bf16 v[56:59], v[160:163], v[188:191], v[56:59]
	v_mfma_f32_16x16x32_bf16 v[52:55], v[152:155], v[196:199], v[52:55]
	v_mfma_f32_16x16x32_bf16 v[44:47], v[160:163], v[196:199], v[44:47]
	v_mfma_f32_16x16x32_bf16 v[36:39], v[152:155], v[204:207], v[36:39]
	v_mfma_f32_16x16x32_bf16 v[28:31], v[160:163], v[204:207], v[28:31]
	v_mfma_f32_16x16x32_bf16 v[20:23], v[152:155], v[212:215], v[20:23]
	v_mfma_f32_16x16x32_bf16 v[12:15], v[160:163], v[212:215], v[12:15]
	v_mfma_f32_16x16x32_bf16 v[60:63], v[156:159], v[192:195], v[60:63]
	v_mfma_f32_16x16x32_bf16 v[56:59], v[164:167], v[192:195], v[56:59]
	v_mfma_f32_16x16x32_bf16 v[52:55], v[156:159], v[200:203], v[52:55]
	v_mfma_f32_16x16x32_bf16 v[44:47], v[164:167], v[200:203], v[44:47]
	v_mfma_f32_16x16x32_bf16 v[36:39], v[156:159], v[208:211], v[36:39]
	v_mfma_f32_16x16x32_bf16 v[28:31], v[164:167], v[208:211], v[28:31]
	v_mfma_f32_16x16x32_bf16 v[20:23], v[156:159], v[216:219], v[20:23]
	v_mfma_f32_16x16x32_bf16 v[12:15], v[164:167], v[216:219], v[12:15]
	v_mfma_f32_16x16x32_bf16 v[48:51], v[172:175], v[188:191], v[48:51]
	v_mfma_f32_16x16x32_bf16 v[40:43], v[180:183], v[188:191], v[40:43]
	v_mfma_f32_16x16x32_bf16 v[32:35], v[172:175], v[196:199], v[32:35]
	v_mfma_f32_16x16x32_bf16 v[24:27], v[180:183], v[196:199], v[24:27]
	v_mfma_f32_16x16x32_bf16 v[16:19], v[172:175], v[204:207], v[16:19]
	v_mfma_f32_16x16x32_bf16 v[8:11], v[180:183], v[204:207], v[8:11]
	v_mfma_f32_16x16x32_bf16 v[4:7], v[172:175], v[212:215], v[4:7]
	v_mfma_f32_16x16x32_bf16 v[0:3], v[180:183], v[212:215], v[0:3]
	v_mfma_f32_16x16x32_bf16 v[48:51], v[176:179], v[192:195], v[48:51]
	v_mfma_f32_16x16x32_bf16 v[40:43], v[184:187], v[192:195], v[40:43]
	v_mfma_f32_16x16x32_bf16 v[32:35], v[176:179], v[200:203], v[32:35]
	v_mfma_f32_16x16x32_bf16 v[24:27], v[184:187], v[200:203], v[24:27]
	v_mfma_f32_16x16x32_bf16 v[16:19], v[176:179], v[208:211], v[16:19]
	v_mfma_f32_16x16x32_bf16 v[8:11], v[184:187], v[208:211], v[8:11]
	v_mfma_f32_16x16x32_bf16 v[4:7], v[176:179], v[216:219], v[4:7]
	v_mfma_f32_16x16x32_bf16 v[0:3], v[184:187], v[216:219], v[0:3]
	s_barrier
.Lpeel457_mid:
	s_add_i32 s47, 0, 0x18000
	v_add_u32_e32 v144, s47, v146
	s_add_i32 s48, 0, 0x1c000
	ds_read_b128 v[152:155], v144
	ds_read_b128 v[156:159], v144 offset:1024
	ds_read_b128 v[160:163], v144 offset:2048
	ds_read_b128 v[164:167], v144 offset:3072
	v_add_u32_e32 v144, s48, v146
	ds_read_b128 v[172:175], v144
	ds_read_b128 v[176:179], v144 offset:1024
	ds_read_b128 v[180:183], v144 offset:2048
	ds_read_b128 v[184:187], v144 offset:3072
	s_add_u32 s24, s24, 0x40000
	s_addc_u32 s25, s25, 0
	s_mov_b32 m0, s30
	v_lshl_add_u64 v[226:227], s[24:25], 0, v[128:129]
	ds_read_b128 v[188:191], v150 offset:32768
	ds_read_b128 v[192:195], v150 offset:33792
	ds_read_b128 v[196:199], v150 offset:34816
	ds_read_b128 v[200:203], v150 offset:35840
	ds_read_b128 v[204:207], v150 offset:36864
	ds_read_b128 v[208:211], v150 offset:37888
	ds_read_b128 v[212:215], v150 offset:38912
	ds_read_b128 v[216:219], v150 offset:39936
	global_load_lds_dwordx4 v[226:227], off
	s_mov_b32 m0, s31
	v_lshl_add_u64 v[226:227], s[24:25], 0, v[132:133]
	global_load_lds_dwordx4 v[226:227], off
	s_waitcnt vmcnt(8) lgkmcnt(0)
	s_barrier
	v_mfma_f32_16x16x32_bf16 v[124:127], v[152:155], v[188:191], v[124:127]
	v_mfma_f32_16x16x32_bf16 v[120:123], v[160:163], v[188:191], v[120:123]
	v_mfma_f32_16x16x32_bf16 v[116:119], v[152:155], v[196:199], v[116:119]
	v_mfma_f32_16x16x32_bf16 v[108:111], v[160:163], v[196:199], v[108:111]
	v_mfma_f32_16x16x32_bf16 v[100:103], v[152:155], v[204:207], v[100:103]
	v_mfma_f32_16x16x32_bf16 v[92:95], v[160:163], v[204:207], v[92:95]
	v_mfma_f32_16x16x32_bf16 v[84:87], v[152:155], v[212:215], v[84:87]
	v_mfma_f32_16x16x32_bf16 v[76:79], v[160:163], v[212:215], v[76:79]
	v_mfma_f32_16x16x32_bf16 v[124:127], v[156:159], v[192:195], v[124:127]
	v_mfma_f32_16x16x32_bf16 v[120:123], v[164:167], v[192:195], v[120:123]
	v_mfma_f32_16x16x32_bf16 v[116:119], v[156:159], v[200:203], v[116:119]
	v_mfma_f32_16x16x32_bf16 v[108:111], v[164:167], v[200:203], v[108:111]
	v_mfma_f32_16x16x32_bf16 v[100:103], v[156:159], v[208:211], v[100:103]
	v_mfma_f32_16x16x32_bf16 v[92:95], v[164:167], v[208:211], v[92:95]
	v_mfma_f32_16x16x32_bf16 v[84:87], v[156:159], v[216:219], v[84:87]
	v_mfma_f32_16x16x32_bf16 v[76:79], v[164:167], v[216:219], v[76:79]
	v_mfma_f32_16x16x32_bf16 v[112:115], v[172:175], v[188:191], v[112:115]
	v_mfma_f32_16x16x32_bf16 v[104:107], v[180:183], v[188:191], v[104:107]
	v_mfma_f32_16x16x32_bf16 v[96:99], v[172:175], v[196:199], v[96:99]
	v_mfma_f32_16x16x32_bf16 v[88:91], v[180:183], v[196:199], v[88:91]
	v_mfma_f32_16x16x32_bf16 v[80:83], v[172:175], v[204:207], v[80:83]
	v_mfma_f32_16x16x32_bf16 v[72:75], v[180:183], v[204:207], v[72:75]
	v_mfma_f32_16x16x32_bf16 v[68:71], v[172:175], v[212:215], v[68:71]
	v_mfma_f32_16x16x32_bf16 v[64:67], v[180:183], v[212:215], v[64:67]
	v_mfma_f32_16x16x32_bf16 v[112:115], v[176:179], v[192:195], v[112:115]
	v_mfma_f32_16x16x32_bf16 v[104:107], v[184:187], v[192:195], v[104:107]
	v_mfma_f32_16x16x32_bf16 v[96:99], v[176:179], v[200:203], v[96:99]
	v_mfma_f32_16x16x32_bf16 v[88:91], v[184:187], v[200:203], v[88:91]
	v_mfma_f32_16x16x32_bf16 v[80:83], v[176:179], v[208:211], v[80:83]
	v_mfma_f32_16x16x32_bf16 v[72:75], v[184:187], v[208:211], v[72:75]
	v_mfma_f32_16x16x32_bf16 v[68:71], v[176:179], v[216:219], v[68:71]
	v_mfma_f32_16x16x32_bf16 v[64:67], v[184:187], v[216:219], v[64:67]
	s_barrier
	s_add_i32 s24, s47, s26
	v_lshl_add_u64 v[168:169], v[168:169], 0, s[6:7]
	s_mov_b32 m0, s24
	ds_read_b128 v[188:191], v150 offset:49152
	ds_read_b128 v[192:195], v150 offset:50176
	ds_read_b128 v[196:199], v150 offset:51200
	ds_read_b128 v[200:203], v150 offset:52224
	ds_read_b128 v[204:207], v150 offset:53248
	ds_read_b128 v[208:211], v150 offset:54272
	ds_read_b128 v[212:215], v150 offset:55296
	ds_read_b128 v[216:219], v150 offset:56320
	global_load_lds_dwordx4 v[168:169], off
	s_add_i32 m0, s24, 0x2000
	s_add_u32 s22, s22, 0x40080
	v_lshl_add_u64 v[168:169], v[220:221], 0, s[6:7]
	s_addc_u32 s23, s23, 0
	s_add_i32 s24, s48, s26
	global_load_lds_dwordx4 v[168:169], off
	s_mov_b32 m0, s24
	v_lshl_add_u64 v[168:169], s[22:23], 0, v[130:131]
	global_load_lds_dwordx4 v[168:169], off
	s_add_i32 m0, s24, 0x2000
	v_lshl_add_u64 v[168:169], s[22:23], 0, v[134:135]
	global_load_lds_dwordx4 v[168:169], off
	v_lshl_add_u64 v[168:169], v[222:223], 0, s[6:7]
	s_mov_b32 m0, s35
	s_nop 0
	global_load_lds_dwordx4 v[168:169], off
	v_lshl_add_u64 v[168:169], v[224:225], 0, s[6:7]
	s_mov_b32 m0, s36
	s_nop 0
	global_load_lds_dwordx4 v[168:169], off
	s_waitcnt vmcnt(8) lgkmcnt(0)
	s_barrier
	v_mfma_f32_16x16x32_bf16 v[60:63], v[152:155], v[188:191], v[60:63]
	v_mfma_f32_16x16x32_bf16 v[56:59], v[160:163], v[188:191], v[56:59]
	v_mfma_f32_16x16x32_bf16 v[52:55], v[152:155], v[196:199], v[52:55]
	v_mfma_f32_16x16x32_bf16 v[44:47], v[160:163], v[196:199], v[44:47]
	v_mfma_f32_16x16x32_bf16 v[36:39], v[152:155], v[204:207], v[36:39]
	v_mfma_f32_16x16x32_bf16 v[28:31], v[160:163], v[204:207], v[28:31]
	v_mfma_f32_16x16x32_bf16 v[20:23], v[152:155], v[212:215], v[20:23]
	v_mfma_f32_16x16x32_bf16 v[12:15], v[160:163], v[212:215], v[12:15]
	v_mfma_f32_16x16x32_bf16 v[60:63], v[156:159], v[192:195], v[60:63]
	v_mfma_f32_16x16x32_bf16 v[56:59], v[164:167], v[192:195], v[56:59]
	v_mfma_f32_16x16x32_bf16 v[52:55], v[156:159], v[200:203], v[52:55]
	v_mfma_f32_16x16x32_bf16 v[44:47], v[164:167], v[200:203], v[44:47]
	v_mfma_f32_16x16x32_bf16 v[36:39], v[156:159], v[208:211], v[36:39]
	v_mfma_f32_16x16x32_bf16 v[28:31], v[164:167], v[208:211], v[28:31]
	v_mfma_f32_16x16x32_bf16 v[20:23], v[156:159], v[216:219], v[20:23]
	v_mfma_f32_16x16x32_bf16 v[12:15], v[164:167], v[216:219], v[12:15]
	v_mfma_f32_16x16x32_bf16 v[48:51], v[172:175], v[188:191], v[48:51]
	v_mfma_f32_16x16x32_bf16 v[40:43], v[180:183], v[188:191], v[40:43]
	v_mfma_f32_16x16x32_bf16 v[32:35], v[172:175], v[196:199], v[32:35]
	v_mfma_f32_16x16x32_bf16 v[24:27], v[180:183], v[196:199], v[24:27]
	v_mfma_f32_16x16x32_bf16 v[16:19], v[172:175], v[204:207], v[16:19]
	v_mfma_f32_16x16x32_bf16 v[8:11], v[180:183], v[204:207], v[8:11]
	v_mfma_f32_16x16x32_bf16 v[4:7], v[172:175], v[212:215], v[4:7]
	v_mfma_f32_16x16x32_bf16 v[0:3], v[180:183], v[212:215], v[0:3]
	v_mfma_f32_16x16x32_bf16 v[48:51], v[176:179], v[192:195], v[48:51]
	v_mfma_f32_16x16x32_bf16 v[40:43], v[184:187], v[192:195], v[40:43]
	v_mfma_f32_16x16x32_bf16 v[32:35], v[176:179], v[200:203], v[32:35]
	v_mfma_f32_16x16x32_bf16 v[24:27], v[184:187], v[200:203], v[24:27]
	v_mfma_f32_16x16x32_bf16 v[16:19], v[176:179], v[208:211], v[16:19]
	v_mfma_f32_16x16x32_bf16 v[8:11], v[184:187], v[208:211], v[8:11]
	v_mfma_f32_16x16x32_bf16 v[4:7], v[176:179], v[216:219], v[4:7]
	v_mfma_f32_16x16x32_bf16 v[0:3], v[184:187], v[216:219], v[0:3]
	s_barrier
	s_add_i32 s46, s46, 2
	s_add_u32 s20, s20, 0x100
	s_addc_u32 s21, s21, 0
	s_add_u32 s44, s44, 0x100
	s_addc_u32 s45, s45, 0
	s_cmp_gt_u32 s46, 13
	s_cbranch_scc0 .LBB0_457
	s_and_b64 vcc, exec, s[8:9]
	s_cbranch_vccz .LBB0_460
	s_barrier

.LBB0_645:
	v_readlane_b32 s64, v246, 32
	v_readlane_b32 s65, v246, 33
	s_ashr_i32 s17, s16, 31
	v_readlane_b32 s66, v246, 34
	v_readlane_b32 s67, v246, 35
	s_mov_b64 s[60:61], s[64:65]
	s_andn2_b64 vcc, exec, s[34:35]
	s_lshl_b64 s[20:21], s[16:17], 19
	s_mov_b64 s[62:63], s[66:67]
	s_add_u32 s20, s62, s20
	s_addc_u32 s21, s63, s21
	s_and_b64 s[22:23], s[34:35], exec
	s_cselect_b32 s17, s21, s27
	s_cselect_b32 s50, s20, s26
	s_ashr_i32 s19, s18, 31
	s_lshl_b64 s[22:23], s[18:19], 19
	s_add_u32 s22, s38, s22
	s_addc_u32 s23, s40, s23
	v_cndmask_b32_e64 v0, 0, 1, s[34:35]
	s_and_b64 s[34:35], s[34:35], exec
	s_cselect_b32 s19, s23, s29
	s_cselect_b32 s51, s22, s28
	s_add_u32 s26, s26, 0x40080
	s_addc_u32 s27, s27, 0
	v_cmp_ne_u32_e64 s[0:1], 1, v0
	s_add_u32 s52, s28, 0x100
	s_addc_u32 s53, s29, 0
	s_mov_b32 s54, -2
	ds_read_b128 v[134:137], v156
	ds_read_b128 v[160:163], v156 offset:1024
	ds_read_b128 v[164:167], v156 offset:2048
	ds_read_b128 v[184:187], v156 offset:3072
	ds_read_b128 v[188:191], v157
	ds_read_b128 v[192:195], v157 offset:1024
	ds_read_b128 v[196:199], v157 offset:2048
	ds_read_b128 v[200:203], v157 offset:3072
	s_add_u32 s28, s26, 0xfffc0080
	s_addc_u32 s29, s27, -1
	s_cmp_eq_u32 s54, 12
	s_cselect_b32 s35, s17, s29
	s_cselect_b32 s34, s50, s28
	s_cselect_b32 s29, s19, s53
	s_cselect_b32 s28, s51, s52
	v_lshl_add_u64 v[138:139], s[26:27], 0, v[128:129]
	s_add_i32 m0, s25, 0xc000
	ds_read_b128 v[204:207], v158
	ds_read_b128 v[208:211], v158 offset:1024
	ds_read_b128 v[212:215], v158 offset:2048
	ds_read_b128 v[216:219], v158 offset:3072
	ds_read_b128 v[220:223], v158 offset:4096
	ds_read_b128 v[224:227], v158 offset:5120
	ds_read_b128 v[228:231], v158 offset:6144
	ds_read_b128 v[232:235], v158 offset:7168
	global_load_lds_dwordx4 v[138:139], off
	s_add_i32 m0, s25, 0xe000
	v_lshl_add_u64 v[138:139], s[26:27], 0, v[132:133]
	global_load_lds_dwordx4 v[138:139], off
	s_waitcnt vmcnt(8) lgkmcnt(0)
	s_barrier
	v_mfma_f32_16x16x32_bf16 v[124:127], v[134:137], v[204:207], 0
	v_mfma_f32_16x16x32_bf16 v[120:123], v[164:167], v[204:207], 0
	v_mfma_f32_16x16x32_bf16 v[108:111], v[134:137], v[212:215], 0
	v_mfma_f32_16x16x32_bf16 v[104:107], v[164:167], v[212:215], 0
	v_mfma_f32_16x16x32_bf16 v[92:95], v[134:137], v[220:223], 0
	v_mfma_f32_16x16x32_bf16 v[88:91], v[164:167], v[220:223], 0
	v_mfma_f32_16x16x32_bf16 v[76:79], v[134:137], v[228:231], 0
	v_mfma_f32_16x16x32_bf16 v[72:75], v[164:167], v[228:231], 0
	v_mfma_f32_16x16x32_bf16 v[124:127], v[160:163], v[208:211], v[124:127]
	v_mfma_f32_16x16x32_bf16 v[120:123], v[184:187], v[208:211], v[120:123]
	v_mfma_f32_16x16x32_bf16 v[108:111], v[160:163], v[216:219], v[108:111]
	v_mfma_f32_16x16x32_bf16 v[104:107], v[184:187], v[216:219], v[104:107]
	v_mfma_f32_16x16x32_bf16 v[92:95], v[160:163], v[224:227], v[92:95]
	v_mfma_f32_16x16x32_bf16 v[88:91], v[184:187], v[224:227], v[88:91]
	v_mfma_f32_16x16x32_bf16 v[76:79], v[160:163], v[232:235], v[76:79]
	v_mfma_f32_16x16x32_bf16 v[72:75], v[184:187], v[232:235], v[72:75]
	v_mfma_f32_16x16x32_bf16 v[116:119], v[188:191], v[204:207], 0
	v_mfma_f32_16x16x32_bf16 v[112:115], v[196:199], v[204:207], 0
	v_mfma_f32_16x16x32_bf16 v[100:103], v[188:191], v[212:215], 0
	v_mfma_f32_16x16x32_bf16 v[96:99], v[196:199], v[212:215], 0
	v_mfma_f32_16x16x32_bf16 v[84:87], v[188:191], v[220:223], 0
	v_mfma_f32_16x16x32_bf16 v[80:83], v[196:199], v[220:223], 0
	v_mfma_f32_16x16x32_bf16 v[68:71], v[188:191], v[228:231], 0
	v_mfma_f32_16x16x32_bf16 v[64:67], v[196:199], v[228:231], 0
	v_mfma_f32_16x16x32_bf16 v[116:119], v[192:195], v[208:211], v[116:119]
	v_mfma_f32_16x16x32_bf16 v[112:115], v[200:203], v[208:211], v[112:115]
	v_mfma_f32_16x16x32_bf16 v[100:103], v[192:195], v[216:219], v[100:103]
	v_mfma_f32_16x16x32_bf16 v[96:99], v[200:203], v[216:219], v[96:99]
	v_mfma_f32_16x16x32_bf16 v[84:87], v[192:195], v[224:227], v[84:87]
	v_mfma_f32_16x16x32_bf16 v[80:83], v[200:203], v[224:227], v[80:83]
	v_mfma_f32_16x16x32_bf16 v[68:71], v[192:195], v[232:235], v[68:71]
	v_mfma_f32_16x16x32_bf16 v[64:67], v[200:203], v[232:235], v[64:67]
	s_barrier
	s_add_i32 s55, s47, s41
	v_lshl_add_u64 v[138:139], s[28:29], 0, v[142:143]
	s_mov_b32 m0, s55
	ds_read_b128 v[204:207], v158 offset:16384
	ds_read_b128 v[208:211], v158 offset:17408
	ds_read_b128 v[212:215], v158 offset:18432
	ds_read_b128 v[216:219], v158 offset:19456
	ds_read_b128 v[220:223], v158 offset:20480
	ds_read_b128 v[224:227], v158 offset:21504
	ds_read_b128 v[228:231], v158 offset:22528
	ds_read_b128 v[232:235], v158 offset:23552
	global_load_lds_dwordx4 v[138:139], off
	s_add_i32 m0, s55, 0x2000
	s_add_u32 s56, s28, 0x40000
	v_lshl_add_u64 v[168:169], s[28:29], 0, v[146:147]
	s_addc_u32 s57, s29, 0
	s_add_i32 s55, s48, s41
	global_load_lds_dwordx4 v[168:169], off
	v_lshl_add_u64 v[236:237], s[56:57], 0, v[142:143]
	s_mov_b32 m0, s55
	v_lshl_add_u64 v[238:239], s[34:35], 0, v[144:145]
	global_load_lds_dwordx4 v[236:237], off
	s_add_i32 m0, s55, 0x2000
	v_lshl_add_u64 v[236:237], s[56:57], 0, v[146:147]
	global_load_lds_dwordx4 v[236:237], off
	s_mov_b32 m0, s25
	v_lshl_add_u64 v[236:237], s[34:35], 0, v[140:141]
	global_load_lds_dwordx4 v[236:237], off
	s_mov_b32 m0, s42
	s_nop 0
	global_load_lds_dwordx4 v[238:239], off
	s_waitcnt vmcnt(8) lgkmcnt(0)
	s_barrier
	v_mfma_f32_16x16x32_bf16 v[60:63], v[134:137], v[204:207], 0
	v_mfma_f32_16x16x32_bf16 v[56:59], v[164:167], v[204:207], 0
	v_mfma_f32_16x16x32_bf16 v[44:47], v[134:137], v[212:215], 0
	v_mfma_f32_16x16x32_bf16 v[40:43], v[164:167], v[212:215], 0
	v_mfma_f32_16x16x32_bf16 v[28:31], v[134:137], v[220:223], 0
	v_mfma_f32_16x16x32_bf16 v[24:27], v[164:167], v[220:223], 0
	v_mfma_f32_16x16x32_bf16 v[12:15], v[134:137], v[228:231], 0
	v_mfma_f32_16x16x32_bf16 v[8:11], v[164:167], v[228:231], 0
	v_mfma_f32_16x16x32_bf16 v[60:63], v[160:163], v[208:211], v[60:63]
	v_mfma_f32_16x16x32_bf16 v[56:59], v[184:187], v[208:211], v[56:59]
	v_mfma_f32_16x16x32_bf16 v[44:47], v[160:163], v[216:219], v[44:47]
	v_mfma_f32_16x16x32_bf16 v[40:43], v[184:187], v[216:219], v[40:43]
	v_mfma_f32_16x16x32_bf16 v[28:31], v[160:163], v[224:227], v[28:31]
	v_mfma_f32_16x16x32_bf16 v[24:27], v[184:187], v[224:227], v[24:27]
	v_mfma_f32_16x16x32_bf16 v[12:15], v[160:163], v[232:235], v[12:15]
	v_mfma_f32_16x16x32_bf16 v[8:11], v[184:187], v[232:235], v[8:11]
	v_mfma_f32_16x16x32_bf16 v[52:55], v[188:191], v[204:207], 0
	v_mfma_f32_16x16x32_bf16 v[48:51], v[196:199], v[204:207], 0
	v_mfma_f32_16x16x32_bf16 v[36:39], v[188:191], v[212:215], 0
	v_mfma_f32_16x16x32_bf16 v[32:35], v[196:199], v[212:215], 0
	v_mfma_f32_16x16x32_bf16 v[20:23], v[188:191], v[220:223], 0
	v_mfma_f32_16x16x32_bf16 v[16:19], v[196:199], v[220:223], 0
	v_mfma_f32_16x16x32_bf16 v[4:7], v[188:191], v[228:231], 0
	v_mfma_f32_16x16x32_bf16 v[0:3], v[196:199], v[228:231], 0
	v_mfma_f32_16x16x32_bf16 v[52:55], v[192:195], v[208:211], v[52:55]
	v_mfma_f32_16x16x32_bf16 v[48:51], v[200:203], v[208:211], v[48:51]
	v_mfma_f32_16x16x32_bf16 v[36:39], v[192:195], v[216:219], v[36:39]
	v_mfma_f32_16x16x32_bf16 v[32:35], v[200:203], v[216:219], v[32:35]
	v_mfma_f32_16x16x32_bf16 v[20:23], v[192:195], v[224:227], v[20:23]
	v_mfma_f32_16x16x32_bf16 v[16:19], v[200:203], v[224:227], v[16:19]
	v_mfma_f32_16x16x32_bf16 v[4:7], v[192:195], v[232:235], v[4:7]
	v_mfma_f32_16x16x32_bf16 v[0:3], v[200:203], v[232:235], v[0:3]
	s_barrier
	s_branch .Lpeel646_mid
.LBB0_646:
	ds_read_b128 v[134:137], v156
	ds_read_b128 v[160:163], v156 offset:1024
	ds_read_b128 v[164:167], v156 offset:2048
	ds_read_b128 v[184:187], v156 offset:3072
	ds_read_b128 v[188:191], v157
	ds_read_b128 v[192:195], v157 offset:1024
	ds_read_b128 v[196:199], v157 offset:2048
	ds_read_b128 v[200:203], v157 offset:3072
	s_add_u32 s28, s26, 0xfffc0080
	s_addc_u32 s29, s27, -1
	s_cmp_eq_u32 s54, 12
	s_cselect_b32 s35, s17, s29
	s_cselect_b32 s34, s50, s28
	s_cselect_b32 s29, s19, s53
	s_cselect_b32 s28, s51, s52
	v_lshl_add_u64 v[138:139], s[26:27], 0, v[128:129]
	s_add_i32 m0, s25, 0xc000
	ds_read_b128 v[204:207], v158
	ds_read_b128 v[208:211], v158 offset:1024
	ds_read_b128 v[212:215], v158 offset:2048
	ds_read_b128 v[216:219], v158 offset:3072
	ds_read_b128 v[220:223], v158 offset:4096
	ds_read_b128 v[224:227], v158 offset:5120
	ds_read_b128 v[228:231], v158 offset:6144
	ds_read_b128 v[232:235], v158 offset:7168
	global_load_lds_dwordx4 v[138:139], off
	s_add_i32 m0, s25, 0xe000
	v_lshl_add_u64 v[138:139], s[26:27], 0, v[132:133]
	global_load_lds_dwordx4 v[138:139], off
	s_waitcnt vmcnt(8) lgkmcnt(0)
	s_barrier
	v_mfma_f32_16x16x32_bf16 v[124:127], v[134:137], v[204:207], v[124:127]
	v_mfma_f32_16x16x32_bf16 v[120:123], v[164:167], v[204:207], v[120:123]
	v_mfma_f32_16x16x32_bf16 v[108:111], v[134:137], v[212:215], v[108:111]
	v_mfma_f32_16x16x32_bf16 v[104:107], v[164:167], v[212:215], v[104:107]
	v_mfma_f32_16x16x32_bf16 v[92:95], v[134:137], v[220:223], v[92:95]
	v_mfma_f32_16x16x32_bf16 v[88:91], v[164:167], v[220:223], v[88:91]
	v_mfma_f32_16x16x32_bf16 v[76:79], v[134:137], v[228:231], v[76:79]
	v_mfma_f32_16x16x32_bf16 v[72:75], v[164:167], v[228:231], v[72:75]
	v_mfma_f32_16x16x32_bf16 v[124:127], v[160:163], v[208:211], v[124:127]
	v_mfma_f32_16x16x32_bf16 v[120:123], v[184:187], v[208:211], v[120:123]
	v_mfma_f32_16x16x32_bf16 v[108:111], v[160:163], v[216:219], v[108:111]
	v_mfma_f32_16x16x32_bf16 v[104:107], v[184:187], v[216:219], v[104:107]
	v_mfma_f32_16x16x32_bf16 v[92:95], v[160:163], v[224:227], v[92:95]
	v_mfma_f32_16x16x32_bf16 v[88:91], v[184:187], v[224:227], v[88:91]
	v_mfma_f32_16x16x32_bf16 v[76:79], v[160:163], v[232:235], v[76:79]
	v_mfma_f32_16x16x32_bf16 v[72:75], v[184:187], v[232:235], v[72:75]
	v_mfma_f32_16x16x32_bf16 v[116:119], v[188:191], v[204:207], v[116:119]
	v_mfma_f32_16x16x32_bf16 v[112:115], v[196:199], v[204:207], v[112:115]
	v_mfma_f32_16x16x32_bf16 v[100:103], v[188:191], v[212:215], v[100:103]
	v_mfma_f32_16x16x32_bf16 v[96:99], v[196:199], v[212:215], v[96:99]
	v_mfma_f32_16x16x32_bf16 v[84:87], v[188:191], v[220:223], v[84:87]
	v_mfma_f32_16x16x32_bf16 v[80:83], v[196:199], v[220:223], v[80:83]
	v_mfma_f32_16x16x32_bf16 v[68:71], v[188:191], v[228:231], v[68:71]
	v_mfma_f32_16x16x32_bf16 v[64:67], v[196:199], v[228:231], v[64:67]
	v_mfma_f32_16x16x32_bf16 v[116:119], v[192:195], v[208:211], v[116:119]
	v_mfma_f32_16x16x32_bf16 v[112:115], v[200:203], v[208:211], v[112:115]
	v_mfma_f32_16x16x32_bf16 v[100:103], v[192:195], v[216:219], v[100:103]
	v_mfma_f32_16x16x32_bf16 v[96:99], v[200:203], v[216:219], v[96:99]
	v_mfma_f32_16x16x32_bf16 v[84:87], v[192:195], v[224:227], v[84:87]
	v_mfma_f32_16x16x32_bf16 v[80:83], v[200:203], v[224:227], v[80:83]
	v_mfma_f32_16x16x32_bf16 v[68:71], v[192:195], v[232:235], v[68:71]
	v_mfma_f32_16x16x32_bf16 v[64:67], v[200:203], v[232:235], v[64:67]
	s_barrier
	s_add_i32 s55, s47, s41
	v_lshl_add_u64 v[138:139], s[28:29], 0, v[142:143]
	s_mov_b32 m0, s55
	ds_read_b128 v[204:207], v158 offset:16384
	ds_read_b128 v[208:211], v158 offset:17408
	ds_read_b128 v[212:215], v158 offset:18432
	ds_read_b128 v[216:219], v158 offset:19456
	ds_read_b128 v[220:223], v158 offset:20480
	ds_read_b128 v[224:227], v158 offset:21504
	ds_read_b128 v[228:231], v158 offset:22528
	ds_read_b128 v[232:235], v158 offset:23552
	global_load_lds_dwordx4 v[138:139], off
	s_add_i32 m0, s55, 0x2000
	s_add_u32 s56, s28, 0x40000
	v_lshl_add_u64 v[168:169], s[28:29], 0, v[146:147]
	s_addc_u32 s57, s29, 0
	s_add_i32 s55, s48, s41
	global_load_lds_dwordx4 v[168:169], off
	v_lshl_add_u64 v[236:237], s[56:57], 0, v[142:143]
	s_mov_b32 m0, s55
	v_lshl_add_u64 v[238:239], s[34:35], 0, v[144:145]
	global_load_lds_dwordx4 v[236:237], off
	s_add_i32 m0, s55, 0x2000
	v_lshl_add_u64 v[236:237], s[56:57], 0, v[146:147]
	global_load_lds_dwordx4 v[236:237], off
	s_mov_b32 m0, s25
	v_lshl_add_u64 v[236:237], s[34:35], 0, v[140:141]
	global_load_lds_dwordx4 v[236:237], off
	s_mov_b32 m0, s42
	s_nop 0
	global_load_lds_dwordx4 v[238:239], off
	s_waitcnt vmcnt(8) lgkmcnt(0)
	s_barrier
	v_mfma_f32_16x16x32_bf16 v[60:63], v[134:137], v[204:207], v[60:63]
	v_mfma_f32_16x16x32_bf16 v[56:59], v[164:167], v[204:207], v[56:59]
	v_mfma_f32_16x16x32_bf16 v[44:47], v[134:137], v[212:215], v[44:47]
	v_mfma_f32_16x16x32_bf16 v[40:43], v[164:167], v[212:215], v[40:43]
	v_mfma_f32_16x16x32_bf16 v[28:31], v[134:137], v[220:223], v[28:31]
	v_mfma_f32_16x16x32_bf16 v[24:27], v[164:167], v[220:223], v[24:27]
	v_mfma_f32_16x16x32_bf16 v[12:15], v[134:137], v[228:231], v[12:15]
	v_mfma_f32_16x16x32_bf16 v[8:11], v[164:167], v[228:231], v[8:11]
	v_mfma_f32_16x16x32_bf16 v[60:63], v[160:163], v[208:211], v[60:63]
	v_mfma_f32_16x16x32_bf16 v[56:59], v[184:187], v[208:211], v[56:59]
	v_mfma_f32_16x16x32_bf16 v[44:47], v[160:163], v[216:219], v[44:47]
	v_mfma_f32_16x16x32_bf16 v[40:43], v[184:187], v[216:219], v[40:43]
	v_mfma_f32_16x16x32_bf16 v[28:31], v[160:163], v[224:227], v[28:31]
	v_mfma_f32_16x16x32_bf16 v[24:27], v[184:187], v[224:227], v[24:27]
	v_mfma_f32_16x16x32_bf16 v[12:15], v[160:163], v[232:235], v[12:15]
	v_mfma_f32_16x16x32_bf16 v[8:11], v[184:187], v[232:235], v[8:11]
	v_mfma_f32_16x16x32_bf16 v[52:55], v[188:191], v[204:207], v[52:55]
	v_mfma_f32_16x16x32_bf16 v[48:51], v[196:199], v[204:207], v[48:51]
	v_mfma_f32_16x16x32_bf16 v[36:39], v[188:191], v[212:215], v[36:39]
	v_mfma_f32_16x16x32_bf16 v[32:35], v[196:199], v[212:215], v[32:35]
	v_mfma_f32_16x16x32_bf16 v[20:23], v[188:191], v[220:223], v[20:23]
	v_mfma_f32_16x16x32_bf16 v[16:19], v[196:199], v[220:223], v[16:19]
	v_mfma_f32_16x16x32_bf16 v[4:7], v[188:191], v[228:231], v[4:7]
	v_mfma_f32_16x16x32_bf16 v[0:3], v[196:199], v[228:231], v[0:3]
	v_mfma_f32_16x16x32_bf16 v[52:55], v[192:195], v[208:211], v[52:55]
	v_mfma_f32_16x16x32_bf16 v[48:51], v[200:203], v[208:211], v[48:51]
	v_mfma_f32_16x16x32_bf16 v[36:39], v[192:195], v[216:219], v[36:39]
	v_mfma_f32_16x16x32_bf16 v[32:35], v[200:203], v[216:219], v[32:35]
	v_mfma_f32_16x16x32_bf16 v[20:23], v[192:195], v[224:227], v[20:23]
	v_mfma_f32_16x16x32_bf16 v[16:19], v[200:203], v[224:227], v[16:19]
	v_mfma_f32_16x16x32_bf16 v[4:7], v[192:195], v[232:235], v[4:7]
	v_mfma_f32_16x16x32_bf16 v[0:3], v[200:203], v[232:235], v[0:3]
	s_barrier
.Lpeel646_mid:
	s_add_i32 s55, 0, 0x18000
	v_add_u32_e32 v130, s55, v154
	s_add_i32 s56, 0, 0x1c000
	ds_read_b128 v[134:137], v130
	ds_read_b128 v[160:163], v130 offset:1024
	ds_read_b128 v[164:167], v130 offset:2048
	ds_read_b128 v[184:187], v130 offset:3072
	v_add_u32_e32 v130, s56, v154
	ds_read_b128 v[188:191], v130
	ds_read_b128 v[192:195], v130 offset:1024
	ds_read_b128 v[196:199], v130 offset:2048
	ds_read_b128 v[200:203], v130 offset:3072
	s_add_u32 s34, s34, 0x40000
	s_addc_u32 s35, s35, 0
	s_mov_b32 m0, s43
	v_lshl_add_u64 v[240:241], s[34:35], 0, v[140:141]
	ds_read_b128 v[204:207], v158 offset:32768
	ds_read_b128 v[208:211], v158 offset:33792
	ds_read_b128 v[212:215], v158 offset:34816
	ds_read_b128 v[216:219], v158 offset:35840
	ds_read_b128 v[220:223], v158 offset:36864
	ds_read_b128 v[224:227], v158 offset:37888
	ds_read_b128 v[228:231], v158 offset:38912
	ds_read_b128 v[232:235], v158 offset:39936
	global_load_lds_dwordx4 v[240:241], off
	s_mov_b32 m0, s44
	v_lshl_add_u64 v[240:241], s[34:35], 0, v[144:145]
	global_load_lds_dwordx4 v[240:241], off
	s_waitcnt vmcnt(8) lgkmcnt(0)
	s_barrier
	v_mfma_f32_16x16x32_bf16 v[124:127], v[134:137], v[204:207], v[124:127]
	v_mfma_f32_16x16x32_bf16 v[120:123], v[164:167], v[204:207], v[120:123]
	v_mfma_f32_16x16x32_bf16 v[108:111], v[134:137], v[212:215], v[108:111]
	v_mfma_f32_16x16x32_bf16 v[104:107], v[164:167], v[212:215], v[104:107]
	v_mfma_f32_16x16x32_bf16 v[92:95], v[134:137], v[220:223], v[92:95]
	v_mfma_f32_16x16x32_bf16 v[88:91], v[164:167], v[220:223], v[88:91]
	v_mfma_f32_16x16x32_bf16 v[76:79], v[134:137], v[228:231], v[76:79]
	v_mfma_f32_16x16x32_bf16 v[72:75], v[164:167], v[228:231], v[72:75]
	v_mfma_f32_16x16x32_bf16 v[124:127], v[160:163], v[208:211], v[124:127]
	v_mfma_f32_16x16x32_bf16 v[120:123], v[184:187], v[208:211], v[120:123]
	v_mfma_f32_16x16x32_bf16 v[108:111], v[160:163], v[216:219], v[108:111]
	v_mfma_f32_16x16x32_bf16 v[104:107], v[184:187], v[216:219], v[104:107]
	v_mfma_f32_16x16x32_bf16 v[92:95], v[160:163], v[224:227], v[92:95]
	v_mfma_f32_16x16x32_bf16 v[88:91], v[184:187], v[224:227], v[88:91]
	v_mfma_f32_16x16x32_bf16 v[76:79], v[160:163], v[232:235], v[76:79]
	v_mfma_f32_16x16x32_bf16 v[72:75], v[184:187], v[232:235], v[72:75]
	v_mfma_f32_16x16x32_bf16 v[116:119], v[188:191], v[204:207], v[116:119]
	v_mfma_f32_16x16x32_bf16 v[112:115], v[196:199], v[204:207], v[112:115]
	v_mfma_f32_16x16x32_bf16 v[100:103], v[188:191], v[212:215], v[100:103]
	v_mfma_f32_16x16x32_bf16 v[96:99], v[196:199], v[212:215], v[96:99]
	v_mfma_f32_16x16x32_bf16 v[84:87], v[188:191], v[220:223], v[84:87]
	v_mfma_f32_16x16x32_bf16 v[80:83], v[196:199], v[220:223], v[80:83]
	v_mfma_f32_16x16x32_bf16 v[68:71], v[188:191], v[228:231], v[68:71]
	v_mfma_f32_16x16x32_bf16 v[64:67], v[196:199], v[228:231], v[64:67]
	v_mfma_f32_16x16x32_bf16 v[116:119], v[192:195], v[208:211], v[116:119]
	v_mfma_f32_16x16x32_bf16 v[112:115], v[200:203], v[208:211], v[112:115]
	v_mfma_f32_16x16x32_bf16 v[100:103], v[192:195], v[216:219], v[100:103]
	v_mfma_f32_16x16x32_bf16 v[96:99], v[200:203], v[216:219], v[96:99]
	v_mfma_f32_16x16x32_bf16 v[84:87], v[192:195], v[224:227], v[84:87]
	v_mfma_f32_16x16x32_bf16 v[80:83], v[200:203], v[224:227], v[80:83]
	v_mfma_f32_16x16x32_bf16 v[68:71], v[192:195], v[232:235], v[68:71]
	v_mfma_f32_16x16x32_bf16 v[64:67], v[200:203], v[232:235], v[64:67]
	s_barrier
	s_add_i32 s34, s55, s41
	v_lshl_add_u64 v[138:139], v[138:139], 0, s[12:13]
	s_mov_b32 m0, s34
	ds_read_b128 v[204:207], v158 offset:49152
	ds_read_b128 v[208:211], v158 offset:50176
	ds_read_b128 v[212:215], v158 offset:51200
	ds_read_b128 v[216:219], v158 offset:52224
	ds_read_b128 v[220:223], v158 offset:53248
	ds_read_b128 v[224:227], v158 offset:54272
	ds_read_b128 v[228:231], v158 offset:55296
	ds_read_b128 v[232:235], v158 offset:56320
	global_load_lds_dwordx4 v[138:139], off
	s_add_i32 m0, s34, 0x2000
	s_add_u32 s28, s28, 0x40080
	v_lshl_add_u64 v[138:139], v[168:169], 0, s[12:13]
	s_addc_u32 s29, s29, 0
	s_add_i32 s34, s56, s41
	global_load_lds_dwordx4 v[138:139], off
	s_mov_b32 m0, s34
	v_lshl_add_u64 v[138:139], s[28:29], 0, v[142:143]
	global_load_lds_dwordx4 v[138:139], off
	s_add_i32 m0, s34, 0x2000
	v_lshl_add_u64 v[138:139], s[28:29], 0, v[146:147]
	global_load_lds_dwordx4 v[138:139], off
	v_lshl_add_u64 v[138:139], v[236:237], 0, s[12:13]
	s_mov_b32 m0, s45
	s_nop 0
	global_load_lds_dwordx4 v[138:139], off
	v_lshl_add_u64 v[138:139], v[238:239], 0, s[12:13]
	s_mov_b32 m0, s46
	s_nop 0
	global_load_lds_dwordx4 v[138:139], off
	s_waitcnt vmcnt(8) lgkmcnt(0)
	s_barrier
	v_mfma_f32_16x16x32_bf16 v[60:63], v[134:137], v[204:207], v[60:63]
	v_mfma_f32_16x16x32_bf16 v[56:59], v[164:167], v[204:207], v[56:59]
	v_mfma_f32_16x16x32_bf16 v[44:47], v[134:137], v[212:215], v[44:47]
	v_mfma_f32_16x16x32_bf16 v[40:43], v[164:167], v[212:215], v[40:43]
	v_mfma_f32_16x16x32_bf16 v[28:31], v[134:137], v[220:223], v[28:31]
	v_mfma_f32_16x16x32_bf16 v[24:27], v[164:167], v[220:223], v[24:27]
	v_mfma_f32_16x16x32_bf16 v[12:15], v[134:137], v[228:231], v[12:15]
	v_mfma_f32_16x16x32_bf16 v[8:11], v[164:167], v[228:231], v[8:11]
	v_mfma_f32_16x16x32_bf16 v[60:63], v[160:163], v[208:211], v[60:63]
	v_mfma_f32_16x16x32_bf16 v[56:59], v[184:187], v[208:211], v[56:59]
	v_mfma_f32_16x16x32_bf16 v[44:47], v[160:163], v[216:219], v[44:47]
	v_mfma_f32_16x16x32_bf16 v[40:43], v[184:187], v[216:219], v[40:43]
	v_mfma_f32_16x16x32_bf16 v[28:31], v[160:163], v[224:227], v[28:31]
	v_mfma_f32_16x16x32_bf16 v[24:27], v[184:187], v[224:227], v[24:27]
	v_mfma_f32_16x16x32_bf16 v[12:15], v[160:163], v[232:235], v[12:15]
	v_mfma_f32_16x16x32_bf16 v[8:11], v[184:187], v[232:235], v[8:11]
	v_mfma_f32_16x16x32_bf16 v[52:55], v[188:191], v[204:207], v[52:55]
	v_mfma_f32_16x16x32_bf16 v[48:51], v[196:199], v[204:207], v[48:51]
	v_mfma_f32_16x16x32_bf16 v[36:39], v[188:191], v[212:215], v[36:39]
	v_mfma_f32_16x16x32_bf16 v[32:35], v[196:199], v[212:215], v[32:35]
	v_mfma_f32_16x16x32_bf16 v[20:23], v[188:191], v[220:223], v[20:23]
	v_mfma_f32_16x16x32_bf16 v[16:19], v[196:199], v[220:223], v[16:19]
	v_mfma_f32_16x16x32_bf16 v[4:7], v[188:191], v[228:231], v[4:7]
	v_mfma_f32_16x16x32_bf16 v[0:3], v[196:199], v[228:231], v[0:3]
	v_mfma_f32_16x16x32_bf16 v[52:55], v[192:195], v[208:211], v[52:55]
	v_mfma_f32_16x16x32_bf16 v[48:51], v[200:203], v[208:211], v[48:51]
	v_mfma_f32_16x16x32_bf16 v[36:39], v[192:195], v[216:219], v[36:39]
	v_mfma_f32_16x16x32_bf16 v[32:35], v[200:203], v[216:219], v[32:35]
	v_mfma_f32_16x16x32_bf16 v[20:23], v[192:195], v[224:227], v[20:23]
	v_mfma_f32_16x16x32_bf16 v[16:19], v[200:203], v[224:227], v[16:19]
	v_mfma_f32_16x16x32_bf16 v[4:7], v[192:195], v[232:235], v[4:7]
	v_mfma_f32_16x16x32_bf16 v[0:3], v[200:203], v[232:235], v[0:3]
	s_barrier
	s_add_i32 s54, s54, 2
	s_add_u32 s26, s26, 0x100
	s_addc_u32 s27, s27, 0
	s_add_u32 s52, s52, 0x100
	s_addc_u32 s53, s53, 0
	s_cmp_gt_u32 s54, 13
	s_cbranch_scc0 .LBB0_646
	s_and_b64 vcc, exec, s[14:15]
	s_cbranch_vccz .LBB0_649
	s_barrier

.LBB0_665:
	s_ashr_i32 s19, s18, 31
	s_lshl_b64 s[20:21], s[18:19], 18
	s_add_u32 s20, s30, s20
	s_addc_u32 s21, s31, s21
	s_and_b64 s[22:23], s[2:3], exec
	s_cselect_b32 s19, s21, s27
	s_cselect_b32 s50, s20, s26
	s_ashr_i32 s17, s16, 31
	s_lshl_b64 s[22:23], s[16:17], 18
	v_readlane_b32 s34, v246, 38
	v_readlane_b32 s35, v246, 39
	s_add_u32 s22, s34, s22
	s_addc_u32 s23, s35, s23
	s_and_b64 s[34:35], s[2:3], exec
	s_cselect_b32 s17, s23, s29
	s_cselect_b32 s51, s22, s28
	s_add_u32 s26, s26, 0x20080
	s_addc_u32 s27, s27, 0
	s_add_u32 s52, s28, 0x100
	s_addc_u32 s53, s29, 0
	s_mov_b32 s54, -2
	ds_read_b128 v[128:131], v187
	ds_read_b128 v[132:135], v187 offset:1024
	ds_read_b128 v[136:139], v187 offset:2048
	ds_read_b128 v[164:167], v187 offset:3072
	ds_read_b128 v[190:193], v188
	ds_read_b128 v[194:197], v188 offset:1024
	ds_read_b128 v[198:201], v188 offset:2048
	ds_read_b128 v[202:205], v188 offset:3072
	s_add_u32 s28, s26, 0xfffe0080
	s_addc_u32 s29, s27, -1
	s_cmp_eq_u32 s54, 4
	s_cselect_b32 s35, s19, s29
	s_cselect_b32 s34, s50, s28
	s_cselect_b32 s29, s17, s53
	s_cselect_b32 s28, s51, s52
	v_lshl_add_u64 v[168:169], s[26:27], 0, v[156:157]
	s_add_i32 m0, s25, 0xc000
	ds_read_b128 v[206:209], v189
	ds_read_b128 v[210:213], v189 offset:1024
	ds_read_b128 v[214:217], v189 offset:2048
	ds_read_b128 v[218:221], v189 offset:3072
	ds_read_b128 v[222:225], v189 offset:4096
	ds_read_b128 v[226:229], v189 offset:5120
	ds_read_b128 v[230:233], v189 offset:6144
	ds_read_b128 v[234:237], v189 offset:7168
	global_load_lds_dwordx4 v[168:169], off
	s_add_i32 m0, s25, 0xe000
	v_lshl_add_u64 v[168:169], s[26:27], 0, v[158:159]
	global_load_lds_dwordx4 v[168:169], off
	s_waitcnt vmcnt(8) lgkmcnt(0)
	s_barrier
	v_mfma_f32_16x16x32_bf16 v[124:127], v[128:131], v[206:209], 0
	v_mfma_f32_16x16x32_bf16 v[120:123], v[136:139], v[206:209], 0
	v_mfma_f32_16x16x32_bf16 v[112:115], v[128:131], v[214:217], 0
	v_mfma_f32_16x16x32_bf16 v[104:107], v[136:139], v[214:217], 0
	v_mfma_f32_16x16x32_bf16 v[92:95], v[128:131], v[222:225], 0
	v_mfma_f32_16x16x32_bf16 v[88:91], v[136:139], v[222:225], 0
	v_mfma_f32_16x16x32_bf16 v[76:79], v[128:131], v[230:233], 0
	v_mfma_f32_16x16x32_bf16 v[72:75], v[136:139], v[230:233], 0
	v_mfma_f32_16x16x32_bf16 v[124:127], v[132:135], v[210:213], v[124:127]
	v_mfma_f32_16x16x32_bf16 v[120:123], v[164:167], v[210:213], v[120:123]
	v_mfma_f32_16x16x32_bf16 v[112:115], v[132:135], v[218:221], v[112:115]
	v_mfma_f32_16x16x32_bf16 v[104:107], v[164:167], v[218:221], v[104:107]
	v_mfma_f32_16x16x32_bf16 v[92:95], v[132:135], v[226:229], v[92:95]
	v_mfma_f32_16x16x32_bf16 v[88:91], v[164:167], v[226:229], v[88:91]
	v_mfma_f32_16x16x32_bf16 v[76:79], v[132:135], v[234:237], v[76:79]
	v_mfma_f32_16x16x32_bf16 v[72:75], v[164:167], v[234:237], v[72:75]
	v_mfma_f32_16x16x32_bf16 v[116:119], v[190:193], v[206:209], 0
	v_mfma_f32_16x16x32_bf16 v[108:111], v[198:201], v[206:209], 0
	v_mfma_f32_16x16x32_bf16 v[100:103], v[190:193], v[214:217], 0
	v_mfma_f32_16x16x32_bf16 v[96:99], v[198:201], v[214:217], 0
	v_mfma_f32_16x16x32_bf16 v[84:87], v[190:193], v[222:225], 0
	v_mfma_f32_16x16x32_bf16 v[80:83], v[198:201], v[222:225], 0
	v_mfma_f32_16x16x32_bf16 v[68:71], v[190:193], v[230:233], 0
	v_mfma_f32_16x16x32_bf16 v[64:67], v[198:201], v[230:233], 0
	v_mfma_f32_16x16x32_bf16 v[116:119], v[194:197], v[210:213], v[116:119]
	v_mfma_f32_16x16x32_bf16 v[108:111], v[202:205], v[210:213], v[108:111]
	v_mfma_f32_16x16x32_bf16 v[100:103], v[194:197], v[218:221], v[100:103]
	v_mfma_f32_16x16x32_bf16 v[96:99], v[202:205], v[218:221], v[96:99]
	v_mfma_f32_16x16x32_bf16 v[84:87], v[194:197], v[226:229], v[84:87]
	v_mfma_f32_16x16x32_bf16 v[80:83], v[202:205], v[226:229], v[80:83]
	v_mfma_f32_16x16x32_bf16 v[68:71], v[194:197], v[234:237], v[68:71]
	v_mfma_f32_16x16x32_bf16 v[64:67], v[202:205], v[234:237], v[64:67]
	s_barrier
	s_add_i32 s55, s47, s40
	v_lshl_add_u64 v[168:169], s[28:29], 0, v[150:151]
	s_mov_b32 m0, s55
	ds_read_b128 v[206:209], v189 offset:16384
	ds_read_b128 v[210:213], v189 offset:17408
	ds_read_b128 v[214:217], v189 offset:18432
	ds_read_b128 v[218:221], v189 offset:19456
	ds_read_b128 v[222:225], v189 offset:20480
	ds_read_b128 v[226:229], v189 offset:21504
	ds_read_b128 v[230:233], v189 offset:22528
	ds_read_b128 v[234:237], v189 offset:23552
	global_load_lds_dwordx4 v[168:169], off
	s_add_i32 m0, s55, 0x2000
	s_add_u32 s56, s28, 0x20000
	v_lshl_add_u64 v[238:239], s[28:29], 0, v[154:155]
	s_addc_u32 s57, s29, 0
	s_add_i32 s55, s48, s40
	global_load_lds_dwordx4 v[238:239], off
	v_lshl_add_u64 v[240:241], s[56:57], 0, v[150:151]
	s_mov_b32 m0, s55
	v_lshl_add_u64 v[242:243], s[34:35], 0, v[152:153]
	global_load_lds_dwordx4 v[240:241], off
	s_add_i32 m0, s55, 0x2000
	v_lshl_add_u64 v[240:241], s[56:57], 0, v[154:155]
	global_load_lds_dwordx4 v[240:241], off
	s_mov_b32 m0, s25
	v_lshl_add_u64 v[240:241], s[34:35], 0, v[148:149]
	global_load_lds_dwordx4 v[240:241], off
	s_mov_b32 m0, s41
	s_nop 0
	global_load_lds_dwordx4 v[242:243], off
	s_waitcnt vmcnt(8) lgkmcnt(0)
	s_barrier
	v_mfma_f32_16x16x32_bf16 v[60:63], v[128:131], v[206:209], 0
	v_mfma_f32_16x16x32_bf16 v[56:59], v[136:139], v[206:209], 0
	v_mfma_f32_16x16x32_bf16 v[44:47], v[128:131], v[214:217], 0
	v_mfma_f32_16x16x32_bf16 v[40:43], v[136:139], v[214:217], 0
	v_mfma_f32_16x16x32_bf16 v[36:39], v[128:131], v[222:225], 0
	v_mfma_f32_16x16x32_bf16 v[32:35], v[136:139], v[222:225], 0
	v_mfma_f32_16x16x32_bf16 v[20:23], v[128:131], v[230:233], 0
	v_mfma_f32_16x16x32_bf16 v[16:19], v[136:139], v[230:233], 0
	v_mfma_f32_16x16x32_bf16 v[60:63], v[132:135], v[210:213], v[60:63]
	v_mfma_f32_16x16x32_bf16 v[56:59], v[164:167], v[210:213], v[56:59]
	v_mfma_f32_16x16x32_bf16 v[44:47], v[132:135], v[218:221], v[44:47]
	v_mfma_f32_16x16x32_bf16 v[40:43], v[164:167], v[218:221], v[40:43]
	v_mfma_f32_16x16x32_bf16 v[36:39], v[132:135], v[226:229], v[36:39]
	v_mfma_f32_16x16x32_bf16 v[32:35], v[164:167], v[226:229], v[32:35]
	v_mfma_f32_16x16x32_bf16 v[20:23], v[132:135], v[234:237], v[20:23]
	v_mfma_f32_16x16x32_bf16 v[16:19], v[164:167], v[234:237], v[16:19]
	v_mfma_f32_16x16x32_bf16 v[52:55], v[190:193], v[206:209], 0
	v_mfma_f32_16x16x32_bf16 v[48:51], v[198:201], v[206:209], 0
	v_mfma_f32_16x16x32_bf16 v[28:31], v[190:193], v[214:217], 0
	v_mfma_f32_16x16x32_bf16 v[24:27], v[198:201], v[214:217], 0
	v_mfma_f32_16x16x32_bf16 v[12:15], v[190:193], v[222:225], 0
	v_mfma_f32_16x16x32_bf16 v[8:11], v[198:201], v[222:225], 0
	v_mfma_f32_16x16x32_bf16 v[4:7], v[190:193], v[230:233], 0
	v_mfma_f32_16x16x32_bf16 v[0:3], v[198:201], v[230:233], 0
	v_mfma_f32_16x16x32_bf16 v[52:55], v[194:197], v[210:213], v[52:55]
	v_mfma_f32_16x16x32_bf16 v[48:51], v[202:205], v[210:213], v[48:51]
	v_mfma_f32_16x16x32_bf16 v[28:31], v[194:197], v[218:221], v[28:31]
	v_mfma_f32_16x16x32_bf16 v[24:27], v[202:205], v[218:221], v[24:27]
	v_mfma_f32_16x16x32_bf16 v[12:15], v[194:197], v[226:229], v[12:15]
	v_mfma_f32_16x16x32_bf16 v[8:11], v[202:205], v[226:229], v[8:11]
	v_mfma_f32_16x16x32_bf16 v[4:7], v[194:197], v[234:237], v[4:7]
	v_mfma_f32_16x16x32_bf16 v[0:3], v[202:205], v[234:237], v[0:3]
	s_barrier
	s_branch .Lpeel666_mid
.LBB0_666:
	ds_read_b128 v[128:131], v187
	ds_read_b128 v[132:135], v187 offset:1024
	ds_read_b128 v[136:139], v187 offset:2048
	ds_read_b128 v[164:167], v187 offset:3072
	ds_read_b128 v[190:193], v188
	ds_read_b128 v[194:197], v188 offset:1024
	ds_read_b128 v[198:201], v188 offset:2048
	ds_read_b128 v[202:205], v188 offset:3072
	s_add_u32 s28, s26, 0xfffe0080
	s_addc_u32 s29, s27, -1
	s_cmp_eq_u32 s54, 4
	s_cselect_b32 s35, s19, s29
	s_cselect_b32 s34, s50, s28
	s_cselect_b32 s29, s17, s53
	s_cselect_b32 s28, s51, s52
	v_lshl_add_u64 v[168:169], s[26:27], 0, v[156:157]
	s_add_i32 m0, s25, 0xc000
	ds_read_b128 v[206:209], v189
	ds_read_b128 v[210:213], v189 offset:1024
	ds_read_b128 v[214:217], v189 offset:2048
	ds_read_b128 v[218:221], v189 offset:3072
	ds_read_b128 v[222:225], v189 offset:4096
	ds_read_b128 v[226:229], v189 offset:5120
	ds_read_b128 v[230:233], v189 offset:6144
	ds_read_b128 v[234:237], v189 offset:7168
	global_load_lds_dwordx4 v[168:169], off
	s_add_i32 m0, s25, 0xe000
	v_lshl_add_u64 v[168:169], s[26:27], 0, v[158:159]
	global_load_lds_dwordx4 v[168:169], off
	s_waitcnt vmcnt(8) lgkmcnt(0)
	s_barrier
	v_mfma_f32_16x16x32_bf16 v[124:127], v[128:131], v[206:209], v[124:127]
	v_mfma_f32_16x16x32_bf16 v[120:123], v[136:139], v[206:209], v[120:123]
	v_mfma_f32_16x16x32_bf16 v[112:115], v[128:131], v[214:217], v[112:115]
	v_mfma_f32_16x16x32_bf16 v[104:107], v[136:139], v[214:217], v[104:107]
	v_mfma_f32_16x16x32_bf16 v[92:95], v[128:131], v[222:225], v[92:95]
	v_mfma_f32_16x16x32_bf16 v[88:91], v[136:139], v[222:225], v[88:91]
	v_mfma_f32_16x16x32_bf16 v[76:79], v[128:131], v[230:233], v[76:79]
	v_mfma_f32_16x16x32_bf16 v[72:75], v[136:139], v[230:233], v[72:75]
	v_mfma_f32_16x16x32_bf16 v[124:127], v[132:135], v[210:213], v[124:127]
	v_mfma_f32_16x16x32_bf16 v[120:123], v[164:167], v[210:213], v[120:123]
	v_mfma_f32_16x16x32_bf16 v[112:115], v[132:135], v[218:221], v[112:115]
	v_mfma_f32_16x16x32_bf16 v[104:107], v[164:167], v[218:221], v[104:107]
	v_mfma_f32_16x16x32_bf16 v[92:95], v[132:135], v[226:229], v[92:95]
	v_mfma_f32_16x16x32_bf16 v[88:91], v[164:167], v[226:229], v[88:91]
	v_mfma_f32_16x16x32_bf16 v[76:79], v[132:135], v[234:237], v[76:79]
	v_mfma_f32_16x16x32_bf16 v[72:75], v[164:167], v[234:237], v[72:75]
	v_mfma_f32_16x16x32_bf16 v[116:119], v[190:193], v[206:209], v[116:119]
	v_mfma_f32_16x16x32_bf16 v[108:111], v[198:201], v[206:209], v[108:111]
	v_mfma_f32_16x16x32_bf16 v[100:103], v[190:193], v[214:217], v[100:103]
	v_mfma_f32_16x16x32_bf16 v[96:99], v[198:201], v[214:217], v[96:99]
	v_mfma_f32_16x16x32_bf16 v[84:87], v[190:193], v[222:225], v[84:87]
	v_mfma_f32_16x16x32_bf16 v[80:83], v[198:201], v[222:225], v[80:83]
	v_mfma_f32_16x16x32_bf16 v[68:71], v[190:193], v[230:233], v[68:71]
	v_mfma_f32_16x16x32_bf16 v[64:67], v[198:201], v[230:233], v[64:67]
	v_mfma_f32_16x16x32_bf16 v[116:119], v[194:197], v[210:213], v[116:119]
	v_mfma_f32_16x16x32_bf16 v[108:111], v[202:205], v[210:213], v[108:111]
	v_mfma_f32_16x16x32_bf16 v[100:103], v[194:197], v[218:221], v[100:103]
	v_mfma_f32_16x16x32_bf16 v[96:99], v[202:205], v[218:221], v[96:99]
	v_mfma_f32_16x16x32_bf16 v[84:87], v[194:197], v[226:229], v[84:87]
	v_mfma_f32_16x16x32_bf16 v[80:83], v[202:205], v[226:229], v[80:83]
	v_mfma_f32_16x16x32_bf16 v[68:71], v[194:197], v[234:237], v[68:71]
	v_mfma_f32_16x16x32_bf16 v[64:67], v[202:205], v[234:237], v[64:67]
	s_barrier
	s_add_i32 s55, s47, s40
	v_lshl_add_u64 v[168:169], s[28:29], 0, v[150:151]
	s_mov_b32 m0, s55
	ds_read_b128 v[206:209], v189 offset:16384
	ds_read_b128 v[210:213], v189 offset:17408
	ds_read_b128 v[214:217], v189 offset:18432
	ds_read_b128 v[218:221], v189 offset:19456
	ds_read_b128 v[222:225], v189 offset:20480
	ds_read_b128 v[226:229], v189 offset:21504
	ds_read_b128 v[230:233], v189 offset:22528
	ds_read_b128 v[234:237], v189 offset:23552
	global_load_lds_dwordx4 v[168:169], off
	s_add_i32 m0, s55, 0x2000
	s_add_u32 s56, s28, 0x20000
	v_lshl_add_u64 v[238:239], s[28:29], 0, v[154:155]
	s_addc_u32 s57, s29, 0
	s_add_i32 s55, s48, s40
	global_load_lds_dwordx4 v[238:239], off
	v_lshl_add_u64 v[240:241], s[56:57], 0, v[150:151]
	s_mov_b32 m0, s55
	v_lshl_add_u64 v[242:243], s[34:35], 0, v[152:153]
	global_load_lds_dwordx4 v[240:241], off
	s_add_i32 m0, s55, 0x2000
	v_lshl_add_u64 v[240:241], s[56:57], 0, v[154:155]
	global_load_lds_dwordx4 v[240:241], off
	s_mov_b32 m0, s25
	v_lshl_add_u64 v[240:241], s[34:35], 0, v[148:149]
	global_load_lds_dwordx4 v[240:241], off
	s_mov_b32 m0, s41
	s_nop 0
	global_load_lds_dwordx4 v[242:243], off
	s_waitcnt vmcnt(8) lgkmcnt(0)
	s_barrier
	v_mfma_f32_16x16x32_bf16 v[60:63], v[128:131], v[206:209], v[60:63]
	v_mfma_f32_16x16x32_bf16 v[56:59], v[136:139], v[206:209], v[56:59]
	v_mfma_f32_16x16x32_bf16 v[44:47], v[128:131], v[214:217], v[44:47]
	v_mfma_f32_16x16x32_bf16 v[40:43], v[136:139], v[214:217], v[40:43]
	v_mfma_f32_16x16x32_bf16 v[36:39], v[128:131], v[222:225], v[36:39]
	v_mfma_f32_16x16x32_bf16 v[32:35], v[136:139], v[222:225], v[32:35]
	v_mfma_f32_16x16x32_bf16 v[20:23], v[128:131], v[230:233], v[20:23]
	v_mfma_f32_16x16x32_bf16 v[16:19], v[136:139], v[230:233], v[16:19]
	v_mfma_f32_16x16x32_bf16 v[60:63], v[132:135], v[210:213], v[60:63]
	v_mfma_f32_16x16x32_bf16 v[56:59], v[164:167], v[210:213], v[56:59]
	v_mfma_f32_16x16x32_bf16 v[44:47], v[132:135], v[218:221], v[44:47]
	v_mfma_f32_16x16x32_bf16 v[40:43], v[164:167], v[218:221], v[40:43]
	v_mfma_f32_16x16x32_bf16 v[36:39], v[132:135], v[226:229], v[36:39]
	v_mfma_f32_16x16x32_bf16 v[32:35], v[164:167], v[226:229], v[32:35]
	v_mfma_f32_16x16x32_bf16 v[20:23], v[132:135], v[234:237], v[20:23]
	v_mfma_f32_16x16x32_bf16 v[16:19], v[164:167], v[234:237], v[16:19]
	v_mfma_f32_16x16x32_bf16 v[52:55], v[190:193], v[206:209], v[52:55]
	v_mfma_f32_16x16x32_bf16 v[48:51], v[198:201], v[206:209], v[48:51]
	v_mfma_f32_16x16x32_bf16 v[28:31], v[190:193], v[214:217], v[28:31]
	v_mfma_f32_16x16x32_bf16 v[24:27], v[198:201], v[214:217], v[24:27]
	v_mfma_f32_16x16x32_bf16 v[12:15], v[190:193], v[222:225], v[12:15]
	v_mfma_f32_16x16x32_bf16 v[8:11], v[198:201], v[222:225], v[8:11]
	v_mfma_f32_16x16x32_bf16 v[4:7], v[190:193], v[230:233], v[4:7]
	v_mfma_f32_16x16x32_bf16 v[0:3], v[198:201], v[230:233], v[0:3]
	v_mfma_f32_16x16x32_bf16 v[52:55], v[194:197], v[210:213], v[52:55]
	v_mfma_f32_16x16x32_bf16 v[48:51], v[202:205], v[210:213], v[48:51]
	v_mfma_f32_16x16x32_bf16 v[28:31], v[194:197], v[218:221], v[28:31]
	v_mfma_f32_16x16x32_bf16 v[24:27], v[202:205], v[218:221], v[24:27]
	v_mfma_f32_16x16x32_bf16 v[12:15], v[194:197], v[226:229], v[12:15]
	v_mfma_f32_16x16x32_bf16 v[8:11], v[202:205], v[226:229], v[8:11]
	v_mfma_f32_16x16x32_bf16 v[4:7], v[194:197], v[234:237], v[4:7]
	v_mfma_f32_16x16x32_bf16 v[0:3], v[202:205], v[234:237], v[0:3]
	s_barrier
.Lpeel666_mid:
	s_add_i32 s55, 0, 0x18000
	s_add_i32 s56, 0, 0x1c000
	v_add_u32_e32 v164, s55, v185
	v_add_u32_e32 v202, s56, v185
	ds_read_b128 v[128:131], v164
	ds_read_b128 v[132:135], v164 offset:1024
	ds_read_b128 v[136:139], v164 offset:2048
	ds_read_b128 v[164:167], v164 offset:3072
	ds_read_b128 v[190:193], v202
	ds_read_b128 v[194:197], v202 offset:1024
	ds_read_b128 v[198:201], v202 offset:2048
	ds_read_b128 v[202:205], v202 offset:3072
	s_add_u32 s34, s34, 0x20000
	s_addc_u32 s35, s35, 0
	s_mov_b32 m0, s42
	v_lshl_add_u64 v[244:245], s[34:35], 0, v[148:149]
	ds_read_b128 v[206:209], v189 offset:32768
	ds_read_b128 v[210:213], v189 offset:33792
	ds_read_b128 v[214:217], v189 offset:34816
	ds_read_b128 v[218:221], v189 offset:35840
	ds_read_b128 v[222:225], v189 offset:36864
	ds_read_b128 v[226:229], v189 offset:37888
	ds_read_b128 v[230:233], v189 offset:38912
	ds_read_b128 v[234:237], v189 offset:39936
	global_load_lds_dwordx4 v[244:245], off
	s_mov_b32 m0, s43
	v_lshl_add_u64 v[244:245], s[34:35], 0, v[152:153]
	global_load_lds_dwordx4 v[244:245], off
	s_waitcnt vmcnt(8) lgkmcnt(0)
	s_barrier
	v_mfma_f32_16x16x32_bf16 v[124:127], v[128:131], v[206:209], v[124:127]
	v_mfma_f32_16x16x32_bf16 v[120:123], v[136:139], v[206:209], v[120:123]
	v_mfma_f32_16x16x32_bf16 v[112:115], v[128:131], v[214:217], v[112:115]
	v_mfma_f32_16x16x32_bf16 v[104:107], v[136:139], v[214:217], v[104:107]
	v_mfma_f32_16x16x32_bf16 v[92:95], v[128:131], v[222:225], v[92:95]
	v_mfma_f32_16x16x32_bf16 v[88:91], v[136:139], v[222:225], v[88:91]
	v_mfma_f32_16x16x32_bf16 v[76:79], v[128:131], v[230:233], v[76:79]
	v_mfma_f32_16x16x32_bf16 v[72:75], v[136:139], v[230:233], v[72:75]
	v_mfma_f32_16x16x32_bf16 v[124:127], v[132:135], v[210:213], v[124:127]
	v_mfma_f32_16x16x32_bf16 v[120:123], v[164:167], v[210:213], v[120:123]
	v_mfma_f32_16x16x32_bf16 v[112:115], v[132:135], v[218:221], v[112:115]
	v_mfma_f32_16x16x32_bf16 v[104:107], v[164:167], v[218:221], v[104:107]
	v_mfma_f32_16x16x32_bf16 v[92:95], v[132:135], v[226:229], v[92:95]
	v_mfma_f32_16x16x32_bf16 v[88:91], v[164:167], v[226:229], v[88:91]
	v_mfma_f32_16x16x32_bf16 v[76:79], v[132:135], v[234:237], v[76:79]
	v_mfma_f32_16x16x32_bf16 v[72:75], v[164:167], v[234:237], v[72:75]
	v_mfma_f32_16x16x32_bf16 v[116:119], v[190:193], v[206:209], v[116:119]
	v_mfma_f32_16x16x32_bf16 v[108:111], v[198:201], v[206:209], v[108:111]
	v_mfma_f32_16x16x32_bf16 v[100:103], v[190:193], v[214:217], v[100:103]
	v_mfma_f32_16x16x32_bf16 v[96:99], v[198:201], v[214:217], v[96:99]
	v_mfma_f32_16x16x32_bf16 v[84:87], v[190:193], v[222:225], v[84:87]
	v_mfma_f32_16x16x32_bf16 v[80:83], v[198:201], v[222:225], v[80:83]
	v_mfma_f32_16x16x32_bf16 v[68:71], v[190:193], v[230:233], v[68:71]
	v_mfma_f32_16x16x32_bf16 v[64:67], v[198:201], v[230:233], v[64:67]
	v_mfma_f32_16x16x32_bf16 v[116:119], v[194:197], v[210:213], v[116:119]
	v_mfma_f32_16x16x32_bf16 v[108:111], v[202:205], v[210:213], v[108:111]
	v_mfma_f32_16x16x32_bf16 v[100:103], v[194:197], v[218:221], v[100:103]
	v_mfma_f32_16x16x32_bf16 v[96:99], v[202:205], v[218:221], v[96:99]
	v_mfma_f32_16x16x32_bf16 v[84:87], v[194:197], v[226:229], v[84:87]
	v_mfma_f32_16x16x32_bf16 v[80:83], v[202:205], v[226:229], v[80:83]
	v_mfma_f32_16x16x32_bf16 v[68:71], v[194:197], v[234:237], v[68:71]
	v_mfma_f32_16x16x32_bf16 v[64:67], v[202:205], v[234:237], v[64:67]
	s_barrier
	s_add_i32 s34, s55, s40
	v_lshl_add_u64 v[168:169], v[168:169], 0, s[12:13]
	s_mov_b32 m0, s34
	ds_read_b128 v[206:209], v189 offset:49152
	ds_read_b128 v[210:213], v189 offset:50176
	ds_read_b128 v[214:217], v189 offset:51200
	ds_read_b128 v[218:221], v189 offset:52224
	ds_read_b128 v[222:225], v189 offset:53248
	ds_read_b128 v[226:229], v189 offset:54272
	ds_read_b128 v[230:233], v189 offset:55296
	ds_read_b128 v[234:237], v189 offset:56320
	global_load_lds_dwordx4 v[168:169], off
	s_add_i32 m0, s34, 0x2000
	s_add_u32 s28, s28, 0x20080
	v_lshl_add_u64 v[168:169], v[238:239], 0, s[12:13]
	s_addc_u32 s29, s29, 0
	s_add_i32 s34, s56, s40
	global_load_lds_dwordx4 v[168:169], off
	s_mov_b32 m0, s34
	v_lshl_add_u64 v[168:169], s[28:29], 0, v[150:151]
	global_load_lds_dwordx4 v[168:169], off
	s_add_i32 m0, s34, 0x2000
	v_lshl_add_u64 v[168:169], s[28:29], 0, v[154:155]
	global_load_lds_dwordx4 v[168:169], off
	v_lshl_add_u64 v[168:169], v[240:241], 0, s[12:13]
	s_mov_b32 m0, s45
	s_nop 0
	global_load_lds_dwordx4 v[168:169], off
	v_lshl_add_u64 v[168:169], v[242:243], 0, s[12:13]
	s_mov_b32 m0, s46
	s_nop 0
	global_load_lds_dwordx4 v[168:169], off
	s_waitcnt vmcnt(8) lgkmcnt(0)
	s_barrier
	v_mfma_f32_16x16x32_bf16 v[60:63], v[128:131], v[206:209], v[60:63]
	v_mfma_f32_16x16x32_bf16 v[56:59], v[136:139], v[206:209], v[56:59]
	v_mfma_f32_16x16x32_bf16 v[44:47], v[128:131], v[214:217], v[44:47]
	v_mfma_f32_16x16x32_bf16 v[40:43], v[136:139], v[214:217], v[40:43]
	v_mfma_f32_16x16x32_bf16 v[36:39], v[128:131], v[222:225], v[36:39]
	v_mfma_f32_16x16x32_bf16 v[32:35], v[136:139], v[222:225], v[32:35]
	v_mfma_f32_16x16x32_bf16 v[20:23], v[128:131], v[230:233], v[20:23]
	v_mfma_f32_16x16x32_bf16 v[16:19], v[136:139], v[230:233], v[16:19]
	v_mfma_f32_16x16x32_bf16 v[60:63], v[132:135], v[210:213], v[60:63]
	v_mfma_f32_16x16x32_bf16 v[56:59], v[164:167], v[210:213], v[56:59]
	v_mfma_f32_16x16x32_bf16 v[44:47], v[132:135], v[218:221], v[44:47]
	v_mfma_f32_16x16x32_bf16 v[40:43], v[164:167], v[218:221], v[40:43]
	v_mfma_f32_16x16x32_bf16 v[36:39], v[132:135], v[226:229], v[36:39]
	v_mfma_f32_16x16x32_bf16 v[32:35], v[164:167], v[226:229], v[32:35]
	v_mfma_f32_16x16x32_bf16 v[20:23], v[132:135], v[234:237], v[20:23]
	v_mfma_f32_16x16x32_bf16 v[16:19], v[164:167], v[234:237], v[16:19]
	v_mfma_f32_16x16x32_bf16 v[52:55], v[190:193], v[206:209], v[52:55]
	v_mfma_f32_16x16x32_bf16 v[48:51], v[198:201], v[206:209], v[48:51]
	v_mfma_f32_16x16x32_bf16 v[28:31], v[190:193], v[214:217], v[28:31]
	v_mfma_f32_16x16x32_bf16 v[24:27], v[198:201], v[214:217], v[24:27]
	v_mfma_f32_16x16x32_bf16 v[12:15], v[190:193], v[222:225], v[12:15]
	v_mfma_f32_16x16x32_bf16 v[8:11], v[198:201], v[222:225], v[8:11]
	v_mfma_f32_16x16x32_bf16 v[4:7], v[190:193], v[230:233], v[4:7]
	v_mfma_f32_16x16x32_bf16 v[0:3], v[198:201], v[230:233], v[0:3]
	v_mfma_f32_16x16x32_bf16 v[52:55], v[194:197], v[210:213], v[52:55]
	v_mfma_f32_16x16x32_bf16 v[48:51], v[202:205], v[210:213], v[48:51]
	v_mfma_f32_16x16x32_bf16 v[28:31], v[194:197], v[218:221], v[28:31]
	v_mfma_f32_16x16x32_bf16 v[24:27], v[202:205], v[218:221], v[24:27]
	v_mfma_f32_16x16x32_bf16 v[12:15], v[194:197], v[226:229], v[12:15]
	v_mfma_f32_16x16x32_bf16 v[8:11], v[202:205], v[226:229], v[8:11]
	v_mfma_f32_16x16x32_bf16 v[4:7], v[194:197], v[234:237], v[4:7]
	v_mfma_f32_16x16x32_bf16 v[0:3], v[202:205], v[234:237], v[0:3]
	s_barrier
	s_add_i32 s54, s54, 2
	s_add_u32 s26, s26, 0x100
	s_addc_u32 s27, s27, 0
	s_add_u32 s52, s52, 0x100
	s_addc_u32 s53, s53, 0
	s_cmp_gt_u32 s54, 5
	s_cbranch_scc0 .LBB0_666
	s_and_b64 vcc, exec, s[14:15]
	s_cbranch_vccz .LBB0_669
	s_barrier

.LBB0_685:
	s_ashr_i32 s23, s22, 31
	s_lshl_b64 s[24:25], s[22:23], 19
	s_add_u32 s24, s72, s24
	s_addc_u32 s25, s73, s25
	s_and_b64 s[26:27], s[0:1], exec
	s_cselect_b32 s23, s25, s31
	s_cselect_b32 s49, s24, s30
	s_ashr_i32 s21, s20, 31
	s_lshl_b64 s[26:27], s[20:21], 19
	v_readlane_b32 s36, v246, 40
	v_readlane_b32 s37, v246, 41
	s_add_u32 s26, s36, s26
	s_addc_u32 s27, s37, s27
	s_and_b64 s[36:37], s[0:1], exec
	s_cselect_b32 s21, s27, s35
	s_cselect_b32 s50, s26, s34
	s_add_u32 s30, s30, 0x40080
	s_addc_u32 s31, s31, 0
	s_add_u32 s51, s34, 0x100
	s_addc_u32 s52, s35, 0
	s_mov_b32 s53, -2
	ds_read_b128 v[136:139], v153
	ds_read_b128 v[156:159], v153 offset:1024
	ds_read_b128 v[160:163], v153 offset:2048
	ds_read_b128 v[164:167], v153 offset:3072
	ds_read_b128 v[180:183], v154
	ds_read_b128 v[184:187], v154 offset:1024
	ds_read_b128 v[188:191], v154 offset:2048
	ds_read_b128 v[192:195], v154 offset:3072
	s_add_u32 s34, s30, 0xfffc0080
	s_addc_u32 s35, s31, -1
	s_cmp_eq_u32 s53, 12
	s_cselect_b32 s37, s23, s35
	s_cselect_b32 s36, s49, s34
	s_cselect_b32 s35, s21, s52
	s_cselect_b32 s34, s50, s51
	v_lshl_add_u64 v[148:149], s[30:31], 0, v[128:129]
	s_add_i32 m0, s29, 0xc000
	ds_read_b128 v[196:199], v155
	ds_read_b128 v[200:203], v155 offset:1024
	ds_read_b128 v[204:207], v155 offset:2048
	ds_read_b128 v[208:211], v155 offset:3072
	ds_read_b128 v[212:215], v155 offset:4096
	ds_read_b128 v[216:219], v155 offset:5120
	ds_read_b128 v[220:223], v155 offset:6144
	ds_read_b128 v[224:227], v155 offset:7168
	global_load_lds_dwordx4 v[148:149], off
	s_add_i32 m0, s29, 0xe000
	v_lshl_add_u64 v[148:149], s[30:31], 0, v[130:131]
	global_load_lds_dwordx4 v[148:149], off
	s_waitcnt vmcnt(8) lgkmcnt(0)
	s_barrier
	v_mfma_f32_16x16x32_bf16 v[124:127], v[136:139], v[196:199], 0
	v_mfma_f32_16x16x32_bf16 v[120:123], v[160:163], v[196:199], 0
	v_mfma_f32_16x16x32_bf16 v[108:111], v[136:139], v[204:207], 0
	v_mfma_f32_16x16x32_bf16 v[104:107], v[160:163], v[204:207], 0
	v_mfma_f32_16x16x32_bf16 v[92:95], v[136:139], v[212:215], 0
	v_mfma_f32_16x16x32_bf16 v[88:91], v[160:163], v[212:215], 0
	v_mfma_f32_16x16x32_bf16 v[76:79], v[136:139], v[220:223], 0
	v_mfma_f32_16x16x32_bf16 v[72:75], v[160:163], v[220:223], 0
	v_mfma_f32_16x16x32_bf16 v[124:127], v[156:159], v[200:203], v[124:127]
	v_mfma_f32_16x16x32_bf16 v[120:123], v[164:167], v[200:203], v[120:123]
	v_mfma_f32_16x16x32_bf16 v[108:111], v[156:159], v[208:211], v[108:111]
	v_mfma_f32_16x16x32_bf16 v[104:107], v[164:167], v[208:211], v[104:107]
	v_mfma_f32_16x16x32_bf16 v[92:95], v[156:159], v[216:219], v[92:95]
	v_mfma_f32_16x16x32_bf16 v[88:91], v[164:167], v[216:219], v[88:91]
	v_mfma_f32_16x16x32_bf16 v[76:79], v[156:159], v[224:227], v[76:79]
	v_mfma_f32_16x16x32_bf16 v[72:75], v[164:167], v[224:227], v[72:75]
	v_mfma_f32_16x16x32_bf16 v[116:119], v[180:183], v[196:199], 0
	v_mfma_f32_16x16x32_bf16 v[112:115], v[188:191], v[196:199], 0
	v_mfma_f32_16x16x32_bf16 v[100:103], v[180:183], v[204:207], 0
	v_mfma_f32_16x16x32_bf16 v[96:99], v[188:191], v[204:207], 0
	v_mfma_f32_16x16x32_bf16 v[84:87], v[180:183], v[212:215], 0
	v_mfma_f32_16x16x32_bf16 v[80:83], v[188:191], v[212:215], 0
	v_mfma_f32_16x16x32_bf16 v[68:71], v[180:183], v[220:223], 0
	v_mfma_f32_16x16x32_bf16 v[64:67], v[188:191], v[220:223], 0
	v_mfma_f32_16x16x32_bf16 v[116:119], v[184:187], v[200:203], v[116:119]
	v_mfma_f32_16x16x32_bf16 v[112:115], v[192:195], v[200:203], v[112:115]
	v_mfma_f32_16x16x32_bf16 v[100:103], v[184:187], v[208:211], v[100:103]
	v_mfma_f32_16x16x32_bf16 v[96:99], v[192:195], v[208:211], v[96:99]
	v_mfma_f32_16x16x32_bf16 v[84:87], v[184:187], v[216:219], v[84:87]
	v_mfma_f32_16x16x32_bf16 v[80:83], v[192:195], v[216:219], v[80:83]
	v_mfma_f32_16x16x32_bf16 v[68:71], v[184:187], v[224:227], v[68:71]
	v_mfma_f32_16x16x32_bf16 v[64:67], v[192:195], v[224:227], v[64:67]
	s_barrier
	s_add_i32 s54, s46, s40
	v_lshl_add_u64 v[148:149], s[34:35], 0, v[142:143]
	s_mov_b32 m0, s54
	ds_read_b128 v[196:199], v155 offset:16384
	ds_read_b128 v[200:203], v155 offset:17408
	ds_read_b128 v[204:207], v155 offset:18432
	ds_read_b128 v[208:211], v155 offset:19456
	ds_read_b128 v[212:215], v155 offset:20480
	ds_read_b128 v[216:219], v155 offset:21504
	ds_read_b128 v[220:223], v155 offset:22528
	ds_read_b128 v[224:227], v155 offset:23552
	global_load_lds_dwordx4 v[148:149], off
	s_add_i32 m0, s54, 0x2000
	s_add_u32 s54, s34, 0x40000
	v_lshl_add_u64 v[168:169], s[34:35], 0, v[146:147]
	s_addc_u32 s55, s35, 0
	s_add_i32 s56, s47, s40
	global_load_lds_dwordx4 v[168:169], off
	v_lshl_add_u64 v[228:229], s[54:55], 0, v[142:143]
	s_mov_b32 m0, s56
	v_lshl_add_u64 v[230:231], s[36:37], 0, v[144:145]
	global_load_lds_dwordx4 v[228:229], off
	s_add_i32 m0, s56, 0x2000
	v_lshl_add_u64 v[228:229], s[54:55], 0, v[146:147]
	global_load_lds_dwordx4 v[228:229], off
	s_mov_b32 m0, s29
	v_lshl_add_u64 v[228:229], s[36:37], 0, v[140:141]
	global_load_lds_dwordx4 v[228:229], off
	s_mov_b32 m0, s39
	s_nop 0
	global_load_lds_dwordx4 v[230:231], off
	s_waitcnt vmcnt(8) lgkmcnt(0)
	s_barrier
	v_mfma_f32_16x16x32_bf16 v[60:63], v[136:139], v[196:199], 0
	v_mfma_f32_16x16x32_bf16 v[56:59], v[160:163], v[196:199], 0
	v_mfma_f32_16x16x32_bf16 v[44:47], v[136:139], v[204:207], 0
	v_mfma_f32_16x16x32_bf16 v[40:43], v[160:163], v[204:207], 0
	v_mfma_f32_16x16x32_bf16 v[28:31], v[136:139], v[212:215], 0
	v_mfma_f32_16x16x32_bf16 v[24:27], v[160:163], v[212:215], 0
	v_mfma_f32_16x16x32_bf16 v[12:15], v[136:139], v[220:223], 0
	v_mfma_f32_16x16x32_bf16 v[8:11], v[160:163], v[220:223], 0
	v_mfma_f32_16x16x32_bf16 v[60:63], v[156:159], v[200:203], v[60:63]
	v_mfma_f32_16x16x32_bf16 v[56:59], v[164:167], v[200:203], v[56:59]
	v_mfma_f32_16x16x32_bf16 v[44:47], v[156:159], v[208:211], v[44:47]
	v_mfma_f32_16x16x32_bf16 v[40:43], v[164:167], v[208:211], v[40:43]
	v_mfma_f32_16x16x32_bf16 v[28:31], v[156:159], v[216:219], v[28:31]
	v_mfma_f32_16x16x32_bf16 v[24:27], v[164:167], v[216:219], v[24:27]
	v_mfma_f32_16x16x32_bf16 v[12:15], v[156:159], v[224:227], v[12:15]
	v_mfma_f32_16x16x32_bf16 v[8:11], v[164:167], v[224:227], v[8:11]
	v_mfma_f32_16x16x32_bf16 v[52:55], v[180:183], v[196:199], 0
	v_mfma_f32_16x16x32_bf16 v[48:51], v[188:191], v[196:199], 0
	v_mfma_f32_16x16x32_bf16 v[36:39], v[180:183], v[204:207], 0
	v_mfma_f32_16x16x32_bf16 v[32:35], v[188:191], v[204:207], 0
	v_mfma_f32_16x16x32_bf16 v[20:23], v[180:183], v[212:215], 0
	v_mfma_f32_16x16x32_bf16 v[16:19], v[188:191], v[212:215], 0
	v_mfma_f32_16x16x32_bf16 v[4:7], v[180:183], v[220:223], 0
	v_mfma_f32_16x16x32_bf16 v[0:3], v[188:191], v[220:223], 0
	v_mfma_f32_16x16x32_bf16 v[52:55], v[184:187], v[200:203], v[52:55]
	v_mfma_f32_16x16x32_bf16 v[48:51], v[192:195], v[200:203], v[48:51]
	v_mfma_f32_16x16x32_bf16 v[36:39], v[184:187], v[208:211], v[36:39]
	v_mfma_f32_16x16x32_bf16 v[32:35], v[192:195], v[208:211], v[32:35]
	v_mfma_f32_16x16x32_bf16 v[20:23], v[184:187], v[216:219], v[20:23]
	v_mfma_f32_16x16x32_bf16 v[16:19], v[192:195], v[216:219], v[16:19]
	v_mfma_f32_16x16x32_bf16 v[4:7], v[184:187], v[224:227], v[4:7]
	v_mfma_f32_16x16x32_bf16 v[0:3], v[192:195], v[224:227], v[0:3]
	s_barrier
	s_branch .Lpeel686_mid
.LBB0_686:
	ds_read_b128 v[136:139], v153
	ds_read_b128 v[156:159], v153 offset:1024
	ds_read_b128 v[160:163], v153 offset:2048
	ds_read_b128 v[164:167], v153 offset:3072
	ds_read_b128 v[180:183], v154
	ds_read_b128 v[184:187], v154 offset:1024
	ds_read_b128 v[188:191], v154 offset:2048
	ds_read_b128 v[192:195], v154 offset:3072
	s_add_u32 s34, s30, 0xfffc0080
	s_addc_u32 s35, s31, -1
	s_cmp_eq_u32 s53, 12
	s_cselect_b32 s37, s23, s35
	s_cselect_b32 s36, s49, s34
	s_cselect_b32 s35, s21, s52
	s_cselect_b32 s34, s50, s51
	v_lshl_add_u64 v[148:149], s[30:31], 0, v[128:129]
	s_add_i32 m0, s29, 0xc000
	ds_read_b128 v[196:199], v155
	ds_read_b128 v[200:203], v155 offset:1024
	ds_read_b128 v[204:207], v155 offset:2048
	ds_read_b128 v[208:211], v155 offset:3072
	ds_read_b128 v[212:215], v155 offset:4096
	ds_read_b128 v[216:219], v155 offset:5120
	ds_read_b128 v[220:223], v155 offset:6144
	ds_read_b128 v[224:227], v155 offset:7168
	global_load_lds_dwordx4 v[148:149], off
	s_add_i32 m0, s29, 0xe000
	v_lshl_add_u64 v[148:149], s[30:31], 0, v[130:131]
	global_load_lds_dwordx4 v[148:149], off
	s_waitcnt vmcnt(8) lgkmcnt(0)
	s_barrier
	v_mfma_f32_16x16x32_bf16 v[124:127], v[136:139], v[196:199], v[124:127]
	v_mfma_f32_16x16x32_bf16 v[120:123], v[160:163], v[196:199], v[120:123]
	v_mfma_f32_16x16x32_bf16 v[108:111], v[136:139], v[204:207], v[108:111]
	v_mfma_f32_16x16x32_bf16 v[104:107], v[160:163], v[204:207], v[104:107]
	v_mfma_f32_16x16x32_bf16 v[92:95], v[136:139], v[212:215], v[92:95]
	v_mfma_f32_16x16x32_bf16 v[88:91], v[160:163], v[212:215], v[88:91]
	v_mfma_f32_16x16x32_bf16 v[76:79], v[136:139], v[220:223], v[76:79]
	v_mfma_f32_16x16x32_bf16 v[72:75], v[160:163], v[220:223], v[72:75]
	v_mfma_f32_16x16x32_bf16 v[124:127], v[156:159], v[200:203], v[124:127]
	v_mfma_f32_16x16x32_bf16 v[120:123], v[164:167], v[200:203], v[120:123]
	v_mfma_f32_16x16x32_bf16 v[108:111], v[156:159], v[208:211], v[108:111]
	v_mfma_f32_16x16x32_bf16 v[104:107], v[164:167], v[208:211], v[104:107]
	v_mfma_f32_16x16x32_bf16 v[92:95], v[156:159], v[216:219], v[92:95]
	v_mfma_f32_16x16x32_bf16 v[88:91], v[164:167], v[216:219], v[88:91]
	v_mfma_f32_16x16x32_bf16 v[76:79], v[156:159], v[224:227], v[76:79]
	v_mfma_f32_16x16x32_bf16 v[72:75], v[164:167], v[224:227], v[72:75]
	v_mfma_f32_16x16x32_bf16 v[116:119], v[180:183], v[196:199], v[116:119]
	v_mfma_f32_16x16x32_bf16 v[112:115], v[188:191], v[196:199], v[112:115]
	v_mfma_f32_16x16x32_bf16 v[100:103], v[180:183], v[204:207], v[100:103]
	v_mfma_f32_16x16x32_bf16 v[96:99], v[188:191], v[204:207], v[96:99]
	v_mfma_f32_16x16x32_bf16 v[84:87], v[180:183], v[212:215], v[84:87]
	v_mfma_f32_16x16x32_bf16 v[80:83], v[188:191], v[212:215], v[80:83]
	v_mfma_f32_16x16x32_bf16 v[68:71], v[180:183], v[220:223], v[68:71]
	v_mfma_f32_16x16x32_bf16 v[64:67], v[188:191], v[220:223], v[64:67]
	v_mfma_f32_16x16x32_bf16 v[116:119], v[184:187], v[200:203], v[116:119]
	v_mfma_f32_16x16x32_bf16 v[112:115], v[192:195], v[200:203], v[112:115]
	v_mfma_f32_16x16x32_bf16 v[100:103], v[184:187], v[208:211], v[100:103]
	v_mfma_f32_16x16x32_bf16 v[96:99], v[192:195], v[208:211], v[96:99]
	v_mfma_f32_16x16x32_bf16 v[84:87], v[184:187], v[216:219], v[84:87]
	v_mfma_f32_16x16x32_bf16 v[80:83], v[192:195], v[216:219], v[80:83]
	v_mfma_f32_16x16x32_bf16 v[68:71], v[184:187], v[224:227], v[68:71]
	v_mfma_f32_16x16x32_bf16 v[64:67], v[192:195], v[224:227], v[64:67]
	s_barrier
	s_add_i32 s54, s46, s40
	v_lshl_add_u64 v[148:149], s[34:35], 0, v[142:143]
	s_mov_b32 m0, s54
	ds_read_b128 v[196:199], v155 offset:16384
	ds_read_b128 v[200:203], v155 offset:17408
	ds_read_b128 v[204:207], v155 offset:18432
	ds_read_b128 v[208:211], v155 offset:19456
	ds_read_b128 v[212:215], v155 offset:20480
	ds_read_b128 v[216:219], v155 offset:21504
	ds_read_b128 v[220:223], v155 offset:22528
	ds_read_b128 v[224:227], v155 offset:23552
	global_load_lds_dwordx4 v[148:149], off
	s_add_i32 m0, s54, 0x2000
	s_add_u32 s54, s34, 0x40000
	v_lshl_add_u64 v[168:169], s[34:35], 0, v[146:147]
	s_addc_u32 s55, s35, 0
	s_add_i32 s56, s47, s40
	global_load_lds_dwordx4 v[168:169], off
	v_lshl_add_u64 v[228:229], s[54:55], 0, v[142:143]
	s_mov_b32 m0, s56
	v_lshl_add_u64 v[230:231], s[36:37], 0, v[144:145]
	global_load_lds_dwordx4 v[228:229], off
	s_add_i32 m0, s56, 0x2000
	v_lshl_add_u64 v[228:229], s[54:55], 0, v[146:147]
	global_load_lds_dwordx4 v[228:229], off
	s_mov_b32 m0, s29
	v_lshl_add_u64 v[228:229], s[36:37], 0, v[140:141]
	global_load_lds_dwordx4 v[228:229], off
	s_mov_b32 m0, s39
	s_nop 0
	global_load_lds_dwordx4 v[230:231], off
	s_waitcnt vmcnt(8) lgkmcnt(0)
	s_barrier
	v_mfma_f32_16x16x32_bf16 v[60:63], v[136:139], v[196:199], v[60:63]
	v_mfma_f32_16x16x32_bf16 v[56:59], v[160:163], v[196:199], v[56:59]
	v_mfma_f32_16x16x32_bf16 v[44:47], v[136:139], v[204:207], v[44:47]
	v_mfma_f32_16x16x32_bf16 v[40:43], v[160:163], v[204:207], v[40:43]
	v_mfma_f32_16x16x32_bf16 v[28:31], v[136:139], v[212:215], v[28:31]
	v_mfma_f32_16x16x32_bf16 v[24:27], v[160:163], v[212:215], v[24:27]
	v_mfma_f32_16x16x32_bf16 v[12:15], v[136:139], v[220:223], v[12:15]
	v_mfma_f32_16x16x32_bf16 v[8:11], v[160:163], v[220:223], v[8:11]
	v_mfma_f32_16x16x32_bf16 v[60:63], v[156:159], v[200:203], v[60:63]
	v_mfma_f32_16x16x32_bf16 v[56:59], v[164:167], v[200:203], v[56:59]
	v_mfma_f32_16x16x32_bf16 v[44:47], v[156:159], v[208:211], v[44:47]
	v_mfma_f32_16x16x32_bf16 v[40:43], v[164:167], v[208:211], v[40:43]
	v_mfma_f32_16x16x32_bf16 v[28:31], v[156:159], v[216:219], v[28:31]
	v_mfma_f32_16x16x32_bf16 v[24:27], v[164:167], v[216:219], v[24:27]
	v_mfma_f32_16x16x32_bf16 v[12:15], v[156:159], v[224:227], v[12:15]
	v_mfma_f32_16x16x32_bf16 v[8:11], v[164:167], v[224:227], v[8:11]
	v_mfma_f32_16x16x32_bf16 v[52:55], v[180:183], v[196:199], v[52:55]
	v_mfma_f32_16x16x32_bf16 v[48:51], v[188:191], v[196:199], v[48:51]
	v_mfma_f32_16x16x32_bf16 v[36:39], v[180:183], v[204:207], v[36:39]
	v_mfma_f32_16x16x32_bf16 v[32:35], v[188:191], v[204:207], v[32:35]
	v_mfma_f32_16x16x32_bf16 v[20:23], v[180:183], v[212:215], v[20:23]
	v_mfma_f32_16x16x32_bf16 v[16:19], v[188:191], v[212:215], v[16:19]
	v_mfma_f32_16x16x32_bf16 v[4:7], v[180:183], v[220:223], v[4:7]
	v_mfma_f32_16x16x32_bf16 v[0:3], v[188:191], v[220:223], v[0:3]
	v_mfma_f32_16x16x32_bf16 v[52:55], v[184:187], v[200:203], v[52:55]
	v_mfma_f32_16x16x32_bf16 v[48:51], v[192:195], v[200:203], v[48:51]
	v_mfma_f32_16x16x32_bf16 v[36:39], v[184:187], v[208:211], v[36:39]
	v_mfma_f32_16x16x32_bf16 v[32:35], v[192:195], v[208:211], v[32:35]
	v_mfma_f32_16x16x32_bf16 v[20:23], v[184:187], v[216:219], v[20:23]
	v_mfma_f32_16x16x32_bf16 v[16:19], v[192:195], v[216:219], v[16:19]
	v_mfma_f32_16x16x32_bf16 v[4:7], v[184:187], v[224:227], v[4:7]
	v_mfma_f32_16x16x32_bf16 v[0:3], v[192:195], v[224:227], v[0:3]
	s_barrier
.Lpeel686_mid:
	s_add_i32 s54, 0, 0x18000
	s_add_i32 s55, 0, 0x1c000
	v_add_u32_e32 v164, s54, v151
	v_add_u32_e32 v179, s55, v151
	ds_read_b128 v[136:139], v164
	ds_read_b128 v[156:159], v164 offset:1024
	ds_read_b128 v[160:163], v164 offset:2048
	ds_read_b128 v[164:167], v164 offset:3072
	ds_read_b128 v[180:183], v179
	ds_read_b128 v[184:187], v179 offset:1024
	ds_read_b128 v[188:191], v179 offset:2048
	ds_read_b128 v[192:195], v179 offset:3072
	s_add_u32 s36, s36, 0x40000
	s_addc_u32 s37, s37, 0
	s_mov_b32 m0, s41
	v_lshl_add_u64 v[232:233], s[36:37], 0, v[140:141]
	ds_read_b128 v[196:199], v155 offset:32768
	ds_read_b128 v[200:203], v155 offset:33792
	ds_read_b128 v[204:207], v155 offset:34816
	ds_read_b128 v[208:211], v155 offset:35840
	ds_read_b128 v[212:215], v155 offset:36864
	ds_read_b128 v[216:219], v155 offset:37888
	ds_read_b128 v[220:223], v155 offset:38912
	ds_read_b128 v[224:227], v155 offset:39936
	global_load_lds_dwordx4 v[232:233], off
	s_mov_b32 m0, s42
	v_lshl_add_u64 v[232:233], s[36:37], 0, v[144:145]
	global_load_lds_dwordx4 v[232:233], off
	s_waitcnt vmcnt(8) lgkmcnt(0)
	s_barrier
	v_mfma_f32_16x16x32_bf16 v[124:127], v[136:139], v[196:199], v[124:127]
	v_mfma_f32_16x16x32_bf16 v[120:123], v[160:163], v[196:199], v[120:123]
	v_mfma_f32_16x16x32_bf16 v[108:111], v[136:139], v[204:207], v[108:111]
	v_mfma_f32_16x16x32_bf16 v[104:107], v[160:163], v[204:207], v[104:107]
	v_mfma_f32_16x16x32_bf16 v[92:95], v[136:139], v[212:215], v[92:95]
	v_mfma_f32_16x16x32_bf16 v[88:91], v[160:163], v[212:215], v[88:91]
	v_mfma_f32_16x16x32_bf16 v[76:79], v[136:139], v[220:223], v[76:79]
	v_mfma_f32_16x16x32_bf16 v[72:75], v[160:163], v[220:223], v[72:75]
	v_mfma_f32_16x16x32_bf16 v[124:127], v[156:159], v[200:203], v[124:127]
	v_mfma_f32_16x16x32_bf16 v[120:123], v[164:167], v[200:203], v[120:123]
	v_mfma_f32_16x16x32_bf16 v[108:111], v[156:159], v[208:211], v[108:111]
	v_mfma_f32_16x16x32_bf16 v[104:107], v[164:167], v[208:211], v[104:107]
	v_mfma_f32_16x16x32_bf16 v[92:95], v[156:159], v[216:219], v[92:95]
	v_mfma_f32_16x16x32_bf16 v[88:91], v[164:167], v[216:219], v[88:91]
	v_mfma_f32_16x16x32_bf16 v[76:79], v[156:159], v[224:227], v[76:79]
	v_mfma_f32_16x16x32_bf16 v[72:75], v[164:167], v[224:227], v[72:75]
	v_mfma_f32_16x16x32_bf16 v[116:119], v[180:183], v[196:199], v[116:119]
	v_mfma_f32_16x16x32_bf16 v[112:115], v[188:191], v[196:199], v[112:115]
	v_mfma_f32_16x16x32_bf16 v[100:103], v[180:183], v[204:207], v[100:103]
	v_mfma_f32_16x16x32_bf16 v[96:99], v[188:191], v[204:207], v[96:99]
	v_mfma_f32_16x16x32_bf16 v[84:87], v[180:183], v[212:215], v[84:87]
	v_mfma_f32_16x16x32_bf16 v[80:83], v[188:191], v[212:215], v[80:83]
	v_mfma_f32_16x16x32_bf16 v[68:71], v[180:183], v[220:223], v[68:71]
	v_mfma_f32_16x16x32_bf16 v[64:67], v[188:191], v[220:223], v[64:67]
	v_mfma_f32_16x16x32_bf16 v[116:119], v[184:187], v[200:203], v[116:119]
	v_mfma_f32_16x16x32_bf16 v[112:115], v[192:195], v[200:203], v[112:115]
	v_mfma_f32_16x16x32_bf16 v[100:103], v[184:187], v[208:211], v[100:103]
	v_mfma_f32_16x16x32_bf16 v[96:99], v[192:195], v[208:211], v[96:99]
	v_mfma_f32_16x16x32_bf16 v[84:87], v[184:187], v[216:219], v[84:87]
	v_mfma_f32_16x16x32_bf16 v[80:83], v[192:195], v[216:219], v[80:83]
	v_mfma_f32_16x16x32_bf16 v[68:71], v[184:187], v[224:227], v[68:71]
	v_mfma_f32_16x16x32_bf16 v[64:67], v[192:195], v[224:227], v[64:67]
	s_barrier
	s_add_i32 s36, s54, s40
	v_lshl_add_u64 v[148:149], v[148:149], 0, s[10:11]
	s_mov_b32 m0, s36
	ds_read_b128 v[196:199], v155 offset:49152
	ds_read_b128 v[200:203], v155 offset:50176
	ds_read_b128 v[204:207], v155 offset:51200
	ds_read_b128 v[208:211], v155 offset:52224
	ds_read_b128 v[212:215], v155 offset:53248
	ds_read_b128 v[216:219], v155 offset:54272
	ds_read_b128 v[220:223], v155 offset:55296
	ds_read_b128 v[224:227], v155 offset:56320
	global_load_lds_dwordx4 v[148:149], off
	s_add_i32 m0, s36, 0x2000
	s_add_u32 s34, s34, 0x40080
	v_lshl_add_u64 v[148:149], v[168:169], 0, s[10:11]
	s_addc_u32 s35, s35, 0
	s_add_i32 s36, s55, s40
	global_load_lds_dwordx4 v[148:149], off
	s_mov_b32 m0, s36
	v_lshl_add_u64 v[148:149], s[34:35], 0, v[142:143]
	global_load_lds_dwordx4 v[148:149], off
	s_add_i32 m0, s36, 0x2000
	v_lshl_add_u64 v[148:149], s[34:35], 0, v[146:147]
	global_load_lds_dwordx4 v[148:149], off
	v_lshl_add_u64 v[148:149], v[228:229], 0, s[10:11]
	s_mov_b32 m0, s44
	s_nop 0
	global_load_lds_dwordx4 v[148:149], off
	v_lshl_add_u64 v[148:149], v[230:231], 0, s[10:11]
	s_mov_b32 m0, s45
	s_nop 0
	global_load_lds_dwordx4 v[148:149], off
	s_waitcnt vmcnt(8) lgkmcnt(0)
	s_barrier
	v_mfma_f32_16x16x32_bf16 v[60:63], v[136:139], v[196:199], v[60:63]
	v_mfma_f32_16x16x32_bf16 v[56:59], v[160:163], v[196:199], v[56:59]
	v_mfma_f32_16x16x32_bf16 v[44:47], v[136:139], v[204:207], v[44:47]
	v_mfma_f32_16x16x32_bf16 v[40:43], v[160:163], v[204:207], v[40:43]
	v_mfma_f32_16x16x32_bf16 v[28:31], v[136:139], v[212:215], v[28:31]
	v_mfma_f32_16x16x32_bf16 v[24:27], v[160:163], v[212:215], v[24:27]
	v_mfma_f32_16x16x32_bf16 v[12:15], v[136:139], v[220:223], v[12:15]
	v_mfma_f32_16x16x32_bf16 v[8:11], v[160:163], v[220:223], v[8:11]
	v_mfma_f32_16x16x32_bf16 v[60:63], v[156:159], v[200:203], v[60:63]
	v_mfma_f32_16x16x32_bf16 v[56:59], v[164:167], v[200:203], v[56:59]
	v_mfma_f32_16x16x32_bf16 v[44:47], v[156:159], v[208:211], v[44:47]
	v_mfma_f32_16x16x32_bf16 v[40:43], v[164:167], v[208:211], v[40:43]
	v_mfma_f32_16x16x32_bf16 v[28:31], v[156:159], v[216:219], v[28:31]
	v_mfma_f32_16x16x32_bf16 v[24:27], v[164:167], v[216:219], v[24:27]
	v_mfma_f32_16x16x32_bf16 v[12:15], v[156:159], v[224:227], v[12:15]
	v_mfma_f32_16x16x32_bf16 v[8:11], v[164:167], v[224:227], v[8:11]
	v_mfma_f32_16x16x32_bf16 v[52:55], v[180:183], v[196:199], v[52:55]
	v_mfma_f32_16x16x32_bf16 v[48:51], v[188:191], v[196:199], v[48:51]
	v_mfma_f32_16x16x32_bf16 v[36:39], v[180:183], v[204:207], v[36:39]
	v_mfma_f32_16x16x32_bf16 v[32:35], v[188:191], v[204:207], v[32:35]
	v_mfma_f32_16x16x32_bf16 v[20:23], v[180:183], v[212:215], v[20:23]
	v_mfma_f32_16x16x32_bf16 v[16:19], v[188:191], v[212:215], v[16:19]
	v_mfma_f32_16x16x32_bf16 v[4:7], v[180:183], v[220:223], v[4:7]
	v_mfma_f32_16x16x32_bf16 v[0:3], v[188:191], v[220:223], v[0:3]
	v_mfma_f32_16x16x32_bf16 v[52:55], v[184:187], v[200:203], v[52:55]
	v_mfma_f32_16x16x32_bf16 v[48:51], v[192:195], v[200:203], v[48:51]
	v_mfma_f32_16x16x32_bf16 v[36:39], v[184:187], v[208:211], v[36:39]
	v_mfma_f32_16x16x32_bf16 v[32:35], v[192:195], v[208:211], v[32:35]
	v_mfma_f32_16x16x32_bf16 v[20:23], v[184:187], v[216:219], v[20:23]
	v_mfma_f32_16x16x32_bf16 v[16:19], v[192:195], v[216:219], v[16:19]
	v_mfma_f32_16x16x32_bf16 v[4:7], v[184:187], v[224:227], v[4:7]
	v_mfma_f32_16x16x32_bf16 v[0:3], v[192:195], v[224:227], v[0:3]
	s_barrier
	s_add_i32 s53, s53, 2
	s_add_u32 s30, s30, 0x100
	s_addc_u32 s31, s31, 0
	s_add_u32 s51, s51, 0x100
	s_addc_u32 s52, s52, 0
	s_cmp_gt_u32 s53, 13
	s_cbranch_scc0 .LBB0_686
	s_and_b64 vcc, exec, s[12:13]
	s_cbranch_vccz .LBB0_689
	s_barrier

.LBB0_758:
	ds_read_b128 v[140:143], v183
	ds_read_b128 v[144:147], v183 offset:1024
	ds_read_b128 v[148:151], v183 offset:2048
	ds_read_b128 v[152:155], v183 offset:3072
	ds_read_b128 v[156:159], v184
	ds_read_b128 v[160:163], v184 offset:1024
	ds_read_b128 v[164:167], v184 offset:2048
	ds_read_b128 v[186:189], v184 offset:3072
	s_add_u32 s36, s34, 0xfffc0080
	s_addc_u32 s37, s35, -1
	s_cmp_eq_u32 s60, 12
	s_cselect_b32 s39, s25, s37
	s_cselect_b32 s38, s54, s36
	s_cselect_b32 s37, s23, s57
	s_cselect_b32 s36, s55, s56
	v_lshl_add_u64 v[222:223], s[34:35], 0, v[132:133]
	s_add_i32 m0, s31, 0xc000
	ds_read_b128 v[190:193], v185
	ds_read_b128 v[194:197], v185 offset:1024
	ds_read_b128 v[198:201], v185 offset:2048
	ds_read_b128 v[202:205], v185 offset:3072
	ds_read_b128 v[206:209], v185 offset:4096
	ds_read_b128 v[210:213], v185 offset:5120
	ds_read_b128 v[214:217], v185 offset:6144
	ds_read_b128 v[218:221], v185 offset:7168
	global_load_lds_dwordx4 v[222:223], off
	s_add_i32 m0, s31, 0xe000
	v_lshl_add_u64 v[222:223], s[34:35], 0, v[134:135]
	global_load_lds_dwordx4 v[222:223], off
	s_waitcnt vmcnt(8) lgkmcnt(0)
	s_barrier
	v_mfma_f32_16x16x32_bf16 v[124:127], v[140:143], v[190:193], v[124:127]
	v_mfma_f32_16x16x32_bf16 v[120:123], v[148:151], v[190:193], v[120:123]
	v_mfma_f32_16x16x32_bf16 v[108:111], v[140:143], v[198:201], v[108:111]
	v_mfma_f32_16x16x32_bf16 v[104:107], v[148:151], v[198:201], v[104:107]
	v_mfma_f32_16x16x32_bf16 v[92:95], v[140:143], v[206:209], v[92:95]
	v_mfma_f32_16x16x32_bf16 v[88:91], v[148:151], v[206:209], v[88:91]
	v_mfma_f32_16x16x32_bf16 v[76:79], v[140:143], v[214:217], v[76:79]
	v_mfma_f32_16x16x32_bf16 v[72:75], v[148:151], v[214:217], v[72:75]
	v_mfma_f32_16x16x32_bf16 v[124:127], v[144:147], v[194:197], v[124:127]
	v_mfma_f32_16x16x32_bf16 v[120:123], v[152:155], v[194:197], v[120:123]
	v_mfma_f32_16x16x32_bf16 v[108:111], v[144:147], v[202:205], v[108:111]
	v_mfma_f32_16x16x32_bf16 v[104:107], v[152:155], v[202:205], v[104:107]
	v_mfma_f32_16x16x32_bf16 v[92:95], v[144:147], v[210:213], v[92:95]
	v_mfma_f32_16x16x32_bf16 v[88:91], v[152:155], v[210:213], v[88:91]
	v_mfma_f32_16x16x32_bf16 v[76:79], v[144:147], v[218:221], v[76:79]
	v_mfma_f32_16x16x32_bf16 v[72:75], v[152:155], v[218:221], v[72:75]
	v_mfma_f32_16x16x32_bf16 v[116:119], v[156:159], v[190:193], v[116:119]
	v_mfma_f32_16x16x32_bf16 v[112:115], v[164:167], v[190:193], v[112:115]
	v_mfma_f32_16x16x32_bf16 v[100:103], v[156:159], v[198:201], v[100:103]
	v_mfma_f32_16x16x32_bf16 v[96:99], v[164:167], v[198:201], v[96:99]
	v_mfma_f32_16x16x32_bf16 v[84:87], v[156:159], v[206:209], v[84:87]
	v_mfma_f32_16x16x32_bf16 v[80:83], v[164:167], v[206:209], v[80:83]
	v_mfma_f32_16x16x32_bf16 v[68:71], v[156:159], v[214:217], v[68:71]
	v_mfma_f32_16x16x32_bf16 v[64:67], v[164:167], v[214:217], v[64:67]
	v_mfma_f32_16x16x32_bf16 v[116:119], v[160:163], v[194:197], v[116:119]
	v_mfma_f32_16x16x32_bf16 v[112:115], v[186:189], v[194:197], v[112:115]
	v_mfma_f32_16x16x32_bf16 v[100:103], v[160:163], v[202:205], v[100:103]
	v_mfma_f32_16x16x32_bf16 v[96:99], v[186:189], v[202:205], v[96:99]
	v_mfma_f32_16x16x32_bf16 v[84:87], v[160:163], v[210:213], v[84:87]
	v_mfma_f32_16x16x32_bf16 v[80:83], v[186:189], v[210:213], v[80:83]
	v_mfma_f32_16x16x32_bf16 v[68:71], v[160:163], v[218:221], v[68:71]
	v_mfma_f32_16x16x32_bf16 v[64:67], v[186:189], v[218:221], v[64:67]
	s_barrier
	s_add_i32 s61, s51, s42
	v_lshl_add_u64 v[222:223], s[36:37], 0, v[128:129]
	s_mov_b32 m0, s61
	ds_read_b128 v[190:193], v185 offset:16384
	ds_read_b128 v[194:197], v185 offset:17408
	ds_read_b128 v[198:201], v185 offset:18432
	ds_read_b128 v[202:205], v185 offset:19456
	ds_read_b128 v[206:209], v185 offset:20480
	ds_read_b128 v[210:213], v185 offset:21504
	ds_read_b128 v[214:217], v185 offset:22528
	ds_read_b128 v[218:221], v185 offset:23552
	global_load_lds_dwordx4 v[222:223], off
	s_add_i32 m0, s61, 0x2000
	s_add_u32 s62, s36, 0x40000
	v_lshl_add_u64 v[224:225], s[36:37], 0, v[130:131]
	s_addc_u32 s63, s37, 0
	s_add_i32 s61, s52, s42
	global_load_lds_dwordx4 v[224:225], off
	v_lshl_add_u64 v[226:227], s[62:63], 0, v[128:129]
	s_mov_b32 m0, s61
	v_lshl_add_u64 v[228:229], s[38:39], 0, v[130:131]
	global_load_lds_dwordx4 v[226:227], off
	s_add_i32 m0, s61, 0x2000
	v_lshl_add_u64 v[226:227], s[62:63], 0, v[130:131]
	global_load_lds_dwordx4 v[226:227], off
	s_mov_b32 m0, s31
	v_lshl_add_u64 v[226:227], s[38:39], 0, v[128:129]
	global_load_lds_dwordx4 v[226:227], off
	s_mov_b32 m0, s43
	s_nop 0
	global_load_lds_dwordx4 v[228:229], off
	s_waitcnt vmcnt(8) lgkmcnt(0)
	s_barrier
	v_mfma_f32_16x16x32_bf16 v[60:63], v[140:143], v[190:193], v[60:63]
	v_mfma_f32_16x16x32_bf16 v[56:59], v[148:151], v[190:193], v[56:59]
	v_mfma_f32_16x16x32_bf16 v[44:47], v[140:143], v[198:201], v[44:47]
	v_mfma_f32_16x16x32_bf16 v[40:43], v[148:151], v[198:201], v[40:43]
	v_mfma_f32_16x16x32_bf16 v[28:31], v[140:143], v[206:209], v[28:31]
	v_mfma_f32_16x16x32_bf16 v[24:27], v[148:151], v[206:209], v[24:27]
	v_mfma_f32_16x16x32_bf16 v[12:15], v[140:143], v[214:217], v[12:15]
	v_mfma_f32_16x16x32_bf16 v[8:11], v[148:151], v[214:217], v[8:11]
	v_mfma_f32_16x16x32_bf16 v[60:63], v[144:147], v[194:197], v[60:63]
	v_mfma_f32_16x16x32_bf16 v[56:59], v[152:155], v[194:197], v[56:59]
	v_mfma_f32_16x16x32_bf16 v[44:47], v[144:147], v[202:205], v[44:47]
	v_mfma_f32_16x16x32_bf16 v[40:43], v[152:155], v[202:205], v[40:43]
	v_mfma_f32_16x16x32_bf16 v[28:31], v[144:147], v[210:213], v[28:31]
	v_mfma_f32_16x16x32_bf16 v[24:27], v[152:155], v[210:213], v[24:27]
	v_mfma_f32_16x16x32_bf16 v[12:15], v[144:147], v[218:221], v[12:15]
	v_mfma_f32_16x16x32_bf16 v[8:11], v[152:155], v[218:221], v[8:11]
	v_mfma_f32_16x16x32_bf16 v[52:55], v[156:159], v[190:193], v[52:55]
	v_mfma_f32_16x16x32_bf16 v[48:51], v[164:167], v[190:193], v[48:51]
	v_mfma_f32_16x16x32_bf16 v[36:39], v[156:159], v[198:201], v[36:39]
	v_mfma_f32_16x16x32_bf16 v[32:35], v[164:167], v[198:201], v[32:35]
	v_mfma_f32_16x16x32_bf16 v[20:23], v[156:159], v[206:209], v[20:23]
	v_mfma_f32_16x16x32_bf16 v[16:19], v[164:167], v[206:209], v[16:19]
	v_mfma_f32_16x16x32_bf16 v[4:7], v[156:159], v[214:217], v[4:7]
	v_mfma_f32_16x16x32_bf16 v[0:3], v[164:167], v[214:217], v[0:3]
	v_mfma_f32_16x16x32_bf16 v[52:55], v[160:163], v[194:197], v[52:55]
	v_mfma_f32_16x16x32_bf16 v[48:51], v[186:189], v[194:197], v[48:51]
	v_mfma_f32_16x16x32_bf16 v[36:39], v[160:163], v[202:205], v[36:39]
	v_mfma_f32_16x16x32_bf16 v[32:35], v[186:189], v[202:205], v[32:35]
	v_mfma_f32_16x16x32_bf16 v[20:23], v[160:163], v[210:213], v[20:23]
	v_mfma_f32_16x16x32_bf16 v[16:19], v[186:189], v[210:213], v[16:19]
	v_mfma_f32_16x16x32_bf16 v[4:7], v[160:163], v[218:221], v[4:7]
	v_mfma_f32_16x16x32_bf16 v[0:3], v[186:189], v[218:221], v[0:3]
	s_barrier
	s_add_i32 s61, 0, 0x18000
	s_add_i32 s62, 0, 0x1c000
	v_add_u32_e32 v152, s61, v181
	v_add_u32_e32 v186, s62, v181
	ds_read_b128 v[140:143], v152
	ds_read_b128 v[144:147], v152 offset:1024
	ds_read_b128 v[148:151], v152 offset:2048
	ds_read_b128 v[152:155], v152 offset:3072
	ds_read_b128 v[156:159], v186
	ds_read_b128 v[160:163], v186 offset:1024
	ds_read_b128 v[164:167], v186 offset:2048
	ds_read_b128 v[186:189], v186 offset:3072
	s_add_u32 s38, s38, 0x40000
	s_addc_u32 s39, s39, 0
	s_mov_b32 m0, s44
	v_lshl_add_u64 v[230:231], s[38:39], 0, v[128:129]
	ds_read_b128 v[190:193], v185 offset:32768
	ds_read_b128 v[194:197], v185 offset:33792
	ds_read_b128 v[198:201], v185 offset:34816
	ds_read_b128 v[202:205], v185 offset:35840
	ds_read_b128 v[206:209], v185 offset:36864
	ds_read_b128 v[210:213], v185 offset:37888
	ds_read_b128 v[214:217], v185 offset:38912
	ds_read_b128 v[218:221], v185 offset:39936
	global_load_lds_dwordx4 v[230:231], off
	s_mov_b32 m0, s45
	v_lshl_add_u64 v[230:231], s[38:39], 0, v[130:131]
	global_load_lds_dwordx4 v[230:231], off
	s_waitcnt vmcnt(8) lgkmcnt(0)
	s_barrier
	v_mfma_f32_16x16x32_bf16 v[124:127], v[140:143], v[190:193], v[124:127]
	v_mfma_f32_16x16x32_bf16 v[120:123], v[148:151], v[190:193], v[120:123]
	v_mfma_f32_16x16x32_bf16 v[108:111], v[140:143], v[198:201], v[108:111]
	v_mfma_f32_16x16x32_bf16 v[104:107], v[148:151], v[198:201], v[104:107]
	v_mfma_f32_16x16x32_bf16 v[92:95], v[140:143], v[206:209], v[92:95]
	v_mfma_f32_16x16x32_bf16 v[88:91], v[148:151], v[206:209], v[88:91]
	v_mfma_f32_16x16x32_bf16 v[76:79], v[140:143], v[214:217], v[76:79]
	v_mfma_f32_16x16x32_bf16 v[72:75], v[148:151], v[214:217], v[72:75]
	v_mfma_f32_16x16x32_bf16 v[124:127], v[144:147], v[194:197], v[124:127]
	v_mfma_f32_16x16x32_bf16 v[120:123], v[152:155], v[194:197], v[120:123]
	v_mfma_f32_16x16x32_bf16 v[108:111], v[144:147], v[202:205], v[108:111]
	v_mfma_f32_16x16x32_bf16 v[104:107], v[152:155], v[202:205], v[104:107]
	v_mfma_f32_16x16x32_bf16 v[92:95], v[144:147], v[210:213], v[92:95]
	v_mfma_f32_16x16x32_bf16 v[88:91], v[152:155], v[210:213], v[88:91]
	v_mfma_f32_16x16x32_bf16 v[76:79], v[144:147], v[218:221], v[76:79]
	v_mfma_f32_16x16x32_bf16 v[72:75], v[152:155], v[218:221], v[72:75]
	v_mfma_f32_16x16x32_bf16 v[116:119], v[156:159], v[190:193], v[116:119]
	v_mfma_f32_16x16x32_bf16 v[112:115], v[164:167], v[190:193], v[112:115]
	v_mfma_f32_16x16x32_bf16 v[100:103], v[156:159], v[198:201], v[100:103]
	v_mfma_f32_16x16x32_bf16 v[96:99], v[164:167], v[198:201], v[96:99]
	v_mfma_f32_16x16x32_bf16 v[84:87], v[156:159], v[206:209], v[84:87]
	v_mfma_f32_16x16x32_bf16 v[80:83], v[164:167], v[206:209], v[80:83]
	v_mfma_f32_16x16x32_bf16 v[68:71], v[156:159], v[214:217], v[68:71]
	v_mfma_f32_16x16x32_bf16 v[64:67], v[164:167], v[214:217], v[64:67]
	v_mfma_f32_16x16x32_bf16 v[116:119], v[160:163], v[194:197], v[116:119]
	v_mfma_f32_16x16x32_bf16 v[112:115], v[186:189], v[194:197], v[112:115]
	v_mfma_f32_16x16x32_bf16 v[100:103], v[160:163], v[202:205], v[100:103]
	v_mfma_f32_16x16x32_bf16 v[96:99], v[186:189], v[202:205], v[96:99]
	v_mfma_f32_16x16x32_bf16 v[84:87], v[160:163], v[210:213], v[84:87]
	v_mfma_f32_16x16x32_bf16 v[80:83], v[186:189], v[210:213], v[80:83]
	v_mfma_f32_16x16x32_bf16 v[68:71], v[160:163], v[218:221], v[68:71]
	v_mfma_f32_16x16x32_bf16 v[64:67], v[186:189], v[218:221], v[64:67]
	s_barrier
	s_add_i32 s38, s61, s42
	v_lshl_add_u64 v[222:223], v[222:223], 0, s[12:13]
	s_mov_b32 m0, s38
	ds_read_b128 v[190:193], v185 offset:49152
	ds_read_b128 v[194:197], v185 offset:50176
	ds_read_b128 v[198:201], v185 offset:51200
	ds_read_b128 v[202:205], v185 offset:52224
	ds_read_b128 v[206:209], v185 offset:53248
	ds_read_b128 v[210:213], v185 offset:54272
	ds_read_b128 v[214:217], v185 offset:55296
	ds_read_b128 v[218:221], v185 offset:56320
	global_load_lds_dwordx4 v[222:223], off
	s_add_i32 m0, s38, 0x2000
	s_add_u32 s36, s36, 0x40080
	v_lshl_add_u64 v[222:223], v[224:225], 0, s[12:13]
	s_addc_u32 s37, s37, 0
	s_add_i32 s38, s62, s42
	global_load_lds_dwordx4 v[222:223], off
	s_mov_b32 m0, s38
	v_lshl_add_u64 v[222:223], s[36:37], 0, v[128:129]
	global_load_lds_dwordx4 v[222:223], off
	s_add_i32 m0, s38, 0x2000
	v_lshl_add_u64 v[222:223], s[36:37], 0, v[130:131]
	global_load_lds_dwordx4 v[222:223], off
	v_lshl_add_u64 v[222:223], v[226:227], 0, s[12:13]
	s_mov_b32 m0, s48
	s_nop 0
	global_load_lds_dwordx4 v[222:223], off
	v_lshl_add_u64 v[222:223], v[228:229], 0, s[12:13]
	s_mov_b32 m0, s49
	s_nop 0
	global_load_lds_dwordx4 v[222:223], off
	s_waitcnt vmcnt(8) lgkmcnt(0)
	s_barrier
	v_mfma_f32_16x16x32_bf16 v[60:63], v[140:143], v[190:193], v[60:63]
	v_mfma_f32_16x16x32_bf16 v[56:59], v[148:151], v[190:193], v[56:59]
	v_mfma_f32_16x16x32_bf16 v[44:47], v[140:143], v[198:201], v[44:47]
	v_mfma_f32_16x16x32_bf16 v[40:43], v[148:151], v[198:201], v[40:43]
	v_mfma_f32_16x16x32_bf16 v[28:31], v[140:143], v[206:209], v[28:31]
	v_mfma_f32_16x16x32_bf16 v[24:27], v[148:151], v[206:209], v[24:27]
	v_mfma_f32_16x16x32_bf16 v[12:15], v[140:143], v[214:217], v[12:15]
	v_mfma_f32_16x16x32_bf16 v[8:11], v[148:151], v[214:217], v[8:11]
	v_mfma_f32_16x16x32_bf16 v[60:63], v[144:147], v[194:197], v[60:63]
	v_mfma_f32_16x16x32_bf16 v[56:59], v[152:155], v[194:197], v[56:59]
	v_mfma_f32_16x16x32_bf16 v[44:47], v[144:147], v[202:205], v[44:47]
	v_mfma_f32_16x16x32_bf16 v[40:43], v[152:155], v[202:205], v[40:43]
	v_mfma_f32_16x16x32_bf16 v[28:31], v[144:147], v[210:213], v[28:31]
	v_mfma_f32_16x16x32_bf16 v[24:27], v[152:155], v[210:213], v[24:27]
	v_mfma_f32_16x16x32_bf16 v[12:15], v[144:147], v[218:221], v[12:15]
	v_mfma_f32_16x16x32_bf16 v[8:11], v[152:155], v[218:221], v[8:11]
	v_mfma_f32_16x16x32_bf16 v[52:55], v[156:159], v[190:193], v[52:55]
	v_mfma_f32_16x16x32_bf16 v[48:51], v[164:167], v[190:193], v[48:51]
	v_mfma_f32_16x16x32_bf16 v[36:39], v[156:159], v[198:201], v[36:39]
	v_mfma_f32_16x16x32_bf16 v[32:35], v[164:167], v[198:201], v[32:35]
	v_mfma_f32_16x16x32_bf16 v[20:23], v[156:159], v[206:209], v[20:23]
	v_mfma_f32_16x16x32_bf16 v[16:19], v[164:167], v[206:209], v[16:19]
	v_mfma_f32_16x16x32_bf16 v[4:7], v[156:159], v[214:217], v[4:7]
	v_mfma_f32_16x16x32_bf16 v[0:3], v[164:167], v[214:217], v[0:3]
	v_mfma_f32_16x16x32_bf16 v[52:55], v[160:163], v[194:197], v[52:55]
	v_mfma_f32_16x16x32_bf16 v[48:51], v[186:189], v[194:197], v[48:51]
	v_mfma_f32_16x16x32_bf16 v[36:39], v[160:163], v[202:205], v[36:39]
	v_mfma_f32_16x16x32_bf16 v[32:35], v[186:189], v[202:205], v[32:35]
	v_mfma_f32_16x16x32_bf16 v[20:23], v[160:163], v[210:213], v[20:23]
	v_mfma_f32_16x16x32_bf16 v[16:19], v[186:189], v[210:213], v[16:19]
	v_mfma_f32_16x16x32_bf16 v[4:7], v[160:163], v[218:221], v[4:7]
	v_mfma_f32_16x16x32_bf16 v[0:3], v[186:189], v[218:221], v[0:3]
	s_barrier
	s_add_i32 s60, s60, 2
	s_add_u32 s34, s34, 0x100
	s_addc_u32 s35, s35, 0
	s_add_u32 s56, s56, 0x100
	s_addc_u32 s57, s57, 0
	s_cmp_gt_u32 s60, 13
	s_cbranch_scc0 .LBB0_758
	s_and_b64 vcc, exec, s[14:15]
	s_cbranch_vccz .LBB0_761
	s_barrier

.LBB0_778:
	v_add_u32_e32 v147, s43, v145
	ds_read_b128 v[148:151], v147
	ds_read_b128 v[152:155], v147 offset:1024
	ds_read_b128 v[156:159], v147 offset:2048
	ds_read_b128 v[160:163], v147 offset:3072
	v_add_u32_e32 v147, s44, v145
	s_add_u32 s26, s12, s24
	ds_read_b128 v[164:167], v147
	ds_read_b128 v[180:183], v147 offset:1024
	ds_read_b128 v[184:187], v147 offset:2048
	ds_read_b128 v[188:191], v147 offset:3072
	s_addc_u32 s27, s13, s25
	s_add_u32 s26, s26, 0x100
	s_addc_u32 s27, s27, 0
	s_add_u32 s51, s46, s24
	s_addc_u32 s52, s47, s25
	s_cmpk_eq_i32 s24, 0x700
	s_cselect_b32 s29, s19, s27
	s_cselect_b32 s28, s48, s26
	s_cselect_b32 s27, s17, s52
	s_cselect_b32 s26, s49, s51
	v_lshl_add_u64 v[168:169], v[140:141], 0, s[24:25]
	s_add_i32 m0, s11, 0xc000
	ds_read_b128 v[192:195], v146
	ds_read_b128 v[196:199], v146 offset:1024
	ds_read_b128 v[200:203], v146 offset:2048
	ds_read_b128 v[204:207], v146 offset:3072
	ds_read_b128 v[208:211], v146 offset:4096
	ds_read_b128 v[212:215], v146 offset:5120
	ds_read_b128 v[216:219], v146 offset:6144
	ds_read_b128 v[220:223], v146 offset:7168
	global_load_lds_dwordx4 v[168:169], off
	v_lshl_add_u64 v[168:169], v[142:143], 0, s[24:25]
	s_add_i32 m0, s11, 0xe000
	s_nop 0
	global_load_lds_dwordx4 v[168:169], off
	s_waitcnt vmcnt(8) lgkmcnt(0)
	s_barrier
	v_mfma_f32_16x16x32_bf16 v[100:103], v[148:151], v[192:195], v[100:103]
	v_mfma_f32_16x16x32_bf16 v[96:99], v[156:159], v[192:195], v[96:99]
	v_mfma_f32_16x16x32_bf16 v[108:111], v[148:151], v[200:203], v[108:111]
	v_mfma_f32_16x16x32_bf16 v[84:87], v[156:159], v[200:203], v[84:87]
	v_mfma_f32_16x16x32_bf16 v[116:119], v[148:151], v[208:211], v[116:119]
	v_mfma_f32_16x16x32_bf16 v[112:115], v[156:159], v[208:211], v[112:115]
	v_mfma_f32_16x16x32_bf16 v[124:127], v[148:151], v[216:219], v[124:127]
	v_mfma_f32_16x16x32_bf16 v[120:123], v[156:159], v[216:219], v[120:123]
	v_mfma_f32_16x16x32_bf16 v[100:103], v[152:155], v[196:199], v[100:103]
	v_mfma_f32_16x16x32_bf16 v[96:99], v[160:163], v[196:199], v[96:99]
	v_mfma_f32_16x16x32_bf16 v[108:111], v[152:155], v[204:207], v[108:111]
	v_mfma_f32_16x16x32_bf16 v[84:87], v[160:163], v[204:207], v[84:87]
	v_mfma_f32_16x16x32_bf16 v[116:119], v[152:155], v[212:215], v[116:119]
	v_mfma_f32_16x16x32_bf16 v[112:115], v[160:163], v[212:215], v[112:115]
	v_mfma_f32_16x16x32_bf16 v[124:127], v[152:155], v[220:223], v[124:127]
	v_mfma_f32_16x16x32_bf16 v[120:123], v[160:163], v[220:223], v[120:123]
	v_mfma_f32_16x16x32_bf16 v[76:79], v[164:167], v[192:195], v[76:79]
	v_mfma_f32_16x16x32_bf16 v[68:71], v[184:187], v[192:195], v[68:71]
	v_mfma_f32_16x16x32_bf16 v[72:75], v[164:167], v[200:203], v[72:75]
	v_mfma_f32_16x16x32_bf16 v[64:67], v[184:187], v[200:203], v[64:67]
	v_mfma_f32_16x16x32_bf16 v[88:91], v[164:167], v[208:211], v[88:91]
	v_mfma_f32_16x16x32_bf16 v[80:83], v[184:187], v[208:211], v[80:83]
	v_mfma_f32_16x16x32_bf16 v[104:107], v[164:167], v[216:219], v[104:107]
	v_mfma_f32_16x16x32_bf16 v[92:95], v[184:187], v[216:219], v[92:95]
	v_mfma_f32_16x16x32_bf16 v[76:79], v[180:183], v[196:199], v[76:79]
	v_mfma_f32_16x16x32_bf16 v[68:71], v[188:191], v[196:199], v[68:71]
	v_mfma_f32_16x16x32_bf16 v[72:75], v[180:183], v[204:207], v[72:75]
	v_mfma_f32_16x16x32_bf16 v[64:67], v[188:191], v[204:207], v[64:67]
	v_mfma_f32_16x16x32_bf16 v[88:91], v[180:183], v[212:215], v[88:91]
	v_mfma_f32_16x16x32_bf16 v[80:83], v[188:191], v[212:215], v[80:83]
	v_mfma_f32_16x16x32_bf16 v[104:107], v[180:183], v[220:223], v[104:107]
	v_mfma_f32_16x16x32_bf16 v[92:95], v[188:191], v[220:223], v[92:95]
	s_barrier
	s_add_i32 s51, s43, s35
	v_lshl_add_u64 v[168:169], s[26:27], 0, v[128:129]
	s_mov_b32 m0, s51
	ds_read_b128 v[192:195], v146 offset:16384
	ds_read_b128 v[196:199], v146 offset:17408
	ds_read_b128 v[200:203], v146 offset:18432
	ds_read_b128 v[204:207], v146 offset:19456
	ds_read_b128 v[208:211], v146 offset:20480
	ds_read_b128 v[212:215], v146 offset:21504
	ds_read_b128 v[216:219], v146 offset:22528
	ds_read_b128 v[220:223], v146 offset:23552
	global_load_lds_dwordx4 v[168:169], off
	s_add_i32 m0, s51, 0x2000
	s_add_u32 s52, s26, 0x40000
	v_lshl_add_u64 v[224:225], s[26:27], 0, v[130:131]
	s_addc_u32 s53, s27, 0
	s_add_i32 s51, s44, s35
	global_load_lds_dwordx4 v[224:225], off
	v_lshl_add_u64 v[226:227], s[52:53], 0, v[128:129]
	s_mov_b32 m0, s51
	v_lshl_add_u64 v[228:229], s[28:29], 0, v[130:131]
	global_load_lds_dwordx4 v[226:227], off
	s_add_i32 m0, s51, 0x2000
	v_lshl_add_u64 v[226:227], s[52:53], 0, v[130:131]
	global_load_lds_dwordx4 v[226:227], off
	s_mov_b32 m0, s11
	v_lshl_add_u64 v[226:227], s[28:29], 0, v[128:129]
	global_load_lds_dwordx4 v[226:227], off
	s_mov_b32 m0, s36
	s_nop 0
	global_load_lds_dwordx4 v[228:229], off
	s_waitcnt vmcnt(8) lgkmcnt(0)
	s_barrier
	v_mfma_f32_16x16x32_bf16 v[60:63], v[148:151], v[192:195], v[60:63]
	v_mfma_f32_16x16x32_bf16 v[56:59], v[156:159], v[192:195], v[56:59]
	v_mfma_f32_16x16x32_bf16 v[44:47], v[148:151], v[200:203], v[44:47]
	v_mfma_f32_16x16x32_bf16 v[40:43], v[156:159], v[200:203], v[40:43]
	v_mfma_f32_16x16x32_bf16 v[28:31], v[148:151], v[208:211], v[28:31]
	v_mfma_f32_16x16x32_bf16 v[24:27], v[156:159], v[208:211], v[24:27]
	v_mfma_f32_16x16x32_bf16 v[12:15], v[148:151], v[216:219], v[12:15]
	v_mfma_f32_16x16x32_bf16 v[8:11], v[156:159], v[216:219], v[8:11]
	v_mfma_f32_16x16x32_bf16 v[60:63], v[152:155], v[196:199], v[60:63]
	v_mfma_f32_16x16x32_bf16 v[56:59], v[160:163], v[196:199], v[56:59]
	v_mfma_f32_16x16x32_bf16 v[44:47], v[152:155], v[204:207], v[44:47]
	v_mfma_f32_16x16x32_bf16 v[40:43], v[160:163], v[204:207], v[40:43]
	v_mfma_f32_16x16x32_bf16 v[28:31], v[152:155], v[212:215], v[28:31]
	v_mfma_f32_16x16x32_bf16 v[24:27], v[160:163], v[212:215], v[24:27]
	v_mfma_f32_16x16x32_bf16 v[12:15], v[152:155], v[220:223], v[12:15]
	v_mfma_f32_16x16x32_bf16 v[8:11], v[160:163], v[220:223], v[8:11]
	v_mfma_f32_16x16x32_bf16 v[52:55], v[164:167], v[192:195], v[52:55]
	v_mfma_f32_16x16x32_bf16 v[48:51], v[184:187], v[192:195], v[48:51]
	v_mfma_f32_16x16x32_bf16 v[36:39], v[164:167], v[200:203], v[36:39]
	v_mfma_f32_16x16x32_bf16 v[32:35], v[184:187], v[200:203], v[32:35]
	v_mfma_f32_16x16x32_bf16 v[20:23], v[164:167], v[208:211], v[20:23]
	v_mfma_f32_16x16x32_bf16 v[16:19], v[184:187], v[208:211], v[16:19]
	v_mfma_f32_16x16x32_bf16 v[4:7], v[164:167], v[216:219], v[4:7]
	v_mfma_f32_16x16x32_bf16 v[0:3], v[184:187], v[216:219], v[0:3]
	v_mfma_f32_16x16x32_bf16 v[52:55], v[180:183], v[196:199], v[52:55]
	v_mfma_f32_16x16x32_bf16 v[48:51], v[188:191], v[196:199], v[48:51]
	v_mfma_f32_16x16x32_bf16 v[36:39], v[180:183], v[204:207], v[36:39]
	v_mfma_f32_16x16x32_bf16 v[32:35], v[188:191], v[204:207], v[32:35]
	v_mfma_f32_16x16x32_bf16 v[20:23], v[180:183], v[212:215], v[20:23]
	v_mfma_f32_16x16x32_bf16 v[16:19], v[188:191], v[212:215], v[16:19]
	v_mfma_f32_16x16x32_bf16 v[4:7], v[180:183], v[220:223], v[4:7]
	v_mfma_f32_16x16x32_bf16 v[0:3], v[188:191], v[220:223], v[0:3]
	s_barrier
	s_add_i32 s51, 0, 0x18000
	v_add_u32_e32 v147, s51, v145
	s_add_i32 s52, 0, 0x1c000
	ds_read_b128 v[148:151], v147
	ds_read_b128 v[152:155], v147 offset:1024
	ds_read_b128 v[156:159], v147 offset:2048
	ds_read_b128 v[160:163], v147 offset:3072
	v_add_u32_e32 v147, s52, v145
	ds_read_b128 v[164:167], v147
	ds_read_b128 v[180:183], v147 offset:1024
	ds_read_b128 v[184:187], v147 offset:2048
	ds_read_b128 v[188:191], v147 offset:3072
	s_add_u32 s28, s28, 0x40000
	s_addc_u32 s29, s29, 0
	s_mov_b32 m0, s37
	v_lshl_add_u64 v[230:231], s[28:29], 0, v[128:129]
	ds_read_b128 v[192:195], v146 offset:32768
	ds_read_b128 v[196:199], v146 offset:33792
	ds_read_b128 v[200:203], v146 offset:34816
	ds_read_b128 v[204:207], v146 offset:35840
	ds_read_b128 v[208:211], v146 offset:36864
	ds_read_b128 v[212:215], v146 offset:37888
	ds_read_b128 v[216:219], v146 offset:38912
	ds_read_b128 v[220:223], v146 offset:39936
	global_load_lds_dwordx4 v[230:231], off
	s_mov_b32 m0, s38
	v_lshl_add_u64 v[230:231], s[28:29], 0, v[130:131]
	global_load_lds_dwordx4 v[230:231], off
	s_waitcnt vmcnt(8) lgkmcnt(0)
	s_barrier
	v_mfma_f32_16x16x32_bf16 v[100:103], v[148:151], v[192:195], v[100:103]
	v_mfma_f32_16x16x32_bf16 v[96:99], v[156:159], v[192:195], v[96:99]
	v_mfma_f32_16x16x32_bf16 v[108:111], v[148:151], v[200:203], v[108:111]
	v_mfma_f32_16x16x32_bf16 v[84:87], v[156:159], v[200:203], v[84:87]
	v_mfma_f32_16x16x32_bf16 v[116:119], v[148:151], v[208:211], v[116:119]
	v_mfma_f32_16x16x32_bf16 v[112:115], v[156:159], v[208:211], v[112:115]
	v_mfma_f32_16x16x32_bf16 v[124:127], v[148:151], v[216:219], v[124:127]
	v_mfma_f32_16x16x32_bf16 v[120:123], v[156:159], v[216:219], v[120:123]
	v_mfma_f32_16x16x32_bf16 v[100:103], v[152:155], v[196:199], v[100:103]
	v_mfma_f32_16x16x32_bf16 v[96:99], v[160:163], v[196:199], v[96:99]
	v_mfma_f32_16x16x32_bf16 v[108:111], v[152:155], v[204:207], v[108:111]
	v_mfma_f32_16x16x32_bf16 v[84:87], v[160:163], v[204:207], v[84:87]
	v_mfma_f32_16x16x32_bf16 v[116:119], v[152:155], v[212:215], v[116:119]
	v_mfma_f32_16x16x32_bf16 v[112:115], v[160:163], v[212:215], v[112:115]
	v_mfma_f32_16x16x32_bf16 v[124:127], v[152:155], v[220:223], v[124:127]
	v_mfma_f32_16x16x32_bf16 v[120:123], v[160:163], v[220:223], v[120:123]
	v_mfma_f32_16x16x32_bf16 v[76:79], v[164:167], v[192:195], v[76:79]
	v_mfma_f32_16x16x32_bf16 v[68:71], v[184:187], v[192:195], v[68:71]
	v_mfma_f32_16x16x32_bf16 v[72:75], v[164:167], v[200:203], v[72:75]
	v_mfma_f32_16x16x32_bf16 v[64:67], v[184:187], v[200:203], v[64:67]
	v_mfma_f32_16x16x32_bf16 v[88:91], v[164:167], v[208:211], v[88:91]
	v_mfma_f32_16x16x32_bf16 v[80:83], v[184:187], v[208:211], v[80:83]
	v_mfma_f32_16x16x32_bf16 v[104:107], v[164:167], v[216:219], v[104:107]
	v_mfma_f32_16x16x32_bf16 v[92:95], v[184:187], v[216:219], v[92:95]
	v_mfma_f32_16x16x32_bf16 v[76:79], v[180:183], v[196:199], v[76:79]
	v_mfma_f32_16x16x32_bf16 v[68:71], v[188:191], v[196:199], v[68:71]
	v_mfma_f32_16x16x32_bf16 v[72:75], v[180:183], v[204:207], v[72:75]
	v_mfma_f32_16x16x32_bf16 v[64:67], v[188:191], v[204:207], v[64:67]
	v_mfma_f32_16x16x32_bf16 v[88:91], v[180:183], v[212:215], v[88:91]
	v_mfma_f32_16x16x32_bf16 v[80:83], v[188:191], v[212:215], v[80:83]
	v_mfma_f32_16x16x32_bf16 v[104:107], v[180:183], v[220:223], v[104:107]
	v_mfma_f32_16x16x32_bf16 v[92:95], v[188:191], v[220:223], v[92:95]
	s_barrier
	s_add_i32 s28, s51, s35
	v_lshl_add_u64 v[168:169], v[168:169], 0, s[14:15]
	s_mov_b32 m0, s28
	ds_read_b128 v[192:195], v146 offset:49152
	ds_read_b128 v[196:199], v146 offset:50176
	ds_read_b128 v[200:203], v146 offset:51200
	ds_read_b128 v[204:207], v146 offset:52224
	ds_read_b128 v[208:211], v146 offset:53248
	ds_read_b128 v[212:215], v146 offset:54272
	ds_read_b128 v[216:219], v146 offset:55296
	ds_read_b128 v[220:223], v146 offset:56320
	global_load_lds_dwordx4 v[168:169], off
	s_add_i32 m0, s28, 0x2000
	s_add_u32 s26, s26, 0x40080
	v_lshl_add_u64 v[168:169], v[224:225], 0, s[14:15]
	s_addc_u32 s27, s27, 0
	s_add_i32 s28, s52, s35
	global_load_lds_dwordx4 v[168:169], off
	s_mov_b32 m0, s28
	v_lshl_add_u64 v[168:169], s[26:27], 0, v[128:129]
	global_load_lds_dwordx4 v[168:169], off
	s_add_i32 m0, s28, 0x2000
	v_lshl_add_u64 v[168:169], s[26:27], 0, v[130:131]
	global_load_lds_dwordx4 v[168:169], off
	v_lshl_add_u64 v[168:169], v[226:227], 0, s[14:15]
	s_mov_b32 m0, s41
	s_nop 0
	global_load_lds_dwordx4 v[168:169], off
	v_lshl_add_u64 v[168:169], v[228:229], 0, s[14:15]
	s_mov_b32 m0, s42
	s_nop 0
	global_load_lds_dwordx4 v[168:169], off
	s_waitcnt vmcnt(8) lgkmcnt(0)
	s_barrier
	v_mfma_f32_16x16x32_bf16 v[60:63], v[148:151], v[192:195], v[60:63]
	v_mfma_f32_16x16x32_bf16 v[56:59], v[156:159], v[192:195], v[56:59]
	v_mfma_f32_16x16x32_bf16 v[44:47], v[148:151], v[200:203], v[44:47]
	v_mfma_f32_16x16x32_bf16 v[40:43], v[156:159], v[200:203], v[40:43]
	v_mfma_f32_16x16x32_bf16 v[28:31], v[148:151], v[208:211], v[28:31]
	v_mfma_f32_16x16x32_bf16 v[24:27], v[156:159], v[208:211], v[24:27]
	v_mfma_f32_16x16x32_bf16 v[12:15], v[148:151], v[216:219], v[12:15]
	v_mfma_f32_16x16x32_bf16 v[8:11], v[156:159], v[216:219], v[8:11]
	v_mfma_f32_16x16x32_bf16 v[60:63], v[152:155], v[196:199], v[60:63]
	v_mfma_f32_16x16x32_bf16 v[56:59], v[160:163], v[196:199], v[56:59]
	v_mfma_f32_16x16x32_bf16 v[44:47], v[152:155], v[204:207], v[44:47]
	v_mfma_f32_16x16x32_bf16 v[40:43], v[160:163], v[204:207], v[40:43]
	v_mfma_f32_16x16x32_bf16 v[28:31], v[152:155], v[212:215], v[28:31]
	v_mfma_f32_16x16x32_bf16 v[24:27], v[160:163], v[212:215], v[24:27]
	v_mfma_f32_16x16x32_bf16 v[12:15], v[152:155], v[220:223], v[12:15]
	v_mfma_f32_16x16x32_bf16 v[8:11], v[160:163], v[220:223], v[8:11]
	v_mfma_f32_16x16x32_bf16 v[52:55], v[164:167], v[192:195], v[52:55]
	v_mfma_f32_16x16x32_bf16 v[48:51], v[184:187], v[192:195], v[48:51]
	v_mfma_f32_16x16x32_bf16 v[36:39], v[164:167], v[200:203], v[36:39]
	v_mfma_f32_16x16x32_bf16 v[32:35], v[184:187], v[200:203], v[32:35]
	v_mfma_f32_16x16x32_bf16 v[20:23], v[164:167], v[208:211], v[20:23]
	v_mfma_f32_16x16x32_bf16 v[16:19], v[184:187], v[208:211], v[16:19]
	v_mfma_f32_16x16x32_bf16 v[4:7], v[164:167], v[216:219], v[4:7]
	v_mfma_f32_16x16x32_bf16 v[0:3], v[184:187], v[216:219], v[0:3]
	v_mfma_f32_16x16x32_bf16 v[52:55], v[180:183], v[196:199], v[52:55]
	v_mfma_f32_16x16x32_bf16 v[48:51], v[188:191], v[196:199], v[48:51]
	v_mfma_f32_16x16x32_bf16 v[36:39], v[180:183], v[204:207], v[36:39]
	v_mfma_f32_16x16x32_bf16 v[32:35], v[188:191], v[204:207], v[32:35]
	v_mfma_f32_16x16x32_bf16 v[20:23], v[180:183], v[212:215], v[20:23]
	v_mfma_f32_16x16x32_bf16 v[16:19], v[188:191], v[212:215], v[16:19]
	v_mfma_f32_16x16x32_bf16 v[4:7], v[180:183], v[220:223], v[4:7]
	v_mfma_f32_16x16x32_bf16 v[0:3], v[188:191], v[220:223], v[0:3]
	s_barrier
	s_add_i32 s50, s50, 2
	s_add_u32 s24, s24, 0x100
	s_addc_u32 s25, s25, 0
	s_cmp_gt_u32 s50, 13
	s_cbranch_scc0 .LBB0_778
	s_add_u32 s24, s46, 0xffffff00
	s_addc_u32 s25, s47, -1
	s_andn2_b64 vcc, exec, s[2:3]
	s_cbranch_vccnz .LBB0_781
	v_mov_b64_e32 v[0:1], 0
	s_mov_b32 s4, s16
	s_mov_b32 s10, s18
	s_mov_b64 s[12:13], s[22:23]
	s_mov_b32 s40, s45
	v_mov_b64_e32 v[2:3], 0
	v_mov_b64_e32 v[4:5], 0
	v_mov_b64_e32 v[6:7], 0
	v_mov_b64_e32 v[16:17], 0
	v_mov_b64_e32 v[18:19], 0
	v_mov_b64_e32 v[20:21], 0
	v_mov_b64_e32 v[22:23], 0
	v_mov_b64_e32 v[32:33], 0
	v_mov_b64_e32 v[34:35], 0
	v_mov_b64_e32 v[36:37], 0
	v_mov_b64_e32 v[38:39], 0
	v_mov_b64_e32 v[48:49], 0
	v_mov_b64_e32 v[50:51], 0
	v_mov_b64_e32 v[52:53], 0
	v_mov_b64_e32 v[54:55], 0
	v_mov_b64_e32 v[8:9], 0
	v_mov_b64_e32 v[10:11], 0
	v_mov_b64_e32 v[12:13], 0
	v_mov_b64_e32 v[14:15], 0
	v_mov_b64_e32 v[24:25], 0
	v_mov_b64_e32 v[26:27], 0
	v_mov_b64_e32 v[28:29], 0
	v_mov_b64_e32 v[30:31], 0
	v_mov_b64_e32 v[40:41], 0
	v_mov_b64_e32 v[42:43], 0
	v_mov_b64_e32 v[44:45], 0
	v_mov_b64_e32 v[46:47], 0
	v_mov_b64_e32 v[56:57], 0
	v_mov_b64_e32 v[58:59], 0
	v_mov_b64_e32 v[60:61], 0
	v_mov_b64_e32 v[62:63], 0
	v_mov_b64_e32 v[92:93], 0
	v_mov_b64_e32 v[94:95], 0
	v_mov_b64_e32 v[104:105], 0
	v_mov_b64_e32 v[106:107], 0
	v_mov_b64_e32 v[80:81], 0
	v_mov_b64_e32 v[82:83], 0
	v_mov_b64_e32 v[88:89], 0
	v_mov_b64_e32 v[90:91], 0
	v_mov_b64_e32 v[64:65], 0
	v_mov_b64_e32 v[66:67], 0
	v_mov_b64_e32 v[72:73], 0
	v_mov_b64_e32 v[74:75], 0
	v_mov_b64_e32 v[68:69], 0
	v_mov_b64_e32 v[70:71], 0
	v_mov_b64_e32 v[76:77], 0
	v_mov_b64_e32 v[78:79], 0
	v_mov_b64_e32 v[120:121], 0
	v_mov_b64_e32 v[122:123], 0
	v_mov_b64_e32 v[124:125], 0
	v_mov_b64_e32 v[126:127], 0
	v_mov_b64_e32 v[112:113], 0
	v_mov_b64_e32 v[114:115], 0
	v_mov_b64_e32 v[116:117], 0
	v_mov_b64_e32 v[118:119], 0
	v_mov_b64_e32 v[84:85], 0
	v_mov_b64_e32 v[86:87], 0
	v_mov_b64_e32 v[108:109], 0
	v_mov_b64_e32 v[110:111], 0
	v_mov_b64_e32 v[96:97], 0
	v_mov_b64_e32 v[98:99], 0
	v_mov_b64_e32 v[100:101], 0
	v_mov_b64_e32 v[102:103], 0
	s_branch .LBB0_782

.LBB0_941:
	v_readlane_b32 s56, v246, 32
	v_readlane_b32 s57, v246, 33
	s_ashr_i32 s15, s14, 31
	v_readlane_b32 s58, v246, 34
	v_readlane_b32 s59, v246, 35
	s_mov_b64 s[48:49], s[56:57]
	s_lshl_b64 s[16:17], s[14:15], 19
	s_mov_b64 s[50:51], s[58:59]
	s_add_u32 s16, s50, s16
	s_addc_u32 s17, s51, s17
	s_and_b64 s[18:19], s[0:1], exec
	s_cselect_b32 s15, s17, s23
	s_cselect_b32 s44, s16, s22
	s_ashr_i32 s13, s12, 31
	s_lshl_b64 s[18:19], s[12:13], 19
	v_readlane_b32 s26, v246, 44
	v_readlane_b32 s27, v246, 45
	s_add_u32 s18, s26, s18
	s_addc_u32 s19, s27, s19
	s_and_b64 s[26:27], s[0:1], exec
	s_cselect_b32 s13, s19, s25
	s_cselect_b32 s45, s18, s24
	s_add_u32 s22, s22, 0x40080
	s_addc_u32 s23, s23, 0
	s_add_u32 s46, s24, 0x100
	s_addc_u32 s47, s25, 0
	s_mov_b32 s48, -2
	ds_read_b128 v[150:153], v147
	ds_read_b128 v[154:157], v147 offset:1024
	ds_read_b128 v[158:161], v147 offset:2048
	ds_read_b128 v[162:165], v147 offset:3072
	ds_read_b128 v[166:169], v148
	ds_read_b128 v[180:183], v148 offset:1024
	ds_read_b128 v[184:187], v148 offset:2048
	ds_read_b128 v[188:191], v148 offset:3072
	s_add_u32 s24, s22, 0xfffc0080
	s_addc_u32 s25, s23, -1
	s_cmp_eq_u32 s48, 12
	s_cselect_b32 s27, s15, s25
	s_cselect_b32 s26, s44, s24
	s_cselect_b32 s25, s13, s47
	s_cselect_b32 s24, s45, s46
	v_lshl_add_u64 v[224:225], s[22:23], 0, v[136:137]
	s_add_i32 m0, s21, 0xc000
	ds_read_b128 v[192:195], v149
	ds_read_b128 v[196:199], v149 offset:1024
	ds_read_b128 v[200:203], v149 offset:2048
	ds_read_b128 v[204:207], v149 offset:3072
	ds_read_b128 v[208:211], v149 offset:4096
	ds_read_b128 v[212:215], v149 offset:5120
	ds_read_b128 v[216:219], v149 offset:6144
	ds_read_b128 v[220:223], v149 offset:7168
	global_load_lds_dwordx4 v[224:225], off
	s_add_i32 m0, s21, 0xe000
	v_lshl_add_u64 v[224:225], s[22:23], 0, v[138:139]
	global_load_lds_dwordx4 v[224:225], off
	s_waitcnt vmcnt(8) lgkmcnt(0)
	s_barrier
	v_mfma_f32_16x16x32_bf16 v[124:127], v[150:153], v[192:195], 0
	v_mfma_f32_16x16x32_bf16 v[120:123], v[158:161], v[192:195], 0
	v_mfma_f32_16x16x32_bf16 v[108:111], v[150:153], v[200:203], 0
	v_mfma_f32_16x16x32_bf16 v[104:107], v[158:161], v[200:203], 0
	v_mfma_f32_16x16x32_bf16 v[92:95], v[150:153], v[208:211], 0
	v_mfma_f32_16x16x32_bf16 v[88:91], v[158:161], v[208:211], 0
	v_mfma_f32_16x16x32_bf16 v[76:79], v[150:153], v[216:219], 0
	v_mfma_f32_16x16x32_bf16 v[72:75], v[158:161], v[216:219], 0
	v_mfma_f32_16x16x32_bf16 v[124:127], v[154:157], v[196:199], v[124:127]
	v_mfma_f32_16x16x32_bf16 v[120:123], v[162:165], v[196:199], v[120:123]
	v_mfma_f32_16x16x32_bf16 v[108:111], v[154:157], v[204:207], v[108:111]
	v_mfma_f32_16x16x32_bf16 v[104:107], v[162:165], v[204:207], v[104:107]
	v_mfma_f32_16x16x32_bf16 v[92:95], v[154:157], v[212:215], v[92:95]
	v_mfma_f32_16x16x32_bf16 v[88:91], v[162:165], v[212:215], v[88:91]
	v_mfma_f32_16x16x32_bf16 v[76:79], v[154:157], v[220:223], v[76:79]
	v_mfma_f32_16x16x32_bf16 v[72:75], v[162:165], v[220:223], v[72:75]
	v_mfma_f32_16x16x32_bf16 v[116:119], v[166:169], v[192:195], 0
	v_mfma_f32_16x16x32_bf16 v[112:115], v[184:187], v[192:195], 0
	v_mfma_f32_16x16x32_bf16 v[100:103], v[166:169], v[200:203], 0
	v_mfma_f32_16x16x32_bf16 v[96:99], v[184:187], v[200:203], 0
	v_mfma_f32_16x16x32_bf16 v[84:87], v[166:169], v[208:211], 0
	v_mfma_f32_16x16x32_bf16 v[80:83], v[184:187], v[208:211], 0
	v_mfma_f32_16x16x32_bf16 v[68:71], v[166:169], v[216:219], 0
	v_mfma_f32_16x16x32_bf16 v[64:67], v[184:187], v[216:219], 0
	v_mfma_f32_16x16x32_bf16 v[116:119], v[180:183], v[196:199], v[116:119]
	v_mfma_f32_16x16x32_bf16 v[112:115], v[188:191], v[196:199], v[112:115]
	v_mfma_f32_16x16x32_bf16 v[100:103], v[180:183], v[204:207], v[100:103]
	v_mfma_f32_16x16x32_bf16 v[96:99], v[188:191], v[204:207], v[96:99]
	v_mfma_f32_16x16x32_bf16 v[84:87], v[180:183], v[212:215], v[84:87]
	v_mfma_f32_16x16x32_bf16 v[80:83], v[188:191], v[212:215], v[80:83]
	v_mfma_f32_16x16x32_bf16 v[68:71], v[180:183], v[220:223], v[68:71]
	v_mfma_f32_16x16x32_bf16 v[64:67], v[188:191], v[220:223], v[64:67]
	s_barrier
	s_add_i32 s49, s40, s28
	v_lshl_add_u64 v[224:225], s[24:25], 0, v[130:131]
	s_mov_b32 m0, s49
	ds_read_b128 v[192:195], v149 offset:16384
	ds_read_b128 v[196:199], v149 offset:17408
	ds_read_b128 v[200:203], v149 offset:18432
	ds_read_b128 v[204:207], v149 offset:19456
	ds_read_b128 v[208:211], v149 offset:20480
	ds_read_b128 v[212:215], v149 offset:21504
	ds_read_b128 v[216:219], v149 offset:22528
	ds_read_b128 v[220:223], v149 offset:23552
	global_load_lds_dwordx4 v[224:225], off
	s_add_i32 m0, s49, 0x2000
	s_add_u32 s50, s24, 0x40000
	v_lshl_add_u64 v[226:227], s[24:25], 0, v[134:135]
	s_addc_u32 s51, s25, 0
	s_add_i32 s49, s41, s28
	global_load_lds_dwordx4 v[226:227], off
	v_lshl_add_u64 v[228:229], s[50:51], 0, v[130:131]
	s_mov_b32 m0, s49
	v_lshl_add_u64 v[230:231], s[26:27], 0, v[132:133]
	global_load_lds_dwordx4 v[228:229], off
	s_add_i32 m0, s49, 0x2000
	v_lshl_add_u64 v[228:229], s[50:51], 0, v[134:135]
	global_load_lds_dwordx4 v[228:229], off
	s_mov_b32 m0, s21
	v_lshl_add_u64 v[228:229], s[26:27], 0, v[128:129]
	global_load_lds_dwordx4 v[228:229], off
	s_mov_b32 m0, s31
	s_nop 0
	global_load_lds_dwordx4 v[230:231], off
	s_waitcnt vmcnt(8) lgkmcnt(0)
	s_barrier
	v_mfma_f32_16x16x32_bf16 v[60:63], v[150:153], v[192:195], 0
	v_mfma_f32_16x16x32_bf16 v[56:59], v[158:161], v[192:195], 0
	v_mfma_f32_16x16x32_bf16 v[44:47], v[150:153], v[200:203], 0
	v_mfma_f32_16x16x32_bf16 v[40:43], v[158:161], v[200:203], 0
	v_mfma_f32_16x16x32_bf16 v[28:31], v[150:153], v[208:211], 0
	v_mfma_f32_16x16x32_bf16 v[24:27], v[158:161], v[208:211], 0
	v_mfma_f32_16x16x32_bf16 v[12:15], v[150:153], v[216:219], 0
	v_mfma_f32_16x16x32_bf16 v[8:11], v[158:161], v[216:219], 0
	v_mfma_f32_16x16x32_bf16 v[60:63], v[154:157], v[196:199], v[60:63]
	v_mfma_f32_16x16x32_bf16 v[56:59], v[162:165], v[196:199], v[56:59]
	v_mfma_f32_16x16x32_bf16 v[44:47], v[154:157], v[204:207], v[44:47]
	v_mfma_f32_16x16x32_bf16 v[40:43], v[162:165], v[204:207], v[40:43]
	v_mfma_f32_16x16x32_bf16 v[28:31], v[154:157], v[212:215], v[28:31]
	v_mfma_f32_16x16x32_bf16 v[24:27], v[162:165], v[212:215], v[24:27]
	v_mfma_f32_16x16x32_bf16 v[12:15], v[154:157], v[220:223], v[12:15]
	v_mfma_f32_16x16x32_bf16 v[8:11], v[162:165], v[220:223], v[8:11]
	v_mfma_f32_16x16x32_bf16 v[52:55], v[166:169], v[192:195], 0
	v_mfma_f32_16x16x32_bf16 v[48:51], v[184:187], v[192:195], 0
	v_mfma_f32_16x16x32_bf16 v[36:39], v[166:169], v[200:203], 0
	v_mfma_f32_16x16x32_bf16 v[32:35], v[184:187], v[200:203], 0
	v_mfma_f32_16x16x32_bf16 v[20:23], v[166:169], v[208:211], 0
	v_mfma_f32_16x16x32_bf16 v[16:19], v[184:187], v[208:211], 0
	v_mfma_f32_16x16x32_bf16 v[4:7], v[166:169], v[216:219], 0
	v_mfma_f32_16x16x32_bf16 v[0:3], v[184:187], v[216:219], 0
	v_mfma_f32_16x16x32_bf16 v[52:55], v[180:183], v[196:199], v[52:55]
	v_mfma_f32_16x16x32_bf16 v[48:51], v[188:191], v[196:199], v[48:51]
	v_mfma_f32_16x16x32_bf16 v[36:39], v[180:183], v[204:207], v[36:39]
	v_mfma_f32_16x16x32_bf16 v[32:35], v[188:191], v[204:207], v[32:35]
	v_mfma_f32_16x16x32_bf16 v[20:23], v[180:183], v[212:215], v[20:23]
	v_mfma_f32_16x16x32_bf16 v[16:19], v[188:191], v[212:215], v[16:19]
	v_mfma_f32_16x16x32_bf16 v[4:7], v[180:183], v[220:223], v[4:7]
	v_mfma_f32_16x16x32_bf16 v[0:3], v[188:191], v[220:223], v[0:3]
	s_barrier
	s_branch .Lpeel942_mid
.LBB0_942:
	ds_read_b128 v[150:153], v147
	ds_read_b128 v[154:157], v147 offset:1024
	ds_read_b128 v[158:161], v147 offset:2048
	ds_read_b128 v[162:165], v147 offset:3072
	ds_read_b128 v[166:169], v148
	ds_read_b128 v[180:183], v148 offset:1024
	ds_read_b128 v[184:187], v148 offset:2048
	ds_read_b128 v[188:191], v148 offset:3072
	s_add_u32 s24, s22, 0xfffc0080
	s_addc_u32 s25, s23, -1
	s_cmp_eq_u32 s48, 12
	s_cselect_b32 s27, s15, s25
	s_cselect_b32 s26, s44, s24
	s_cselect_b32 s25, s13, s47
	s_cselect_b32 s24, s45, s46
	v_lshl_add_u64 v[224:225], s[22:23], 0, v[136:137]
	s_add_i32 m0, s21, 0xc000
	ds_read_b128 v[192:195], v149
	ds_read_b128 v[196:199], v149 offset:1024
	ds_read_b128 v[200:203], v149 offset:2048
	ds_read_b128 v[204:207], v149 offset:3072
	ds_read_b128 v[208:211], v149 offset:4096
	ds_read_b128 v[212:215], v149 offset:5120
	ds_read_b128 v[216:219], v149 offset:6144
	ds_read_b128 v[220:223], v149 offset:7168
	global_load_lds_dwordx4 v[224:225], off
	s_add_i32 m0, s21, 0xe000
	v_lshl_add_u64 v[224:225], s[22:23], 0, v[138:139]
	global_load_lds_dwordx4 v[224:225], off
	s_waitcnt vmcnt(8) lgkmcnt(0)
	s_barrier
	v_mfma_f32_16x16x32_bf16 v[124:127], v[150:153], v[192:195], v[124:127]
	v_mfma_f32_16x16x32_bf16 v[120:123], v[158:161], v[192:195], v[120:123]
	v_mfma_f32_16x16x32_bf16 v[108:111], v[150:153], v[200:203], v[108:111]
	v_mfma_f32_16x16x32_bf16 v[104:107], v[158:161], v[200:203], v[104:107]
	v_mfma_f32_16x16x32_bf16 v[92:95], v[150:153], v[208:211], v[92:95]
	v_mfma_f32_16x16x32_bf16 v[88:91], v[158:161], v[208:211], v[88:91]
	v_mfma_f32_16x16x32_bf16 v[76:79], v[150:153], v[216:219], v[76:79]
	v_mfma_f32_16x16x32_bf16 v[72:75], v[158:161], v[216:219], v[72:75]
	v_mfma_f32_16x16x32_bf16 v[124:127], v[154:157], v[196:199], v[124:127]
	v_mfma_f32_16x16x32_bf16 v[120:123], v[162:165], v[196:199], v[120:123]
	v_mfma_f32_16x16x32_bf16 v[108:111], v[154:157], v[204:207], v[108:111]
	v_mfma_f32_16x16x32_bf16 v[104:107], v[162:165], v[204:207], v[104:107]
	v_mfma_f32_16x16x32_bf16 v[92:95], v[154:157], v[212:215], v[92:95]
	v_mfma_f32_16x16x32_bf16 v[88:91], v[162:165], v[212:215], v[88:91]
	v_mfma_f32_16x16x32_bf16 v[76:79], v[154:157], v[220:223], v[76:79]
	v_mfma_f32_16x16x32_bf16 v[72:75], v[162:165], v[220:223], v[72:75]
	v_mfma_f32_16x16x32_bf16 v[116:119], v[166:169], v[192:195], v[116:119]
	v_mfma_f32_16x16x32_bf16 v[112:115], v[184:187], v[192:195], v[112:115]
	v_mfma_f32_16x16x32_bf16 v[100:103], v[166:169], v[200:203], v[100:103]
	v_mfma_f32_16x16x32_bf16 v[96:99], v[184:187], v[200:203], v[96:99]
	v_mfma_f32_16x16x32_bf16 v[84:87], v[166:169], v[208:211], v[84:87]
	v_mfma_f32_16x16x32_bf16 v[80:83], v[184:187], v[208:211], v[80:83]
	v_mfma_f32_16x16x32_bf16 v[68:71], v[166:169], v[216:219], v[68:71]
	v_mfma_f32_16x16x32_bf16 v[64:67], v[184:187], v[216:219], v[64:67]
	v_mfma_f32_16x16x32_bf16 v[116:119], v[180:183], v[196:199], v[116:119]
	v_mfma_f32_16x16x32_bf16 v[112:115], v[188:191], v[196:199], v[112:115]
	v_mfma_f32_16x16x32_bf16 v[100:103], v[180:183], v[204:207], v[100:103]
	v_mfma_f32_16x16x32_bf16 v[96:99], v[188:191], v[204:207], v[96:99]
	v_mfma_f32_16x16x32_bf16 v[84:87], v[180:183], v[212:215], v[84:87]
	v_mfma_f32_16x16x32_bf16 v[80:83], v[188:191], v[212:215], v[80:83]
	v_mfma_f32_16x16x32_bf16 v[68:71], v[180:183], v[220:223], v[68:71]
	v_mfma_f32_16x16x32_bf16 v[64:67], v[188:191], v[220:223], v[64:67]
	s_barrier
	s_add_i32 s49, s40, s28
	v_lshl_add_u64 v[224:225], s[24:25], 0, v[130:131]
	s_mov_b32 m0, s49
	ds_read_b128 v[192:195], v149 offset:16384
	ds_read_b128 v[196:199], v149 offset:17408
	ds_read_b128 v[200:203], v149 offset:18432
	ds_read_b128 v[204:207], v149 offset:19456
	ds_read_b128 v[208:211], v149 offset:20480
	ds_read_b128 v[212:215], v149 offset:21504
	ds_read_b128 v[216:219], v149 offset:22528
	ds_read_b128 v[220:223], v149 offset:23552
	global_load_lds_dwordx4 v[224:225], off
	s_add_i32 m0, s49, 0x2000
	s_add_u32 s50, s24, 0x40000
	v_lshl_add_u64 v[226:227], s[24:25], 0, v[134:135]
	s_addc_u32 s51, s25, 0
	s_add_i32 s49, s41, s28
	global_load_lds_dwordx4 v[226:227], off
	v_lshl_add_u64 v[228:229], s[50:51], 0, v[130:131]
	s_mov_b32 m0, s49
	v_lshl_add_u64 v[230:231], s[26:27], 0, v[132:133]
	global_load_lds_dwordx4 v[228:229], off
	s_add_i32 m0, s49, 0x2000
	v_lshl_add_u64 v[228:229], s[50:51], 0, v[134:135]
	global_load_lds_dwordx4 v[228:229], off
	s_mov_b32 m0, s21
	v_lshl_add_u64 v[228:229], s[26:27], 0, v[128:129]
	global_load_lds_dwordx4 v[228:229], off
	s_mov_b32 m0, s31
	s_nop 0
	global_load_lds_dwordx4 v[230:231], off
	s_waitcnt vmcnt(8) lgkmcnt(0)
	s_barrier
	v_mfma_f32_16x16x32_bf16 v[60:63], v[150:153], v[192:195], v[60:63]
	v_mfma_f32_16x16x32_bf16 v[56:59], v[158:161], v[192:195], v[56:59]
	v_mfma_f32_16x16x32_bf16 v[44:47], v[150:153], v[200:203], v[44:47]
	v_mfma_f32_16x16x32_bf16 v[40:43], v[158:161], v[200:203], v[40:43]
	v_mfma_f32_16x16x32_bf16 v[28:31], v[150:153], v[208:211], v[28:31]
	v_mfma_f32_16x16x32_bf16 v[24:27], v[158:161], v[208:211], v[24:27]
	v_mfma_f32_16x16x32_bf16 v[12:15], v[150:153], v[216:219], v[12:15]
	v_mfma_f32_16x16x32_bf16 v[8:11], v[158:161], v[216:219], v[8:11]
	v_mfma_f32_16x16x32_bf16 v[60:63], v[154:157], v[196:199], v[60:63]
	v_mfma_f32_16x16x32_bf16 v[56:59], v[162:165], v[196:199], v[56:59]
	v_mfma_f32_16x16x32_bf16 v[44:47], v[154:157], v[204:207], v[44:47]
	v_mfma_f32_16x16x32_bf16 v[40:43], v[162:165], v[204:207], v[40:43]
	v_mfma_f32_16x16x32_bf16 v[28:31], v[154:157], v[212:215], v[28:31]
	v_mfma_f32_16x16x32_bf16 v[24:27], v[162:165], v[212:215], v[24:27]
	v_mfma_f32_16x16x32_bf16 v[12:15], v[154:157], v[220:223], v[12:15]
	v_mfma_f32_16x16x32_bf16 v[8:11], v[162:165], v[220:223], v[8:11]
	v_mfma_f32_16x16x32_bf16 v[52:55], v[166:169], v[192:195], v[52:55]
	v_mfma_f32_16x16x32_bf16 v[48:51], v[184:187], v[192:195], v[48:51]
	v_mfma_f32_16x16x32_bf16 v[36:39], v[166:169], v[200:203], v[36:39]
	v_mfma_f32_16x16x32_bf16 v[32:35], v[184:187], v[200:203], v[32:35]
	v_mfma_f32_16x16x32_bf16 v[20:23], v[166:169], v[208:211], v[20:23]
	v_mfma_f32_16x16x32_bf16 v[16:19], v[184:187], v[208:211], v[16:19]
	v_mfma_f32_16x16x32_bf16 v[4:7], v[166:169], v[216:219], v[4:7]
	v_mfma_f32_16x16x32_bf16 v[0:3], v[184:187], v[216:219], v[0:3]
	v_mfma_f32_16x16x32_bf16 v[52:55], v[180:183], v[196:199], v[52:55]
	v_mfma_f32_16x16x32_bf16 v[48:51], v[188:191], v[196:199], v[48:51]
	v_mfma_f32_16x16x32_bf16 v[36:39], v[180:183], v[204:207], v[36:39]
	v_mfma_f32_16x16x32_bf16 v[32:35], v[188:191], v[204:207], v[32:35]
	v_mfma_f32_16x16x32_bf16 v[20:23], v[180:183], v[212:215], v[20:23]
	v_mfma_f32_16x16x32_bf16 v[16:19], v[188:191], v[212:215], v[16:19]
	v_mfma_f32_16x16x32_bf16 v[4:7], v[180:183], v[220:223], v[4:7]
	v_mfma_f32_16x16x32_bf16 v[0:3], v[188:191], v[220:223], v[0:3]
	s_barrier
.Lpeel942_mid:
	s_add_i32 s49, 0, 0x18000
	s_add_i32 s50, 0, 0x1c000
	v_add_u32_e32 v162, s49, v145
	v_add_u32_e32 v179, s50, v145
	ds_read_b128 v[150:153], v162
	ds_read_b128 v[154:157], v162 offset:1024
	ds_read_b128 v[158:161], v162 offset:2048
	ds_read_b128 v[162:165], v162 offset:3072
	ds_read_b128 v[166:169], v179
	ds_read_b128 v[180:183], v179 offset:1024
	ds_read_b128 v[184:187], v179 offset:2048
	ds_read_b128 v[188:191], v179 offset:3072
	s_add_u32 s26, s26, 0x40000
	s_addc_u32 s27, s27, 0
	s_mov_b32 m0, s33
	v_lshl_add_u64 v[232:233], s[26:27], 0, v[128:129]
	ds_read_b128 v[192:195], v149 offset:32768
	ds_read_b128 v[196:199], v149 offset:33792
	ds_read_b128 v[200:203], v149 offset:34816
	ds_read_b128 v[204:207], v149 offset:35840
	ds_read_b128 v[208:211], v149 offset:36864
	ds_read_b128 v[212:215], v149 offset:37888
	ds_read_b128 v[216:219], v149 offset:38912
	ds_read_b128 v[220:223], v149 offset:39936
	global_load_lds_dwordx4 v[232:233], off
	s_mov_b32 m0, s34
	v_lshl_add_u64 v[232:233], s[26:27], 0, v[132:133]
	global_load_lds_dwordx4 v[232:233], off
	s_waitcnt vmcnt(8) lgkmcnt(0)
	s_barrier
	v_mfma_f32_16x16x32_bf16 v[124:127], v[150:153], v[192:195], v[124:127]
	v_mfma_f32_16x16x32_bf16 v[120:123], v[158:161], v[192:195], v[120:123]
	v_mfma_f32_16x16x32_bf16 v[108:111], v[150:153], v[200:203], v[108:111]
	v_mfma_f32_16x16x32_bf16 v[104:107], v[158:161], v[200:203], v[104:107]
	v_mfma_f32_16x16x32_bf16 v[92:95], v[150:153], v[208:211], v[92:95]
	v_mfma_f32_16x16x32_bf16 v[88:91], v[158:161], v[208:211], v[88:91]
	v_mfma_f32_16x16x32_bf16 v[76:79], v[150:153], v[216:219], v[76:79]
	v_mfma_f32_16x16x32_bf16 v[72:75], v[158:161], v[216:219], v[72:75]
	v_mfma_f32_16x16x32_bf16 v[124:127], v[154:157], v[196:199], v[124:127]
	v_mfma_f32_16x16x32_bf16 v[120:123], v[162:165], v[196:199], v[120:123]
	v_mfma_f32_16x16x32_bf16 v[108:111], v[154:157], v[204:207], v[108:111]
	v_mfma_f32_16x16x32_bf16 v[104:107], v[162:165], v[204:207], v[104:107]
	v_mfma_f32_16x16x32_bf16 v[92:95], v[154:157], v[212:215], v[92:95]
	v_mfma_f32_16x16x32_bf16 v[88:91], v[162:165], v[212:215], v[88:91]
	v_mfma_f32_16x16x32_bf16 v[76:79], v[154:157], v[220:223], v[76:79]
	v_mfma_f32_16x16x32_bf16 v[72:75], v[162:165], v[220:223], v[72:75]
	v_mfma_f32_16x16x32_bf16 v[116:119], v[166:169], v[192:195], v[116:119]
	v_mfma_f32_16x16x32_bf16 v[112:115], v[184:187], v[192:195], v[112:115]
	v_mfma_f32_16x16x32_bf16 v[100:103], v[166:169], v[200:203], v[100:103]
	v_mfma_f32_16x16x32_bf16 v[96:99], v[184:187], v[200:203], v[96:99]
	v_mfma_f32_16x16x32_bf16 v[84:87], v[166:169], v[208:211], v[84:87]
	v_mfma_f32_16x16x32_bf16 v[80:83], v[184:187], v[208:211], v[80:83]
	v_mfma_f32_16x16x32_bf16 v[68:71], v[166:169], v[216:219], v[68:71]
	v_mfma_f32_16x16x32_bf16 v[64:67], v[184:187], v[216:219], v[64:67]
	v_mfma_f32_16x16x32_bf16 v[116:119], v[180:183], v[196:199], v[116:119]
	v_mfma_f32_16x16x32_bf16 v[112:115], v[188:191], v[196:199], v[112:115]
	v_mfma_f32_16x16x32_bf16 v[100:103], v[180:183], v[204:207], v[100:103]
	v_mfma_f32_16x16x32_bf16 v[96:99], v[188:191], v[204:207], v[96:99]
	v_mfma_f32_16x16x32_bf16 v[84:87], v[180:183], v[212:215], v[84:87]
	v_mfma_f32_16x16x32_bf16 v[80:83], v[188:191], v[212:215], v[80:83]
	v_mfma_f32_16x16x32_bf16 v[68:71], v[180:183], v[220:223], v[68:71]
	v_mfma_f32_16x16x32_bf16 v[64:67], v[188:191], v[220:223], v[64:67]
	s_barrier
	s_add_i32 s26, s49, s28
	v_lshl_add_u64 v[224:225], v[224:225], 0, s[8:9]
	s_mov_b32 m0, s26
	ds_read_b128 v[192:195], v149 offset:49152
	ds_read_b128 v[196:199], v149 offset:50176
	ds_read_b128 v[200:203], v149 offset:51200
	ds_read_b128 v[204:207], v149 offset:52224
	ds_read_b128 v[208:211], v149 offset:53248
	ds_read_b128 v[212:215], v149 offset:54272
	ds_read_b128 v[216:219], v149 offset:55296
	ds_read_b128 v[220:223], v149 offset:56320
	global_load_lds_dwordx4 v[224:225], off
	s_add_i32 m0, s26, 0x2000
	s_add_u32 s24, s24, 0x40080
	v_lshl_add_u64 v[224:225], v[226:227], 0, s[8:9]
	s_addc_u32 s25, s25, 0
	s_add_i32 s26, s50, s28
	global_load_lds_dwordx4 v[224:225], off
	s_mov_b32 m0, s26
	v_lshl_add_u64 v[224:225], s[24:25], 0, v[130:131]
	global_load_lds_dwordx4 v[224:225], off
	s_add_i32 m0, s26, 0x2000
	v_lshl_add_u64 v[224:225], s[24:25], 0, v[134:135]
	global_load_lds_dwordx4 v[224:225], off
	v_lshl_add_u64 v[224:225], v[228:229], 0, s[8:9]
	s_mov_b32 m0, s37
	s_nop 0
	global_load_lds_dwordx4 v[224:225], off
	v_lshl_add_u64 v[224:225], v[230:231], 0, s[8:9]
	s_mov_b32 m0, s38
	s_nop 0
	global_load_lds_dwordx4 v[224:225], off
	s_waitcnt vmcnt(8) lgkmcnt(0)
	s_barrier
	v_mfma_f32_16x16x32_bf16 v[60:63], v[150:153], v[192:195], v[60:63]
	v_mfma_f32_16x16x32_bf16 v[56:59], v[158:161], v[192:195], v[56:59]
	v_mfma_f32_16x16x32_bf16 v[44:47], v[150:153], v[200:203], v[44:47]
	v_mfma_f32_16x16x32_bf16 v[40:43], v[158:161], v[200:203], v[40:43]
	v_mfma_f32_16x16x32_bf16 v[28:31], v[150:153], v[208:211], v[28:31]
	v_mfma_f32_16x16x32_bf16 v[24:27], v[158:161], v[208:211], v[24:27]
	v_mfma_f32_16x16x32_bf16 v[12:15], v[150:153], v[216:219], v[12:15]
	v_mfma_f32_16x16x32_bf16 v[8:11], v[158:161], v[216:219], v[8:11]
	v_mfma_f32_16x16x32_bf16 v[60:63], v[154:157], v[196:199], v[60:63]
	v_mfma_f32_16x16x32_bf16 v[56:59], v[162:165], v[196:199], v[56:59]
	v_mfma_f32_16x16x32_bf16 v[44:47], v[154:157], v[204:207], v[44:47]
	v_mfma_f32_16x16x32_bf16 v[40:43], v[162:165], v[204:207], v[40:43]
	v_mfma_f32_16x16x32_bf16 v[28:31], v[154:157], v[212:215], v[28:31]
	v_mfma_f32_16x16x32_bf16 v[24:27], v[162:165], v[212:215], v[24:27]
	v_mfma_f32_16x16x32_bf16 v[12:15], v[154:157], v[220:223], v[12:15]
	v_mfma_f32_16x16x32_bf16 v[8:11], v[162:165], v[220:223], v[8:11]
	v_mfma_f32_16x16x32_bf16 v[52:55], v[166:169], v[192:195], v[52:55]
	v_mfma_f32_16x16x32_bf16 v[48:51], v[184:187], v[192:195], v[48:51]
	v_mfma_f32_16x16x32_bf16 v[36:39], v[166:169], v[200:203], v[36:39]
	v_mfma_f32_16x16x32_bf16 v[32:35], v[184:187], v[200:203], v[32:35]
	v_mfma_f32_16x16x32_bf16 v[20:23], v[166:169], v[208:211], v[20:23]
	v_mfma_f32_16x16x32_bf16 v[16:19], v[184:187], v[208:211], v[16:19]
	v_mfma_f32_16x16x32_bf16 v[4:7], v[166:169], v[216:219], v[4:7]
	v_mfma_f32_16x16x32_bf16 v[0:3], v[184:187], v[216:219], v[0:3]
	v_mfma_f32_16x16x32_bf16 v[52:55], v[180:183], v[196:199], v[52:55]
	v_mfma_f32_16x16x32_bf16 v[48:51], v[188:191], v[196:199], v[48:51]
	v_mfma_f32_16x16x32_bf16 v[36:39], v[180:183], v[204:207], v[36:39]
	v_mfma_f32_16x16x32_bf16 v[32:35], v[188:191], v[204:207], v[32:35]
	v_mfma_f32_16x16x32_bf16 v[20:23], v[180:183], v[212:215], v[20:23]
	v_mfma_f32_16x16x32_bf16 v[16:19], v[188:191], v[212:215], v[16:19]
	v_mfma_f32_16x16x32_bf16 v[4:7], v[180:183], v[220:223], v[4:7]
	v_mfma_f32_16x16x32_bf16 v[0:3], v[188:191], v[220:223], v[0:3]
	s_barrier
	s_add_i32 s48, s48, 2
	s_add_u32 s22, s22, 0x100
	s_addc_u32 s23, s23, 0
	s_add_u32 s46, s46, 0x100
	s_addc_u32 s47, s47, 0
	s_cmp_gt_u32 s48, 13
	s_cbranch_scc0 .LBB0_942
	s_and_b64 vcc, exec, s[10:11]
	s_cbranch_vccz .LBB0_945
	s_barrier

.LBB0_1018:
	ds_read_b128 v[152:155], v149
	ds_read_b128 v[156:159], v149 offset:1024
	ds_read_b128 v[160:163], v149 offset:2048
	ds_read_b128 v[164:167], v149 offset:3072
	ds_read_b128 v[174:177], v150
	ds_read_b128 v[178:181], v150 offset:1024
	ds_read_b128 v[182:185], v150 offset:2048
	ds_read_b128 v[186:189], v150 offset:3072
	s_add_u32 s34, s30, 0xfff50080
	s_addc_u32 s35, s31, -1
	s_cmp_eq_u32 s60, 40
	s_cselect_b32 s37, s5, s35
	s_cselect_b32 s36, s4, s34
	s_cselect_b32 s35, s29, s57
	s_cselect_b32 s34, s28, s56
	v_lshl_add_u64 v[140:141], s[30:31], 0, v[132:133]
	s_add_i32 m0, s41, 0xc000
	ds_read_b128 v[190:193], v151
	ds_read_b128 v[194:197], v151 offset:1024
	ds_read_b128 v[198:201], v151 offset:2048
	ds_read_b128 v[202:205], v151 offset:3072
	ds_read_b128 v[206:209], v151 offset:4096
	ds_read_b128 v[210:213], v151 offset:5120
	ds_read_b128 v[214:217], v151 offset:6144
	ds_read_b128 v[218:221], v151 offset:7168
	global_load_lds_dwordx4 v[140:141], off
	s_add_i32 m0, s41, 0xe000
	v_lshl_add_u64 v[140:141], s[30:31], 0, v[134:135]
	global_load_lds_dwordx4 v[140:141], off
	s_waitcnt vmcnt(8) lgkmcnt(0)
	s_barrier
	v_mfma_f32_16x16x32_bf16 v[124:127], v[152:155], v[190:193], v[124:127]
	v_mfma_f32_16x16x32_bf16 v[120:123], v[160:163], v[190:193], v[120:123]
	v_mfma_f32_16x16x32_bf16 v[112:115], v[152:155], v[198:201], v[112:115]
	v_mfma_f32_16x16x32_bf16 v[108:111], v[160:163], v[198:201], v[108:111]
	v_mfma_f32_16x16x32_bf16 v[96:99], v[152:155], v[206:209], v[96:99]
	v_mfma_f32_16x16x32_bf16 v[92:95], v[160:163], v[206:209], v[92:95]
	v_mfma_f32_16x16x32_bf16 v[80:83], v[152:155], v[214:217], v[80:83]
	v_mfma_f32_16x16x32_bf16 v[76:79], v[160:163], v[214:217], v[76:79]
	v_mfma_f32_16x16x32_bf16 v[124:127], v[156:159], v[194:197], v[124:127]
	v_mfma_f32_16x16x32_bf16 v[120:123], v[164:167], v[194:197], v[120:123]
	v_mfma_f32_16x16x32_bf16 v[112:115], v[156:159], v[202:205], v[112:115]
	v_mfma_f32_16x16x32_bf16 v[108:111], v[164:167], v[202:205], v[108:111]
	v_mfma_f32_16x16x32_bf16 v[96:99], v[156:159], v[210:213], v[96:99]
	v_mfma_f32_16x16x32_bf16 v[92:95], v[164:167], v[210:213], v[92:95]
	v_mfma_f32_16x16x32_bf16 v[80:83], v[156:159], v[218:221], v[80:83]
	v_mfma_f32_16x16x32_bf16 v[76:79], v[164:167], v[218:221], v[76:79]
	v_mfma_f32_16x16x32_bf16 v[116:119], v[174:177], v[190:193], v[116:119]
	v_mfma_f32_16x16x32_bf16 v[104:107], v[182:185], v[190:193], v[104:107]
	v_mfma_f32_16x16x32_bf16 v[100:103], v[174:177], v[198:201], v[100:103]
	v_mfma_f32_16x16x32_bf16 v[88:91], v[182:185], v[198:201], v[88:91]
	v_mfma_f32_16x16x32_bf16 v[84:87], v[174:177], v[206:209], v[84:87]
	v_mfma_f32_16x16x32_bf16 v[72:75], v[182:185], v[206:209], v[72:75]
	v_mfma_f32_16x16x32_bf16 v[68:71], v[174:177], v[214:217], v[68:71]
	v_mfma_f32_16x16x32_bf16 v[64:67], v[182:185], v[214:217], v[64:67]
	v_mfma_f32_16x16x32_bf16 v[116:119], v[178:181], v[194:197], v[116:119]
	v_mfma_f32_16x16x32_bf16 v[104:107], v[186:189], v[194:197], v[104:107]
	v_mfma_f32_16x16x32_bf16 v[100:103], v[178:181], v[202:205], v[100:103]
	v_mfma_f32_16x16x32_bf16 v[88:91], v[186:189], v[202:205], v[88:91]
	v_mfma_f32_16x16x32_bf16 v[84:87], v[178:181], v[210:213], v[84:87]
	v_mfma_f32_16x16x32_bf16 v[72:75], v[186:189], v[210:213], v[72:75]
	v_mfma_f32_16x16x32_bf16 v[68:71], v[178:181], v[218:221], v[68:71]
	v_mfma_f32_16x16x32_bf16 v[64:67], v[186:189], v[218:221], v[64:67]
	s_barrier
	s_add_i32 s61, s50, s40
	v_lshl_add_u64 v[140:141], s[34:35], 0, v[128:129]
	s_mov_b32 m0, s61
	ds_read_b128 v[190:193], v151 offset:16384
	ds_read_b128 v[194:197], v151 offset:17408
	ds_read_b128 v[198:201], v151 offset:18432
	ds_read_b128 v[202:205], v151 offset:19456
	ds_read_b128 v[206:209], v151 offset:20480
	ds_read_b128 v[210:213], v151 offset:21504
	ds_read_b128 v[214:217], v151 offset:22528
	ds_read_b128 v[218:221], v151 offset:23552
	global_load_lds_dwordx4 v[140:141], off
	s_add_i32 m0, s61, 0x2000
	s_add_u32 s62, s34, 0xb0000
	v_lshl_add_u64 v[168:169], s[34:35], 0, v[130:131]
	s_addc_u32 s63, s35, 0
	s_add_i32 s61, s51, s40
	global_load_lds_dwordx4 v[168:169], off
	v_lshl_add_u64 v[222:223], s[62:63], 0, v[128:129]
	s_mov_b32 m0, s61
	v_lshl_add_u64 v[224:225], s[36:37], 0, v[130:131]
	global_load_lds_dwordx4 v[222:223], off
	s_add_i32 m0, s61, 0x2000
	v_lshl_add_u64 v[222:223], s[62:63], 0, v[130:131]
	global_load_lds_dwordx4 v[222:223], off
	s_mov_b32 m0, s41
	v_lshl_add_u64 v[222:223], s[36:37], 0, v[128:129]
	global_load_lds_dwordx4 v[222:223], off
	s_mov_b32 m0, s42
	s_nop 0
	global_load_lds_dwordx4 v[224:225], off
	s_waitcnt vmcnt(8) lgkmcnt(0)
	s_barrier
	v_mfma_f32_16x16x32_bf16 v[60:63], v[152:155], v[190:193], v[60:63]
	v_mfma_f32_16x16x32_bf16 v[56:59], v[160:163], v[190:193], v[56:59]
	v_mfma_f32_16x16x32_bf16 v[48:51], v[152:155], v[198:201], v[48:51]
	v_mfma_f32_16x16x32_bf16 v[44:47], v[160:163], v[198:201], v[44:47]
	v_mfma_f32_16x16x32_bf16 v[32:35], v[152:155], v[206:209], v[32:35]
	v_mfma_f32_16x16x32_bf16 v[28:31], v[160:163], v[206:209], v[28:31]
	v_mfma_f32_16x16x32_bf16 v[16:19], v[152:155], v[214:217], v[16:19]
	v_mfma_f32_16x16x32_bf16 v[8:11], v[160:163], v[214:217], v[8:11]
	v_mfma_f32_16x16x32_bf16 v[60:63], v[156:159], v[194:197], v[60:63]
	v_mfma_f32_16x16x32_bf16 v[56:59], v[164:167], v[194:197], v[56:59]
	v_mfma_f32_16x16x32_bf16 v[48:51], v[156:159], v[202:205], v[48:51]
	v_mfma_f32_16x16x32_bf16 v[44:47], v[164:167], v[202:205], v[44:47]
	v_mfma_f32_16x16x32_bf16 v[32:35], v[156:159], v[210:213], v[32:35]
	v_mfma_f32_16x16x32_bf16 v[28:31], v[164:167], v[210:213], v[28:31]
	v_mfma_f32_16x16x32_bf16 v[16:19], v[156:159], v[218:221], v[16:19]
	v_mfma_f32_16x16x32_bf16 v[8:11], v[164:167], v[218:221], v[8:11]
	v_mfma_f32_16x16x32_bf16 v[52:55], v[174:177], v[190:193], v[52:55]
	v_mfma_f32_16x16x32_bf16 v[40:43], v[182:185], v[190:193], v[40:43]
	v_mfma_f32_16x16x32_bf16 v[36:39], v[174:177], v[198:201], v[36:39]
	v_mfma_f32_16x16x32_bf16 v[24:27], v[182:185], v[198:201], v[24:27]
	v_mfma_f32_16x16x32_bf16 v[20:23], v[174:177], v[206:209], v[20:23]
	v_mfma_f32_16x16x32_bf16 v[12:15], v[182:185], v[206:209], v[12:15]
	v_mfma_f32_16x16x32_bf16 v[4:7], v[174:177], v[214:217], v[4:7]
	v_mfma_f32_16x16x32_bf16 v[0:3], v[182:185], v[214:217], v[0:3]
	v_mfma_f32_16x16x32_bf16 v[52:55], v[178:181], v[194:197], v[52:55]
	v_mfma_f32_16x16x32_bf16 v[40:43], v[186:189], v[194:197], v[40:43]
	v_mfma_f32_16x16x32_bf16 v[36:39], v[178:181], v[202:205], v[36:39]
	v_mfma_f32_16x16x32_bf16 v[24:27], v[186:189], v[202:205], v[24:27]
	v_mfma_f32_16x16x32_bf16 v[20:23], v[178:181], v[210:213], v[20:23]
	v_mfma_f32_16x16x32_bf16 v[12:15], v[186:189], v[210:213], v[12:15]
	v_mfma_f32_16x16x32_bf16 v[4:7], v[178:181], v[218:221], v[4:7]
	v_mfma_f32_16x16x32_bf16 v[0:3], v[186:189], v[218:221], v[0:3]
	s_barrier
	s_add_i32 s61, 0, 0x18000
	s_add_i32 s62, 0, 0x1c000
	v_add_u32_e32 v164, s61, v147
	v_add_u32_e32 v186, s62, v147
	ds_read_b128 v[152:155], v164
	ds_read_b128 v[156:159], v164 offset:1024
	ds_read_b128 v[160:163], v164 offset:2048
	ds_read_b128 v[164:167], v164 offset:3072
	ds_read_b128 v[174:177], v186
	ds_read_b128 v[178:181], v186 offset:1024
	ds_read_b128 v[182:185], v186 offset:2048
	ds_read_b128 v[186:189], v186 offset:3072
	s_add_u32 s36, s36, 0xb0000
	s_addc_u32 s37, s37, 0
	s_mov_b32 m0, s43
	v_lshl_add_u64 v[226:227], s[36:37], 0, v[128:129]
	ds_read_b128 v[190:193], v151 offset:32768
	ds_read_b128 v[194:197], v151 offset:33792
	ds_read_b128 v[198:201], v151 offset:34816
	ds_read_b128 v[202:205], v151 offset:35840
	ds_read_b128 v[206:209], v151 offset:36864
	ds_read_b128 v[210:213], v151 offset:37888
	ds_read_b128 v[214:217], v151 offset:38912
	ds_read_b128 v[218:221], v151 offset:39936
	global_load_lds_dwordx4 v[226:227], off
	s_mov_b32 m0, s44
	v_lshl_add_u64 v[226:227], s[36:37], 0, v[130:131]
	global_load_lds_dwordx4 v[226:227], off
	s_waitcnt vmcnt(8) lgkmcnt(0)
	s_barrier
	v_mfma_f32_16x16x32_bf16 v[124:127], v[152:155], v[190:193], v[124:127]
	v_mfma_f32_16x16x32_bf16 v[120:123], v[160:163], v[190:193], v[120:123]
	v_mfma_f32_16x16x32_bf16 v[112:115], v[152:155], v[198:201], v[112:115]
	v_mfma_f32_16x16x32_bf16 v[108:111], v[160:163], v[198:201], v[108:111]
	v_mfma_f32_16x16x32_bf16 v[96:99], v[152:155], v[206:209], v[96:99]
	v_mfma_f32_16x16x32_bf16 v[92:95], v[160:163], v[206:209], v[92:95]
	v_mfma_f32_16x16x32_bf16 v[80:83], v[152:155], v[214:217], v[80:83]
	v_mfma_f32_16x16x32_bf16 v[76:79], v[160:163], v[214:217], v[76:79]
	v_mfma_f32_16x16x32_bf16 v[124:127], v[156:159], v[194:197], v[124:127]
	v_mfma_f32_16x16x32_bf16 v[120:123], v[164:167], v[194:197], v[120:123]
	v_mfma_f32_16x16x32_bf16 v[112:115], v[156:159], v[202:205], v[112:115]
	v_mfma_f32_16x16x32_bf16 v[108:111], v[164:167], v[202:205], v[108:111]
	v_mfma_f32_16x16x32_bf16 v[96:99], v[156:159], v[210:213], v[96:99]
	v_mfma_f32_16x16x32_bf16 v[92:95], v[164:167], v[210:213], v[92:95]
	v_mfma_f32_16x16x32_bf16 v[80:83], v[156:159], v[218:221], v[80:83]
	v_mfma_f32_16x16x32_bf16 v[76:79], v[164:167], v[218:221], v[76:79]
	v_mfma_f32_16x16x32_bf16 v[116:119], v[174:177], v[190:193], v[116:119]
	v_mfma_f32_16x16x32_bf16 v[104:107], v[182:185], v[190:193], v[104:107]
	v_mfma_f32_16x16x32_bf16 v[100:103], v[174:177], v[198:201], v[100:103]
	v_mfma_f32_16x16x32_bf16 v[88:91], v[182:185], v[198:201], v[88:91]
	v_mfma_f32_16x16x32_bf16 v[84:87], v[174:177], v[206:209], v[84:87]
	v_mfma_f32_16x16x32_bf16 v[72:75], v[182:185], v[206:209], v[72:75]
	v_mfma_f32_16x16x32_bf16 v[68:71], v[174:177], v[214:217], v[68:71]
	v_mfma_f32_16x16x32_bf16 v[64:67], v[182:185], v[214:217], v[64:67]
	v_mfma_f32_16x16x32_bf16 v[116:119], v[178:181], v[194:197], v[116:119]
	v_mfma_f32_16x16x32_bf16 v[104:107], v[186:189], v[194:197], v[104:107]
	v_mfma_f32_16x16x32_bf16 v[100:103], v[178:181], v[202:205], v[100:103]
	v_mfma_f32_16x16x32_bf16 v[88:91], v[186:189], v[202:205], v[88:91]
	v_mfma_f32_16x16x32_bf16 v[84:87], v[178:181], v[210:213], v[84:87]
	v_mfma_f32_16x16x32_bf16 v[72:75], v[186:189], v[210:213], v[72:75]
	v_mfma_f32_16x16x32_bf16 v[68:71], v[178:181], v[218:221], v[68:71]
	v_mfma_f32_16x16x32_bf16 v[64:67], v[186:189], v[218:221], v[64:67]
	s_barrier
	s_add_i32 s36, s61, s40
	v_lshl_add_u64 v[140:141], v[140:141], 0, s[16:17]
	s_mov_b32 m0, s36
	ds_read_b128 v[190:193], v151 offset:49152
	ds_read_b128 v[194:197], v151 offset:50176
	ds_read_b128 v[198:201], v151 offset:51200
	ds_read_b128 v[202:205], v151 offset:52224
	ds_read_b128 v[206:209], v151 offset:53248
	ds_read_b128 v[210:213], v151 offset:54272
	ds_read_b128 v[214:217], v151 offset:55296
	ds_read_b128 v[218:221], v151 offset:56320
	global_load_lds_dwordx4 v[140:141], off
	s_add_i32 m0, s36, 0x2000
	s_add_u32 s34, s34, 0xb0080
	v_lshl_add_u64 v[140:141], v[168:169], 0, s[16:17]
	s_addc_u32 s35, s35, 0
	s_add_i32 s36, s62, s40
	global_load_lds_dwordx4 v[140:141], off
	s_mov_b32 m0, s36
	v_lshl_add_u64 v[140:141], s[34:35], 0, v[128:129]
	global_load_lds_dwordx4 v[140:141], off
	s_add_i32 m0, s36, 0x2000
	v_lshl_add_u64 v[140:141], s[34:35], 0, v[130:131]
	global_load_lds_dwordx4 v[140:141], off
	v_lshl_add_u64 v[140:141], v[222:223], 0, s[16:17]
	s_mov_b32 m0, s47
	s_nop 0
	global_load_lds_dwordx4 v[140:141], off
	v_lshl_add_u64 v[140:141], v[224:225], 0, s[16:17]
	s_mov_b32 m0, s48
	s_nop 0
	global_load_lds_dwordx4 v[140:141], off
	s_waitcnt vmcnt(8) lgkmcnt(0)
	s_barrier
	v_mfma_f32_16x16x32_bf16 v[60:63], v[152:155], v[190:193], v[60:63]
	v_mfma_f32_16x16x32_bf16 v[56:59], v[160:163], v[190:193], v[56:59]
	v_mfma_f32_16x16x32_bf16 v[48:51], v[152:155], v[198:201], v[48:51]
	v_mfma_f32_16x16x32_bf16 v[44:47], v[160:163], v[198:201], v[44:47]
	v_mfma_f32_16x16x32_bf16 v[32:35], v[152:155], v[206:209], v[32:35]
	v_mfma_f32_16x16x32_bf16 v[28:31], v[160:163], v[206:209], v[28:31]
	v_mfma_f32_16x16x32_bf16 v[16:19], v[152:155], v[214:217], v[16:19]
	v_mfma_f32_16x16x32_bf16 v[8:11], v[160:163], v[214:217], v[8:11]
	v_mfma_f32_16x16x32_bf16 v[60:63], v[156:159], v[194:197], v[60:63]
	v_mfma_f32_16x16x32_bf16 v[56:59], v[164:167], v[194:197], v[56:59]
	v_mfma_f32_16x16x32_bf16 v[48:51], v[156:159], v[202:205], v[48:51]
	v_mfma_f32_16x16x32_bf16 v[44:47], v[164:167], v[202:205], v[44:47]
	v_mfma_f32_16x16x32_bf16 v[32:35], v[156:159], v[210:213], v[32:35]
	v_mfma_f32_16x16x32_bf16 v[28:31], v[164:167], v[210:213], v[28:31]
	v_mfma_f32_16x16x32_bf16 v[16:19], v[156:159], v[218:221], v[16:19]
	v_mfma_f32_16x16x32_bf16 v[8:11], v[164:167], v[218:221], v[8:11]
	v_mfma_f32_16x16x32_bf16 v[52:55], v[174:177], v[190:193], v[52:55]
	v_mfma_f32_16x16x32_bf16 v[40:43], v[182:185], v[190:193], v[40:43]
	v_mfma_f32_16x16x32_bf16 v[36:39], v[174:177], v[198:201], v[36:39]
	v_mfma_f32_16x16x32_bf16 v[24:27], v[182:185], v[198:201], v[24:27]
	v_mfma_f32_16x16x32_bf16 v[20:23], v[174:177], v[206:209], v[20:23]
	v_mfma_f32_16x16x32_bf16 v[12:15], v[182:185], v[206:209], v[12:15]
	v_mfma_f32_16x16x32_bf16 v[4:7], v[174:177], v[214:217], v[4:7]
	v_mfma_f32_16x16x32_bf16 v[0:3], v[182:185], v[214:217], v[0:3]
	v_mfma_f32_16x16x32_bf16 v[52:55], v[178:181], v[194:197], v[52:55]
	v_mfma_f32_16x16x32_bf16 v[40:43], v[186:189], v[194:197], v[40:43]
	v_mfma_f32_16x16x32_bf16 v[36:39], v[178:181], v[202:205], v[36:39]
	v_mfma_f32_16x16x32_bf16 v[24:27], v[186:189], v[202:205], v[24:27]
	v_mfma_f32_16x16x32_bf16 v[20:23], v[178:181], v[210:213], v[20:23]
	v_mfma_f32_16x16x32_bf16 v[12:15], v[186:189], v[210:213], v[12:15]
	v_mfma_f32_16x16x32_bf16 v[4:7], v[178:181], v[218:221], v[4:7]
	v_mfma_f32_16x16x32_bf16 v[0:3], v[186:189], v[218:221], v[0:3]
	s_barrier
	s_add_i32 s60, s60, 2
	s_add_u32 s30, s30, 0x100
	s_addc_u32 s31, s31, 0
	s_add_u32 s56, s56, 0x100
	s_addc_u32 s57, s57, 0
	s_cmp_gt_u32 s60, 41
	s_cbranch_scc0 .LBB0_1018
	s_and_b64 vcc, exec, s[18:19]
	s_cbranch_vccz .LBB0_1021
	s_barrier

.LBB0_1042:
	v_add_u32_e32 v147, s39, v146
	ds_read_b128 v[148:151], v147
	ds_read_b128 v[152:155], v147 offset:1024
	ds_read_b128 v[156:159], v147 offset:2048
	ds_read_b128 v[164:167], v147 offset:3072
	v_add_u32_e32 v147, s40, v146
	s_add_u32 s20, s12, s18
	ds_read_b128 v[174:177], v147
	ds_read_b128 v[178:181], v147 offset:1024
	ds_read_b128 v[182:185], v147 offset:2048
	ds_read_b128 v[186:189], v147 offset:3072
	s_addc_u32 s21, s13, s19
	s_add_u32 s20, s20, 0x100
	s_addc_u32 s21, s21, 0
	s_add_u32 s47, s44, s18
	s_addc_u32 s48, s45, s19
	s_cmpk_eq_i32 s18, 0x1500
	s_cselect_b32 s23, s17, s21
	s_cselect_b32 s22, s16, s20
	s_cselect_b32 s21, s5, s48
	s_cselect_b32 s20, s4, s47
	v_lshl_add_u64 v[160:161], v[140:141], 0, s[18:19]
	s_add_i32 m0, s29, 0xc000
	ds_read_b128 v[190:193], v144
	ds_read_b128 v[194:197], v144 offset:1024
	ds_read_b128 v[198:201], v144 offset:2048
	ds_read_b128 v[202:205], v144 offset:3072
	ds_read_b128 v[206:209], v144 offset:4096
	ds_read_b128 v[210:213], v144 offset:5120
	ds_read_b128 v[214:217], v144 offset:6144
	ds_read_b128 v[218:221], v144 offset:7168
	global_load_lds_dwordx4 v[160:161], off
	v_lshl_add_u64 v[160:161], v[142:143], 0, s[18:19]
	s_add_i32 m0, s29, 0xe000
	s_nop 0
	global_load_lds_dwordx4 v[160:161], off
	s_waitcnt vmcnt(8) lgkmcnt(0)
	s_barrier
	v_mfma_f32_16x16x32_bf16 v[124:127], v[148:151], v[190:193], v[124:127]
	v_mfma_f32_16x16x32_bf16 v[120:123], v[156:159], v[190:193], v[120:123]
	v_mfma_f32_16x16x32_bf16 v[116:119], v[148:151], v[198:201], v[116:119]
	v_mfma_f32_16x16x32_bf16 v[100:103], v[156:159], v[198:201], v[100:103]
	v_mfma_f32_16x16x32_bf16 v[104:107], v[148:151], v[206:209], v[104:107]
	v_mfma_f32_16x16x32_bf16 v[92:95], v[156:159], v[206:209], v[92:95]
	v_mfma_f32_16x16x32_bf16 v[96:99], v[148:151], v[214:217], v[96:99]
	v_mfma_f32_16x16x32_bf16 v[76:79], v[156:159], v[214:217], v[76:79]
	v_mfma_f32_16x16x32_bf16 v[124:127], v[152:155], v[194:197], v[124:127]
	v_mfma_f32_16x16x32_bf16 v[120:123], v[164:167], v[194:197], v[120:123]
	v_mfma_f32_16x16x32_bf16 v[116:119], v[152:155], v[202:205], v[116:119]
	v_mfma_f32_16x16x32_bf16 v[100:103], v[164:167], v[202:205], v[100:103]
	v_mfma_f32_16x16x32_bf16 v[104:107], v[152:155], v[210:213], v[104:107]
	v_mfma_f32_16x16x32_bf16 v[92:95], v[164:167], v[210:213], v[92:95]
	v_mfma_f32_16x16x32_bf16 v[96:99], v[152:155], v[218:221], v[96:99]
	v_mfma_f32_16x16x32_bf16 v[76:79], v[164:167], v[218:221], v[76:79]
	v_mfma_f32_16x16x32_bf16 v[112:115], v[174:177], v[190:193], v[112:115]
	v_mfma_f32_16x16x32_bf16 v[108:111], v[182:185], v[190:193], v[108:111]
	v_mfma_f32_16x16x32_bf16 v[88:91], v[174:177], v[198:201], v[88:91]
	v_mfma_f32_16x16x32_bf16 v[80:83], v[182:185], v[198:201], v[80:83]
	v_mfma_f32_16x16x32_bf16 v[84:87], v[174:177], v[206:209], v[84:87]
	v_mfma_f32_16x16x32_bf16 v[72:75], v[182:185], v[206:209], v[72:75]
	v_mfma_f32_16x16x32_bf16 v[68:71], v[174:177], v[214:217], v[68:71]
	v_mfma_f32_16x16x32_bf16 v[64:67], v[182:185], v[214:217], v[64:67]
	v_mfma_f32_16x16x32_bf16 v[112:115], v[178:181], v[194:197], v[112:115]
	v_mfma_f32_16x16x32_bf16 v[108:111], v[186:189], v[194:197], v[108:111]
	v_mfma_f32_16x16x32_bf16 v[88:91], v[178:181], v[202:205], v[88:91]
	v_mfma_f32_16x16x32_bf16 v[80:83], v[186:189], v[202:205], v[80:83]
	v_mfma_f32_16x16x32_bf16 v[84:87], v[178:181], v[210:213], v[84:87]
	v_mfma_f32_16x16x32_bf16 v[72:75], v[186:189], v[210:213], v[72:75]
	v_mfma_f32_16x16x32_bf16 v[68:71], v[178:181], v[218:221], v[68:71]
	v_mfma_f32_16x16x32_bf16 v[64:67], v[186:189], v[218:221], v[64:67]
	s_barrier
	s_add_i32 s47, s39, s28
	v_lshl_add_u64 v[160:161], s[20:21], 0, v[128:129]
	s_mov_b32 m0, s47
	ds_read_b128 v[190:193], v144 offset:16384
	ds_read_b128 v[194:197], v144 offset:17408
	ds_read_b128 v[198:201], v144 offset:18432
	ds_read_b128 v[202:205], v144 offset:19456
	ds_read_b128 v[206:209], v144 offset:20480
	ds_read_b128 v[210:213], v144 offset:21504
	ds_read_b128 v[214:217], v144 offset:22528
	ds_read_b128 v[218:221], v144 offset:23552
	global_load_lds_dwordx4 v[160:161], off
	s_add_i32 m0, s47, 0x2000
	s_add_u32 s48, s20, 0xb0000
	v_lshl_add_u64 v[168:169], s[20:21], 0, v[130:131]
	s_addc_u32 s49, s21, 0
	s_add_i32 s47, s40, s28
	global_load_lds_dwordx4 v[168:169], off
	v_lshl_add_u64 v[222:223], s[48:49], 0, v[128:129]
	s_mov_b32 m0, s47
	v_lshl_add_u64 v[224:225], s[22:23], 0, v[130:131]
	global_load_lds_dwordx4 v[222:223], off
	s_add_i32 m0, s47, 0x2000
	v_lshl_add_u64 v[222:223], s[48:49], 0, v[130:131]
	global_load_lds_dwordx4 v[222:223], off
	s_mov_b32 m0, s29
	v_lshl_add_u64 v[222:223], s[22:23], 0, v[128:129]
	global_load_lds_dwordx4 v[222:223], off
	s_mov_b32 m0, s30
	s_nop 0
	global_load_lds_dwordx4 v[224:225], off
	s_waitcnt vmcnt(8) lgkmcnt(0)
	s_barrier
	v_mfma_f32_16x16x32_bf16 v[60:63], v[148:151], v[190:193], v[60:63]
	v_mfma_f32_16x16x32_bf16 v[56:59], v[156:159], v[190:193], v[56:59]
	v_mfma_f32_16x16x32_bf16 v[44:47], v[148:151], v[198:201], v[44:47]
	v_mfma_f32_16x16x32_bf16 v[40:43], v[156:159], v[198:201], v[40:43]
	v_mfma_f32_16x16x32_bf16 v[28:31], v[148:151], v[206:209], v[28:31]
	v_mfma_f32_16x16x32_bf16 v[24:27], v[156:159], v[206:209], v[24:27]
	v_mfma_f32_16x16x32_bf16 v[12:15], v[148:151], v[214:217], v[12:15]
	v_mfma_f32_16x16x32_bf16 v[8:11], v[156:159], v[214:217], v[8:11]
	v_mfma_f32_16x16x32_bf16 v[60:63], v[152:155], v[194:197], v[60:63]
	v_mfma_f32_16x16x32_bf16 v[56:59], v[164:167], v[194:197], v[56:59]
	v_mfma_f32_16x16x32_bf16 v[44:47], v[152:155], v[202:205], v[44:47]
	v_mfma_f32_16x16x32_bf16 v[40:43], v[164:167], v[202:205], v[40:43]
	v_mfma_f32_16x16x32_bf16 v[28:31], v[152:155], v[210:213], v[28:31]
	v_mfma_f32_16x16x32_bf16 v[24:27], v[164:167], v[210:213], v[24:27]
	v_mfma_f32_16x16x32_bf16 v[12:15], v[152:155], v[218:221], v[12:15]
	v_mfma_f32_16x16x32_bf16 v[8:11], v[164:167], v[218:221], v[8:11]
	v_mfma_f32_16x16x32_bf16 v[52:55], v[174:177], v[190:193], v[52:55]
	v_mfma_f32_16x16x32_bf16 v[48:51], v[182:185], v[190:193], v[48:51]
	v_mfma_f32_16x16x32_bf16 v[36:39], v[174:177], v[198:201], v[36:39]
	v_mfma_f32_16x16x32_bf16 v[32:35], v[182:185], v[198:201], v[32:35]
	v_mfma_f32_16x16x32_bf16 v[20:23], v[174:177], v[206:209], v[20:23]
	v_mfma_f32_16x16x32_bf16 v[16:19], v[182:185], v[206:209], v[16:19]
	v_mfma_f32_16x16x32_bf16 v[4:7], v[174:177], v[214:217], v[4:7]
	v_mfma_f32_16x16x32_bf16 v[0:3], v[182:185], v[214:217], v[0:3]
	v_mfma_f32_16x16x32_bf16 v[52:55], v[178:181], v[194:197], v[52:55]
	v_mfma_f32_16x16x32_bf16 v[48:51], v[186:189], v[194:197], v[48:51]
	v_mfma_f32_16x16x32_bf16 v[36:39], v[178:181], v[202:205], v[36:39]
	v_mfma_f32_16x16x32_bf16 v[32:35], v[186:189], v[202:205], v[32:35]
	v_mfma_f32_16x16x32_bf16 v[20:23], v[178:181], v[210:213], v[20:23]
	v_mfma_f32_16x16x32_bf16 v[16:19], v[186:189], v[210:213], v[16:19]
	v_mfma_f32_16x16x32_bf16 v[4:7], v[178:181], v[218:221], v[4:7]
	v_mfma_f32_16x16x32_bf16 v[0:3], v[186:189], v[218:221], v[0:3]
	s_barrier
	s_add_i32 s47, 0, 0x18000
	v_add_u32_e32 v147, s47, v146
	s_add_i32 s48, 0, 0x1c000
	ds_read_b128 v[148:151], v147
	ds_read_b128 v[152:155], v147 offset:1024
	ds_read_b128 v[156:159], v147 offset:2048
	ds_read_b128 v[164:167], v147 offset:3072
	v_add_u32_e32 v147, s48, v146
	ds_read_b128 v[174:177], v147
	ds_read_b128 v[178:181], v147 offset:1024
	ds_read_b128 v[182:185], v147 offset:2048
	ds_read_b128 v[186:189], v147 offset:3072
	s_add_u32 s22, s22, 0xb0000
	s_addc_u32 s23, s23, 0
	s_mov_b32 m0, s31
	v_lshl_add_u64 v[226:227], s[22:23], 0, v[128:129]
	ds_read_b128 v[190:193], v144 offset:32768
	ds_read_b128 v[194:197], v144 offset:33792
	ds_read_b128 v[198:201], v144 offset:34816
	ds_read_b128 v[202:205], v144 offset:35840
	ds_read_b128 v[206:209], v144 offset:36864
	ds_read_b128 v[210:213], v144 offset:37888
	ds_read_b128 v[214:217], v144 offset:38912
	ds_read_b128 v[218:221], v144 offset:39936
	global_load_lds_dwordx4 v[226:227], off
	s_mov_b32 m0, s34
	v_lshl_add_u64 v[226:227], s[22:23], 0, v[130:131]
	global_load_lds_dwordx4 v[226:227], off
	s_waitcnt vmcnt(8) lgkmcnt(0)
	s_barrier
	v_mfma_f32_16x16x32_bf16 v[124:127], v[148:151], v[190:193], v[124:127]
	v_mfma_f32_16x16x32_bf16 v[120:123], v[156:159], v[190:193], v[120:123]
	v_mfma_f32_16x16x32_bf16 v[116:119], v[148:151], v[198:201], v[116:119]
	v_mfma_f32_16x16x32_bf16 v[100:103], v[156:159], v[198:201], v[100:103]
	v_mfma_f32_16x16x32_bf16 v[104:107], v[148:151], v[206:209], v[104:107]
	v_mfma_f32_16x16x32_bf16 v[92:95], v[156:159], v[206:209], v[92:95]
	v_mfma_f32_16x16x32_bf16 v[96:99], v[148:151], v[214:217], v[96:99]
	v_mfma_f32_16x16x32_bf16 v[76:79], v[156:159], v[214:217], v[76:79]
	v_mfma_f32_16x16x32_bf16 v[124:127], v[152:155], v[194:197], v[124:127]
	v_mfma_f32_16x16x32_bf16 v[120:123], v[164:167], v[194:197], v[120:123]
	v_mfma_f32_16x16x32_bf16 v[116:119], v[152:155], v[202:205], v[116:119]
	v_mfma_f32_16x16x32_bf16 v[100:103], v[164:167], v[202:205], v[100:103]
	v_mfma_f32_16x16x32_bf16 v[104:107], v[152:155], v[210:213], v[104:107]
	v_mfma_f32_16x16x32_bf16 v[92:95], v[164:167], v[210:213], v[92:95]
	v_mfma_f32_16x16x32_bf16 v[96:99], v[152:155], v[218:221], v[96:99]
	v_mfma_f32_16x16x32_bf16 v[76:79], v[164:167], v[218:221], v[76:79]
	v_mfma_f32_16x16x32_bf16 v[112:115], v[174:177], v[190:193], v[112:115]
	v_mfma_f32_16x16x32_bf16 v[108:111], v[182:185], v[190:193], v[108:111]
	v_mfma_f32_16x16x32_bf16 v[88:91], v[174:177], v[198:201], v[88:91]
	v_mfma_f32_16x16x32_bf16 v[80:83], v[182:185], v[198:201], v[80:83]
	v_mfma_f32_16x16x32_bf16 v[84:87], v[174:177], v[206:209], v[84:87]
	v_mfma_f32_16x16x32_bf16 v[72:75], v[182:185], v[206:209], v[72:75]
	v_mfma_f32_16x16x32_bf16 v[68:71], v[174:177], v[214:217], v[68:71]
	v_mfma_f32_16x16x32_bf16 v[64:67], v[182:185], v[214:217], v[64:67]
	v_mfma_f32_16x16x32_bf16 v[112:115], v[178:181], v[194:197], v[112:115]
	v_mfma_f32_16x16x32_bf16 v[108:111], v[186:189], v[194:197], v[108:111]
	v_mfma_f32_16x16x32_bf16 v[88:91], v[178:181], v[202:205], v[88:91]
	v_mfma_f32_16x16x32_bf16 v[80:83], v[186:189], v[202:205], v[80:83]
	v_mfma_f32_16x16x32_bf16 v[84:87], v[178:181], v[210:213], v[84:87]
	v_mfma_f32_16x16x32_bf16 v[72:75], v[186:189], v[210:213], v[72:75]
	v_mfma_f32_16x16x32_bf16 v[68:71], v[178:181], v[218:221], v[68:71]
	v_mfma_f32_16x16x32_bf16 v[64:67], v[186:189], v[218:221], v[64:67]
	s_barrier
	s_add_i32 s22, s47, s28
	v_lshl_add_u64 v[160:161], v[160:161], 0, s[14:15]
	s_mov_b32 m0, s22
	ds_read_b128 v[190:193], v144 offset:49152
	ds_read_b128 v[194:197], v144 offset:50176
	ds_read_b128 v[198:201], v144 offset:51200
	ds_read_b128 v[202:205], v144 offset:52224
	ds_read_b128 v[206:209], v144 offset:53248
	ds_read_b128 v[210:213], v144 offset:54272
	ds_read_b128 v[214:217], v144 offset:55296
	ds_read_b128 v[218:221], v144 offset:56320
	global_load_lds_dwordx4 v[160:161], off
	s_add_i32 m0, s22, 0x2000
	s_add_u32 s20, s20, 0xb0080
	v_lshl_add_u64 v[160:161], v[168:169], 0, s[14:15]
	s_addc_u32 s21, s21, 0
	s_add_i32 s22, s48, s28
	global_load_lds_dwordx4 v[160:161], off
	s_mov_b32 m0, s22
	v_lshl_add_u64 v[160:161], s[20:21], 0, v[128:129]
	global_load_lds_dwordx4 v[160:161], off
	s_add_i32 m0, s22, 0x2000
	v_lshl_add_u64 v[160:161], s[20:21], 0, v[130:131]
	global_load_lds_dwordx4 v[160:161], off
	v_lshl_add_u64 v[160:161], v[222:223], 0, s[14:15]
	s_mov_b32 m0, s37
	s_nop 0
	global_load_lds_dwordx4 v[160:161], off
	v_lshl_add_u64 v[160:161], v[224:225], 0, s[14:15]
	s_mov_b32 m0, s38
	s_nop 0
	global_load_lds_dwordx4 v[160:161], off
	s_waitcnt vmcnt(8) lgkmcnt(0)
	s_barrier
	v_mfma_f32_16x16x32_bf16 v[60:63], v[148:151], v[190:193], v[60:63]
	v_mfma_f32_16x16x32_bf16 v[56:59], v[156:159], v[190:193], v[56:59]
	v_mfma_f32_16x16x32_bf16 v[44:47], v[148:151], v[198:201], v[44:47]
	v_mfma_f32_16x16x32_bf16 v[40:43], v[156:159], v[198:201], v[40:43]
	v_mfma_f32_16x16x32_bf16 v[28:31], v[148:151], v[206:209], v[28:31]
	v_mfma_f32_16x16x32_bf16 v[24:27], v[156:159], v[206:209], v[24:27]
	v_mfma_f32_16x16x32_bf16 v[12:15], v[148:151], v[214:217], v[12:15]
	v_mfma_f32_16x16x32_bf16 v[8:11], v[156:159], v[214:217], v[8:11]
	v_mfma_f32_16x16x32_bf16 v[60:63], v[152:155], v[194:197], v[60:63]
	v_mfma_f32_16x16x32_bf16 v[56:59], v[164:167], v[194:197], v[56:59]
	v_mfma_f32_16x16x32_bf16 v[44:47], v[152:155], v[202:205], v[44:47]
	v_mfma_f32_16x16x32_bf16 v[40:43], v[164:167], v[202:205], v[40:43]
	v_mfma_f32_16x16x32_bf16 v[28:31], v[152:155], v[210:213], v[28:31]
	v_mfma_f32_16x16x32_bf16 v[24:27], v[164:167], v[210:213], v[24:27]
	v_mfma_f32_16x16x32_bf16 v[12:15], v[152:155], v[218:221], v[12:15]
	v_mfma_f32_16x16x32_bf16 v[8:11], v[164:167], v[218:221], v[8:11]
	v_mfma_f32_16x16x32_bf16 v[52:55], v[174:177], v[190:193], v[52:55]
	v_mfma_f32_16x16x32_bf16 v[48:51], v[182:185], v[190:193], v[48:51]
	v_mfma_f32_16x16x32_bf16 v[36:39], v[174:177], v[198:201], v[36:39]
	v_mfma_f32_16x16x32_bf16 v[32:35], v[182:185], v[198:201], v[32:35]
	v_mfma_f32_16x16x32_bf16 v[20:23], v[174:177], v[206:209], v[20:23]
	v_mfma_f32_16x16x32_bf16 v[16:19], v[182:185], v[206:209], v[16:19]
	v_mfma_f32_16x16x32_bf16 v[4:7], v[174:177], v[214:217], v[4:7]
	v_mfma_f32_16x16x32_bf16 v[0:3], v[182:185], v[214:217], v[0:3]
	v_mfma_f32_16x16x32_bf16 v[52:55], v[178:181], v[194:197], v[52:55]
	v_mfma_f32_16x16x32_bf16 v[48:51], v[186:189], v[194:197], v[48:51]
	v_mfma_f32_16x16x32_bf16 v[36:39], v[178:181], v[202:205], v[36:39]
	v_mfma_f32_16x16x32_bf16 v[32:35], v[186:189], v[202:205], v[32:35]
	v_mfma_f32_16x16x32_bf16 v[20:23], v[178:181], v[210:213], v[20:23]
	v_mfma_f32_16x16x32_bf16 v[16:19], v[186:189], v[210:213], v[16:19]
	v_mfma_f32_16x16x32_bf16 v[4:7], v[178:181], v[218:221], v[4:7]
	v_mfma_f32_16x16x32_bf16 v[0:3], v[186:189], v[218:221], v[0:3]
	s_barrier
	s_add_i32 s46, s46, 2
	s_add_u32 s18, s18, 0x100
	s_addc_u32 s19, s19, 0
	s_cmp_gt_u32 s46, 41
	s_cbranch_scc0 .LBB0_1042
	s_add_u32 s18, s44, 0xffffff00
	s_addc_u32 s19, s45, -1
	s_and_b64 vcc, exec, s[2:3]
	s_cbranch_vccnz .LBB0_1045
	v_mov_b64_e32 v[0:1], 0
	s_mov_b32 s10, s41
	s_mov_b32 s24, s42
	s_mov_b64 s[12:13], s[16:17]
	s_mov_b32 s36, s43
	v_mov_b64_e32 v[2:3], 0
	v_mov_b64_e32 v[4:5], 0
	v_mov_b64_e32 v[6:7], 0
	v_mov_b64_e32 v[16:17], 0
	v_mov_b64_e32 v[18:19], 0
	v_mov_b64_e32 v[20:21], 0
	v_mov_b64_e32 v[22:23], 0
	v_mov_b64_e32 v[32:33], 0
	v_mov_b64_e32 v[34:35], 0
	v_mov_b64_e32 v[36:37], 0
	v_mov_b64_e32 v[38:39], 0
	v_mov_b64_e32 v[48:49], 0
	v_mov_b64_e32 v[50:51], 0
	v_mov_b64_e32 v[52:53], 0
	v_mov_b64_e32 v[54:55], 0
	v_mov_b64_e32 v[8:9], 0
	v_mov_b64_e32 v[10:11], 0
	v_mov_b64_e32 v[12:13], 0
	v_mov_b64_e32 v[14:15], 0
	v_mov_b64_e32 v[24:25], 0
	v_mov_b64_e32 v[26:27], 0
	v_mov_b64_e32 v[28:29], 0
	v_mov_b64_e32 v[30:31], 0
	v_mov_b64_e32 v[40:41], 0
	v_mov_b64_e32 v[42:43], 0
	v_mov_b64_e32 v[44:45], 0
	v_mov_b64_e32 v[46:47], 0
	v_mov_b64_e32 v[56:57], 0
	v_mov_b64_e32 v[58:59], 0
	v_mov_b64_e32 v[60:61], 0
	v_mov_b64_e32 v[62:63], 0
	v_mov_b64_e32 v[64:65], 0
	v_mov_b64_e32 v[66:67], 0
	v_mov_b64_e32 v[68:69], 0
	v_mov_b64_e32 v[70:71], 0
	v_mov_b64_e32 v[72:73], 0
	v_mov_b64_e32 v[74:75], 0
	v_mov_b64_e32 v[84:85], 0
	v_mov_b64_e32 v[86:87], 0
	v_mov_b64_e32 v[80:81], 0
	v_mov_b64_e32 v[82:83], 0
	v_mov_b64_e32 v[88:89], 0
	v_mov_b64_e32 v[90:91], 0
	v_mov_b64_e32 v[108:109], 0
	v_mov_b64_e32 v[110:111], 0
	v_mov_b64_e32 v[112:113], 0
	v_mov_b64_e32 v[114:115], 0
	v_mov_b64_e32 v[76:77], 0
	v_mov_b64_e32 v[78:79], 0
	v_mov_b64_e32 v[96:97], 0
	v_mov_b64_e32 v[98:99], 0
	v_mov_b64_e32 v[92:93], 0
	v_mov_b64_e32 v[94:95], 0
	v_mov_b64_e32 v[104:105], 0
	v_mov_b64_e32 v[106:107], 0
	v_mov_b64_e32 v[100:101], 0
	v_mov_b64_e32 v[102:103], 0
	v_mov_b64_e32 v[116:117], 0
	v_mov_b64_e32 v[118:119], 0
	v_mov_b64_e32 v[120:121], 0
	v_mov_b64_e32 v[122:123], 0
	v_mov_b64_e32 v[124:125], 0
	v_mov_b64_e32 v[126:127], 0
	s_andn2_b64 vcc, exec, s[0:1]
	s_cbranch_vccnz .LBB0_1046
	s_branch .LBB0_1047
